# v21 plus: K-loop load segments issue the ds_reads first, ahead of the scalar set-up and the LDS-DMA loads
# speedup vs baseline: 1.0025x; 1.0025x over previous
;     __device__ __forceinline__ void a_ready(const Unit& u) const { wait_panel(cnt, u.pm, need, tmo, wave); }
;     __device__ __forceinline__ void a_ready(const Unit& u) const { wait_panel(cnt, u.pm, need, tmo, wave); }
; #define PG8_STAGE(bufoff, gbase, voff) do { _Pragma("unroll") for (int _i = 0; _i < 2; ++_i) \
;         __builtin_amdgcn_global_load_lds((const unsigned*)((const char*)(gbase) + (voff)[_i]), (PG8_LAS unsigned*)(lds + (bufoff) + ldsw + _i * 8192), 16, 0, 0); } while (0)
; #define PG8_LDA(dst, b, h) do { _Pragma("unroll") for (int m = 0; m < 4; ++m) _Pragma("unroll") for (int k = 0; k < 2; ++k) dst[m][k] = *(const PG8_LAS bf16x8*)(lds + PG8_SA(b, h) + aoff + m * 2048 + k * 1024); } while (0)
; #define PG8_LDB(dst, b, h) do { _Pragma("unroll") for (int n = 0; n < 2; ++n) _Pragma("unroll") for (int k = 0; k < 2; ++k) dst[n][k] = *(const PG8_LAS bf16x8*)(lds + PG8_SB(b, h) + boff + n * 2048 + k * 1024); } while (0)
; #define PG8_WAIT_V(n) asm volatile("s_waitcnt vmcnt(" #n ")" ::: "memory")
; #define PG8_WAIT_L(n) asm volatile("s_waitcnt lgkmcnt(" #n ")" ::: "memory")
; #define PG8_BAR __builtin_amdgcn_s_barrier()
; #define PG8_SCHED __builtin_amdgcn_sched_barrier(0)
; template <class Epi, class Sched, bool ALIGN_EPI = false, bool SP2 = false>
; __device__ __forceinline__ void gemm_phase(PG8_LAS unsigned char* lds, const Gemm g, const Sched& S, const Epi& E, const int tid_in) {
;     ...
;             const bool last = (t == nt - 2);
;             const char* a1 = cA + (size_t)(t + 1) * kstep;
;             const char* a2 = last ? nA : cA + (size_t)(t + 2) * kstep; const char* b2 = last ? nB : cB + (size_t)(t + 2) * kstep;
;             const char* a3 = a2 + kstep; const char* b3 = b2 + kstep;
;             if (last && has_next) S.a_ready(nxt);
;             if constexpr (SP2) {
;             PG8_LDB(B0, 0, 0); PG8_LDB(B1, 0, 1); PG8_SCHED; PG8_LDA(At, 0, 0); PG8_STAGE(PG8_SA(1, 1), a1 + hstepA, voffA);
;             PG8_WAIT_V(8); PG8_WAIT_L(0); PG8_BAR; PG8_MMA(0, 0, At, B0); PG8_MMA(0, 1, At, B1); PG8_BAR; PG8_SCHED;
;             PG8_LDA(At, 0, 1); PG8_STAGE(PG8_SB(0, 0), b2, voffB); PG8_STAGE(PG8_SB(0, 1), b2 + hstepB, voffB); PG8_STAGE(PG8_SA(0, 0), a2, voffA);
;             PG8_WAIT_V(8); PG8_WAIT_L(0); PG8_BAR; PG8_MMA(1, 0, At, B0); PG8_MMA(1, 1, At, B1); PG8_BAR; PG8_SCHED;
.LBB0_476:
	ds_read_b128 v[138:141], v249
	ds_read_b128 v[150:153], v249 offset:1024
	ds_read_b128 v[154:157], v249 offset:2048
	ds_read_b128 v[158:161], v249 offset:3072
	ds_read_b128 v[162:165], v249 offset:16384
	ds_read_b128 v[166:169], v249 offset:17408
	ds_read_b128 v[190:193], v249 offset:18432
	ds_read_b128 v[194:197], v249 offset:19456
	ds_read_b128 v[198:201], v148
	ds_read_b128 v[202:205], v148 offset:1024
	ds_read_b128 v[206:209], v148 offset:2048
	ds_read_b128 v[210:213], v148 offset:3072
	ds_read_b128 v[224:227], v148 offset:4096
	ds_read_b128 v[228:231], v148 offset:5120
	ds_read_b128 v[232:235], v148 offset:6144
	ds_read_b128 v[236:239], v148 offset:7168
	s_add_u32 s22, s52, 0xfff80080
	s_addc_u32 s23, s53, -1
	s_add_i32 s45, 0, 0x10000
	s_cmp_eq_u32 s43, 28
	s_cselect_b32 s55, s6, s23
	s_cselect_b32 s54, s11, s22
	s_cselect_b32 s23, s12, s35
	s_cselect_b32 s22, s33, s34
	s_add_i32 s47, 0, 0x14000
	s_add_i32 m0, s21, 0xc000
	s_nop 0
	global_load_lds_dwordx4 v134, s[52:53]
	s_add_i32 m0, s21, 0xe000
	s_nop 0
	global_load_lds_dwordx4 v136, s[52:53]
	s_waitcnt vmcnt(8) lgkmcnt(0)
	s_barrier
	v_mfma_f32_16x16x32_bf16 v[124:127], v[138:141], v[198:201], v[124:127]
	v_mfma_f32_16x16x32_bf16 v[120:123], v[154:157], v[198:201], v[120:123]
	v_mfma_f32_16x16x32_bf16 v[108:111], v[138:141], v[206:209], v[108:111]
	v_mfma_f32_16x16x32_bf16 v[104:107], v[154:157], v[206:209], v[104:107]
	v_mfma_f32_16x16x32_bf16 v[92:95], v[138:141], v[224:227], v[92:95]
	v_mfma_f32_16x16x32_bf16 v[88:91], v[154:157], v[224:227], v[88:91]
	v_mfma_f32_16x16x32_bf16 v[76:79], v[138:141], v[232:235], v[76:79]
	v_mfma_f32_16x16x32_bf16 v[72:75], v[154:157], v[232:235], v[72:75]
	v_mfma_f32_16x16x32_bf16 v[124:127], v[150:153], v[202:205], v[124:127]
	v_mfma_f32_16x16x32_bf16 v[120:123], v[158:161], v[202:205], v[120:123]
	v_mfma_f32_16x16x32_bf16 v[108:111], v[150:153], v[210:213], v[108:111]
	v_mfma_f32_16x16x32_bf16 v[104:107], v[158:161], v[210:213], v[104:107]
	v_mfma_f32_16x16x32_bf16 v[92:95], v[150:153], v[228:231], v[92:95]
	v_mfma_f32_16x16x32_bf16 v[88:91], v[158:161], v[228:231], v[88:91]
	v_mfma_f32_16x16x32_bf16 v[76:79], v[150:153], v[236:239], v[76:79]
	v_mfma_f32_16x16x32_bf16 v[72:75], v[158:161], v[236:239], v[72:75]
	v_mfma_f32_16x16x32_bf16 v[116:119], v[162:165], v[198:201], v[116:119]
	v_mfma_f32_16x16x32_bf16 v[112:115], v[190:193], v[198:201], v[112:115]
	v_mfma_f32_16x16x32_bf16 v[100:103], v[162:165], v[206:209], v[100:103]
	v_mfma_f32_16x16x32_bf16 v[96:99], v[190:193], v[206:209], v[96:99]
	v_mfma_f32_16x16x32_bf16 v[84:87], v[162:165], v[224:227], v[84:87]
	v_mfma_f32_16x16x32_bf16 v[80:83], v[190:193], v[224:227], v[80:83]
	v_mfma_f32_16x16x32_bf16 v[68:71], v[162:165], v[232:235], v[68:71]
	v_mfma_f32_16x16x32_bf16 v[64:67], v[190:193], v[232:235], v[64:67]
	v_mfma_f32_16x16x32_bf16 v[116:119], v[166:169], v[202:205], v[116:119]
	v_mfma_f32_16x16x32_bf16 v[112:115], v[194:197], v[202:205], v[112:115]
	v_mfma_f32_16x16x32_bf16 v[100:103], v[166:169], v[210:213], v[100:103]
	v_mfma_f32_16x16x32_bf16 v[96:99], v[194:197], v[210:213], v[96:99]
	v_mfma_f32_16x16x32_bf16 v[84:87], v[166:169], v[228:231], v[84:87]
	v_mfma_f32_16x16x32_bf16 v[80:83], v[194:197], v[228:231], v[80:83]
	v_mfma_f32_16x16x32_bf16 v[68:71], v[166:169], v[236:239], v[68:71]
	v_mfma_f32_16x16x32_bf16 v[64:67], v[194:197], v[236:239], v[64:67]
	s_barrier
	ds_read_b128 v[198:201], v148 offset:16384
	ds_read_b128 v[202:205], v148 offset:17408
	ds_read_b128 v[206:209], v148 offset:18432
	ds_read_b128 v[210:213], v148 offset:19456
	ds_read_b128 v[224:227], v148 offset:20480
	ds_read_b128 v[228:231], v148 offset:21504
	ds_read_b128 v[232:235], v148 offset:22528
	ds_read_b128 v[236:239], v148 offset:23552
	s_add_i32 s45, s45, s20
	s_mov_b32 m0, s45
	s_nop 0
	global_load_lds_dwordx4 v172, s[22:23]
	s_add_i32 m0, s45, 0x2000
	s_add_u32 s60, s22, 0x80000
	s_addc_u32 s61, s23, 0
	s_add_i32 s45, s47, s20
	global_load_lds_dwordx4 v132, s[22:23]
	s_mov_b32 m0, s45
	s_nop 0
	global_load_lds_dwordx4 v172, s[60:61]
	s_add_i32 m0, s45, 0x2000
	s_nop 0
	global_load_lds_dwordx4 v132, s[60:61]
	s_mov_b32 m0, s21
	s_nop 0
	global_load_lds_dwordx4 v128, s[54:55]
	s_mov_b32 m0, s30
	s_nop 0
	global_load_lds_dwordx4 v130, s[54:55]
	s_waitcnt vmcnt(8) lgkmcnt(0)
	s_barrier
	v_mfma_f32_16x16x32_bf16 v[60:63], v[138:141], v[198:201], v[60:63]
	v_mfma_f32_16x16x32_bf16 v[56:59], v[154:157], v[198:201], v[56:59]
	v_mfma_f32_16x16x32_bf16 v[44:47], v[138:141], v[206:209], v[44:47]
	v_mfma_f32_16x16x32_bf16 v[40:43], v[154:157], v[206:209], v[40:43]
	v_mfma_f32_16x16x32_bf16 v[28:31], v[138:141], v[224:227], v[28:31]
	v_mfma_f32_16x16x32_bf16 v[24:27], v[154:157], v[224:227], v[24:27]
	v_mfma_f32_16x16x32_bf16 v[12:15], v[138:141], v[232:235], v[12:15]
	v_mfma_f32_16x16x32_bf16 v[8:11], v[154:157], v[232:235], v[8:11]
	v_mfma_f32_16x16x32_bf16 v[60:63], v[150:153], v[202:205], v[60:63]
	v_mfma_f32_16x16x32_bf16 v[56:59], v[158:161], v[202:205], v[56:59]
	v_mfma_f32_16x16x32_bf16 v[44:47], v[150:153], v[210:213], v[44:47]
	v_mfma_f32_16x16x32_bf16 v[40:43], v[158:161], v[210:213], v[40:43]
	v_mfma_f32_16x16x32_bf16 v[28:31], v[150:153], v[228:231], v[28:31]
	v_mfma_f32_16x16x32_bf16 v[24:27], v[158:161], v[228:231], v[24:27]
	v_mfma_f32_16x16x32_bf16 v[12:15], v[150:153], v[236:239], v[12:15]
	v_mfma_f32_16x16x32_bf16 v[8:11], v[158:161], v[236:239], v[8:11]
	v_mfma_f32_16x16x32_bf16 v[52:55], v[162:165], v[198:201], v[52:55]
	v_mfma_f32_16x16x32_bf16 v[48:51], v[190:193], v[198:201], v[48:51]
	v_mfma_f32_16x16x32_bf16 v[36:39], v[162:165], v[206:209], v[36:39]
	v_mfma_f32_16x16x32_bf16 v[32:35], v[190:193], v[206:209], v[32:35]
	v_mfma_f32_16x16x32_bf16 v[20:23], v[162:165], v[224:227], v[20:23]
	v_mfma_f32_16x16x32_bf16 v[16:19], v[190:193], v[224:227], v[16:19]
	v_mfma_f32_16x16x32_bf16 v[4:7], v[162:165], v[232:235], v[4:7]
	v_mfma_f32_16x16x32_bf16 v[0:3], v[190:193], v[232:235], v[0:3]
	v_mfma_f32_16x16x32_bf16 v[52:55], v[166:169], v[202:205], v[52:55]
	v_mfma_f32_16x16x32_bf16 v[48:51], v[194:197], v[202:205], v[48:51]
	v_mfma_f32_16x16x32_bf16 v[36:39], v[166:169], v[210:213], v[36:39]
	v_mfma_f32_16x16x32_bf16 v[32:35], v[194:197], v[210:213], v[32:35]
	v_mfma_f32_16x16x32_bf16 v[20:23], v[166:169], v[228:231], v[20:23]
	v_mfma_f32_16x16x32_bf16 v[16:19], v[194:197], v[228:231], v[16:19]
	v_mfma_f32_16x16x32_bf16 v[4:7], v[166:169], v[236:239], v[4:7]
	v_mfma_f32_16x16x32_bf16 v[0:3], v[194:197], v[236:239], v[0:3]
	s_barrier
; #define PG8_STAGE(bufoff, gbase, voff) do { _Pragma("unroll") for (int _i = 0; _i < 2; ++_i) \
;         __builtin_amdgcn_global_load_lds((const unsigned*)((const char*)(gbase) + (voff)[_i]), (PG8_LAS unsigned*)(lds + (bufoff) + ldsw + _i * 8192), 16, 0, 0); } while (0)
; #define PG8_LDA(dst, b, h) do { _Pragma("unroll") for (int m = 0; m < 4; ++m) _Pragma("unroll") for (int k = 0; k < 2; ++k) dst[m][k] = *(const PG8_LAS bf16x8*)(lds + PG8_SA(b, h) + aoff + m * 2048 + k * 1024); } while (0)
; #define PG8_LDB(dst, b, h) do { _Pragma("unroll") for (int n = 0; n < 2; ++n) _Pragma("unroll") for (int k = 0; k < 2; ++k) dst[n][k] = *(const PG8_LAS bf16x8*)(lds + PG8_SB(b, h) + boff + n * 2048 + k * 1024); } while (0)
; #define PG8_MMA(ai, bj, At, Bt) do { __builtin_amdgcn_s_setprio(1); _Pragma("unroll") for (int m = 0; m < 4; ++m) _Pragma("unroll") for (int n = 0; n < 2; ++n) _Pragma("unroll") for (int k = 0; k < 2; ++k) \
;         acc[ai][bj][m][n] = __builtin_amdgcn_mfma_f32_16x16x32_bf16(Bt[n][k], At[m][k], acc[ai][bj][m][n], 0, 0, 0); __builtin_amdgcn_s_setprio(0); } while (0)
; #define PG8_WAIT_V(n) asm volatile("s_waitcnt vmcnt(" #n ")" ::: "memory")
; #define PG8_WAIT_L(n) asm volatile("s_waitcnt lgkmcnt(" #n ")" ::: "memory")
; #define PG8_BAR __builtin_amdgcn_s_barrier()
; #define PG8_SCHED __builtin_amdgcn_sched_barrier(0)
; template <class Epi, class Sched, bool ALIGN_EPI = false, bool SP2 = false>
; __device__ __forceinline__ void gemm_phase(PG8_LAS unsigned char* lds, const Gemm g, const Sched& S, const Epi& E, const int tid_in) {
;     ...
;             PG8_LDB(B0, 1, 0); PG8_LDB(B1, 1, 1); PG8_SCHED; PG8_LDA(At, 1, 0); PG8_STAGE(PG8_SA(0, 1), a2 + hstepA, voffA);
;             PG8_WAIT_V(8); PG8_WAIT_L(0); PG8_BAR; PG8_MMA(0, 0, At, B0); PG8_MMA(0, 1, At, B1); PG8_BAR; PG8_SCHED;
;             PG8_LDA(At, 1, 1); PG8_STAGE(PG8_SB(1, 0), b3, voffB); PG8_STAGE(PG8_SB(1, 1), b3 + hstepB, voffB); PG8_STAGE(PG8_SA(1, 0), a3, voffA);
;             PG8_WAIT_V(8); PG8_WAIT_L(0); PG8_BAR; PG8_MMA(1, 0, At, B0); PG8_MMA(1, 1, At, B1); PG8_BAR; PG8_SCHED;
;     ...
;         if constexpr (ALIGN_EPI) { if (wr == 0) PG8_BAR; }
	ds_read_b128 v[138:141], v249 offset:32768
	ds_read_b128 v[150:153], v249 offset:33792
	ds_read_b128 v[154:157], v249 offset:34816
	ds_read_b128 v[158:161], v249 offset:35840
	ds_read_b128 v[162:165], v249 offset:49152
	ds_read_b128 v[166:169], v249 offset:50176
	ds_read_b128 v[190:193], v249 offset:51200
	ds_read_b128 v[194:197], v249 offset:52224
	ds_read_b128 v[198:201], v148 offset:32768
	ds_read_b128 v[202:205], v148 offset:33792
	ds_read_b128 v[206:209], v148 offset:34816
	ds_read_b128 v[210:213], v148 offset:35840
	ds_read_b128 v[224:227], v148 offset:36864
	ds_read_b128 v[228:231], v148 offset:37888
	ds_read_b128 v[232:235], v148 offset:38912
	ds_read_b128 v[236:239], v148 offset:39936
	s_add_i32 s45, 0, 0x18000
	s_add_i32 s47, 0, 0x1c000
	s_add_u32 s54, s54, 0x80000
	s_addc_u32 s55, s55, 0
	s_mov_b32 m0, s31
	s_nop 0
	global_load_lds_dwordx4 v128, s[54:55]
	s_mov_b32 m0, s37
	s_nop 0
	global_load_lds_dwordx4 v130, s[54:55]
	s_waitcnt vmcnt(8) lgkmcnt(0)
	s_barrier
	v_mfma_f32_16x16x32_bf16 v[124:127], v[138:141], v[198:201], v[124:127]
	v_mfma_f32_16x16x32_bf16 v[120:123], v[154:157], v[198:201], v[120:123]
	v_mfma_f32_16x16x32_bf16 v[108:111], v[138:141], v[206:209], v[108:111]
	v_mfma_f32_16x16x32_bf16 v[104:107], v[154:157], v[206:209], v[104:107]
	v_mfma_f32_16x16x32_bf16 v[92:95], v[138:141], v[224:227], v[92:95]
	v_mfma_f32_16x16x32_bf16 v[88:91], v[154:157], v[224:227], v[88:91]
	v_mfma_f32_16x16x32_bf16 v[76:79], v[138:141], v[232:235], v[76:79]
	v_mfma_f32_16x16x32_bf16 v[72:75], v[154:157], v[232:235], v[72:75]
	v_mfma_f32_16x16x32_bf16 v[124:127], v[150:153], v[202:205], v[124:127]
	v_mfma_f32_16x16x32_bf16 v[120:123], v[158:161], v[202:205], v[120:123]
	v_mfma_f32_16x16x32_bf16 v[108:111], v[150:153], v[210:213], v[108:111]
	v_mfma_f32_16x16x32_bf16 v[104:107], v[158:161], v[210:213], v[104:107]
	v_mfma_f32_16x16x32_bf16 v[92:95], v[150:153], v[228:231], v[92:95]
	v_mfma_f32_16x16x32_bf16 v[88:91], v[158:161], v[228:231], v[88:91]
	v_mfma_f32_16x16x32_bf16 v[76:79], v[150:153], v[236:239], v[76:79]
	v_mfma_f32_16x16x32_bf16 v[72:75], v[158:161], v[236:239], v[72:75]
	v_mfma_f32_16x16x32_bf16 v[116:119], v[162:165], v[198:201], v[116:119]
	v_mfma_f32_16x16x32_bf16 v[112:115], v[190:193], v[198:201], v[112:115]
	v_mfma_f32_16x16x32_bf16 v[100:103], v[162:165], v[206:209], v[100:103]
	v_mfma_f32_16x16x32_bf16 v[96:99], v[190:193], v[206:209], v[96:99]
	v_mfma_f32_16x16x32_bf16 v[84:87], v[162:165], v[224:227], v[84:87]
	v_mfma_f32_16x16x32_bf16 v[80:83], v[190:193], v[224:227], v[80:83]
	v_mfma_f32_16x16x32_bf16 v[68:71], v[162:165], v[232:235], v[68:71]
	v_mfma_f32_16x16x32_bf16 v[64:67], v[190:193], v[232:235], v[64:67]
	v_mfma_f32_16x16x32_bf16 v[116:119], v[166:169], v[202:205], v[116:119]
	v_mfma_f32_16x16x32_bf16 v[112:115], v[194:197], v[202:205], v[112:115]
	v_mfma_f32_16x16x32_bf16 v[100:103], v[166:169], v[210:213], v[100:103]
	v_mfma_f32_16x16x32_bf16 v[96:99], v[194:197], v[210:213], v[96:99]
	v_mfma_f32_16x16x32_bf16 v[84:87], v[166:169], v[228:231], v[84:87]
	v_mfma_f32_16x16x32_bf16 v[80:83], v[194:197], v[228:231], v[80:83]
	v_mfma_f32_16x16x32_bf16 v[68:71], v[166:169], v[236:239], v[68:71]
	v_mfma_f32_16x16x32_bf16 v[64:67], v[194:197], v[236:239], v[64:67]
	s_barrier
	ds_read_b128 v[198:201], v148 offset:49152
	ds_read_b128 v[202:205], v148 offset:50176
	ds_read_b128 v[206:209], v148 offset:51200
	ds_read_b128 v[210:213], v148 offset:52224
	ds_read_b128 v[224:227], v148 offset:53248
	ds_read_b128 v[228:231], v148 offset:54272
	ds_read_b128 v[232:235], v148 offset:55296
	ds_read_b128 v[236:239], v148 offset:56320
	s_add_i32 s45, s45, s20
	s_mov_b32 m0, s45
	s_add_u32 s100, s22, 0x80
	s_addc_u32 s101, s23, 0
	global_load_lds_dwordx4 v172, s[100:101]
	s_add_i32 m0, s45, 0x2000
	s_add_u32 s22, s22, 0x80080
	s_addc_u32 s23, s23, 0
	s_add_i32 s45, s47, s20
	global_load_lds_dwordx4 v132, s[100:101]
	s_mov_b32 m0, s45
	s_nop 0
	global_load_lds_dwordx4 v172, s[22:23]
	s_add_i32 m0, s45, 0x2000
	s_nop 0
	global_load_lds_dwordx4 v132, s[22:23]
	s_mov_b32 m0, s38
	s_nop 0
	s_add_u32 s100, s54, 0xfff80080
	s_addc_u32 s101, s55, -1
	global_load_lds_dwordx4 v128, s[100:101]
	s_mov_b32 m0, s56
	s_nop 0
	global_load_lds_dwordx4 v130, s[100:101]
	s_waitcnt vmcnt(8) lgkmcnt(0)
	s_barrier
	v_mfma_f32_16x16x32_bf16 v[60:63], v[138:141], v[198:201], v[60:63]
	v_mfma_f32_16x16x32_bf16 v[56:59], v[154:157], v[198:201], v[56:59]
	v_mfma_f32_16x16x32_bf16 v[44:47], v[138:141], v[206:209], v[44:47]
	v_mfma_f32_16x16x32_bf16 v[40:43], v[154:157], v[206:209], v[40:43]
	v_mfma_f32_16x16x32_bf16 v[28:31], v[138:141], v[224:227], v[28:31]
	v_mfma_f32_16x16x32_bf16 v[24:27], v[154:157], v[224:227], v[24:27]
	v_mfma_f32_16x16x32_bf16 v[12:15], v[138:141], v[232:235], v[12:15]
	v_mfma_f32_16x16x32_bf16 v[8:11], v[154:157], v[232:235], v[8:11]
	v_mfma_f32_16x16x32_bf16 v[60:63], v[150:153], v[202:205], v[60:63]
	v_mfma_f32_16x16x32_bf16 v[56:59], v[158:161], v[202:205], v[56:59]
	v_mfma_f32_16x16x32_bf16 v[44:47], v[150:153], v[210:213], v[44:47]
	v_mfma_f32_16x16x32_bf16 v[40:43], v[158:161], v[210:213], v[40:43]
	v_mfma_f32_16x16x32_bf16 v[28:31], v[150:153], v[228:231], v[28:31]
	v_mfma_f32_16x16x32_bf16 v[24:27], v[158:161], v[228:231], v[24:27]
	v_mfma_f32_16x16x32_bf16 v[12:15], v[150:153], v[236:239], v[12:15]
	v_mfma_f32_16x16x32_bf16 v[8:11], v[158:161], v[236:239], v[8:11]
	v_mfma_f32_16x16x32_bf16 v[52:55], v[162:165], v[198:201], v[52:55]
	v_mfma_f32_16x16x32_bf16 v[48:51], v[190:193], v[198:201], v[48:51]
	v_mfma_f32_16x16x32_bf16 v[36:39], v[162:165], v[206:209], v[36:39]
	v_mfma_f32_16x16x32_bf16 v[32:35], v[190:193], v[206:209], v[32:35]
	v_mfma_f32_16x16x32_bf16 v[20:23], v[162:165], v[224:227], v[20:23]
	v_mfma_f32_16x16x32_bf16 v[16:19], v[190:193], v[224:227], v[16:19]
	v_mfma_f32_16x16x32_bf16 v[4:7], v[162:165], v[232:235], v[4:7]
	v_mfma_f32_16x16x32_bf16 v[0:3], v[190:193], v[232:235], v[0:3]
	v_mfma_f32_16x16x32_bf16 v[52:55], v[166:169], v[202:205], v[52:55]
	v_mfma_f32_16x16x32_bf16 v[48:51], v[194:197], v[202:205], v[48:51]
	v_mfma_f32_16x16x32_bf16 v[36:39], v[166:169], v[210:213], v[36:39]
	v_mfma_f32_16x16x32_bf16 v[32:35], v[194:197], v[210:213], v[32:35]
	v_mfma_f32_16x16x32_bf16 v[20:23], v[166:169], v[228:231], v[20:23]
	v_mfma_f32_16x16x32_bf16 v[16:19], v[194:197], v[228:231], v[16:19]
	v_mfma_f32_16x16x32_bf16 v[4:7], v[166:169], v[236:239], v[4:7]
	v_mfma_f32_16x16x32_bf16 v[0:3], v[194:197], v[236:239], v[0:3]
	s_barrier
	s_add_i32 s43, s43, 2
	s_add_u32 s52, s52, 0x100
	s_addc_u32 s53, s53, 0
	s_add_u32 s34, s34, 0x100
	s_addc_u32 s35, s35, 0
	s_cmp_gt_u32 s43, 29
	s_cbranch_scc0 .LBB0_476
	s_and_b64 vcc, exec, s[28:29]
	s_cbranch_vccz .LBB0_479
	s_barrier

;     __device__ __forceinline__ void a_ready(const Unit& u) const { wait_panel(cnt, u.pm, need, tmo, wave); }
;     __device__ __forceinline__ void a_ready(const Unit& u) const { wait_panel(cnt, u.pm, need, tmo, wave); }
; #define PG8_STAGE(bufoff, gbase, voff) do { _Pragma("unroll") for (int _i = 0; _i < 2; ++_i) \
;         __builtin_amdgcn_global_load_lds((const unsigned*)((const char*)(gbase) + (voff)[_i]), (PG8_LAS unsigned*)(lds + (bufoff) + ldsw + _i * 8192), 16, 0, 0); } while (0)
; #define PG8_LDA(dst, b, h) do { _Pragma("unroll") for (int m = 0; m < 4; ++m) _Pragma("unroll") for (int k = 0; k < 2; ++k) dst[m][k] = *(const PG8_LAS bf16x8*)(lds + PG8_SA(b, h) + aoff + m * 2048 + k * 1024); } while (0)
; #define PG8_LDB(dst, b, h) do { _Pragma("unroll") for (int n = 0; n < 2; ++n) _Pragma("unroll") for (int k = 0; k < 2; ++k) dst[n][k] = *(const PG8_LAS bf16x8*)(lds + PG8_SB(b, h) + boff + n * 2048 + k * 1024); } while (0)
; #define PG8_WAIT_V(n) asm volatile("s_waitcnt vmcnt(" #n ")" ::: "memory")
; #define PG8_WAIT_L(n) asm volatile("s_waitcnt lgkmcnt(" #n ")" ::: "memory")
; #define PG8_BAR __builtin_amdgcn_s_barrier()
; #define PG8_SCHED __builtin_amdgcn_sched_barrier(0)
; template <class Epi, class Sched, bool ALIGN_EPI = false, bool SP2 = false>
; __device__ __forceinline__ void gemm_phase(PG8_LAS unsigned char* lds, const Gemm g, const Sched& S, const Epi& E, const int tid_in) {
;     ...
;             const bool last = (t == nt - 2);
;             const char* a1 = cA + (size_t)(t + 1) * kstep;
;             const char* a2 = last ? nA : cA + (size_t)(t + 2) * kstep; const char* b2 = last ? nB : cB + (size_t)(t + 2) * kstep;
;             const char* a3 = a2 + kstep; const char* b3 = b2 + kstep;
;             if (last && has_next) S.a_ready(nxt);
;             if constexpr (SP2) {
;             PG8_LDB(B0, 0, 0); PG8_LDB(B1, 0, 1); PG8_SCHED; PG8_LDA(At, 0, 0); PG8_STAGE(PG8_SA(1, 1), a1 + hstepA, voffA);
;             PG8_WAIT_V(8); PG8_WAIT_L(0); PG8_BAR; PG8_MMA(0, 0, At, B0); PG8_MMA(0, 1, At, B1); PG8_BAR; PG8_SCHED;
;             PG8_LDA(At, 0, 1); PG8_STAGE(PG8_SB(0, 0), b2, voffB); PG8_STAGE(PG8_SB(0, 1), b2 + hstepB, voffB); PG8_STAGE(PG8_SA(0, 0), a2, voffA);
;             PG8_WAIT_V(8); PG8_WAIT_L(0); PG8_BAR; PG8_MMA(1, 0, At, B0); PG8_MMA(1, 1, At, B1); PG8_BAR; PG8_SCHED;
.LBB0_756:
	ds_read_b128 v[88:91], v249
	ds_read_b128 v[92:95], v249 offset:1024
	ds_read_b128 v[96:99], v249 offset:2048
	ds_read_b128 v[146:149], v249 offset:3072
	ds_read_b128 v[150:153], v249 offset:16384
	ds_read_b128 v[154:157], v249 offset:17408
	ds_read_b128 v[158:161], v249 offset:18432
	ds_read_b128 v[162:165], v249 offset:19456
	ds_read_b128 v[166:169], v192
	ds_read_b128 v[194:197], v192 offset:1024
	ds_read_b128 v[198:201], v192 offset:2048
	ds_read_b128 v[202:205], v192 offset:3072
	ds_read_b128 v[206:209], v192 offset:4096
	ds_read_b128 v[210:213], v192 offset:5120
	ds_read_b128 v[224:227], v192 offset:6144
	ds_read_b128 v[228:231], v192 offset:7168
	s_add_u32 s22, s36, 0x100
	s_addc_u32 s23, s37, 0
	s_add_i32 s34, 0, 0x10000
	s_cmp_eq_u32 s33, 2
	s_cselect_b32 s45, s73, s23
	s_cselect_b32 s44, s72, s22
	s_cselect_b32 s43, s77, s21
	s_cselect_b32 s42, s76, s12
	s_add_i32 s46, 0, 0x14000
	s_add_i32 m0, s74, 0xc000
	s_nop 0
	global_load_lds_dwordx4 v142, s[36:37]
	s_add_i32 m0, s74, 0xe000
	s_nop 0
	global_load_lds_dwordx4 v144, s[36:37]
	s_waitcnt vmcnt(8) lgkmcnt(0)
	s_barrier
	v_mfma_f32_16x16x32_bf16 v[136:139], v[88:91], v[166:169], v[136:139]
	v_mfma_f32_16x16x32_bf16 v[60:63], v[96:99], v[166:169], v[60:63]
	v_mfma_f32_16x16x32_bf16 v[128:131], v[88:91], v[198:201], v[128:131]
	v_mfma_f32_16x16x32_bf16 v[52:55], v[96:99], v[198:201], v[52:55]
	v_mfma_f32_16x16x32_bf16 v[120:123], v[88:91], v[206:209], v[120:123]
	v_mfma_f32_16x16x32_bf16 v[44:47], v[96:99], v[206:209], v[44:47]
	v_mfma_f32_16x16x32_bf16 v[112:115], v[88:91], v[224:227], v[112:115]
	v_mfma_f32_16x16x32_bf16 v[36:39], v[96:99], v[224:227], v[36:39]
	v_mfma_f32_16x16x32_bf16 v[136:139], v[92:95], v[194:197], v[136:139]
	v_mfma_f32_16x16x32_bf16 v[60:63], v[146:149], v[194:197], v[60:63]
	v_mfma_f32_16x16x32_bf16 v[128:131], v[92:95], v[202:205], v[128:131]
	v_mfma_f32_16x16x32_bf16 v[52:55], v[146:149], v[202:205], v[52:55]
	v_mfma_f32_16x16x32_bf16 v[120:123], v[92:95], v[210:213], v[120:123]
	v_mfma_f32_16x16x32_bf16 v[44:47], v[146:149], v[210:213], v[44:47]
	v_mfma_f32_16x16x32_bf16 v[112:115], v[92:95], v[228:231], v[112:115]
	v_mfma_f32_16x16x32_bf16 v[36:39], v[146:149], v[228:231], v[36:39]
	v_mfma_f32_16x16x32_bf16 v[132:135], v[150:153], v[166:169], v[132:135]
	v_mfma_f32_16x16x32_bf16 v[56:59], v[158:161], v[166:169], v[56:59]
	v_mfma_f32_16x16x32_bf16 v[124:127], v[150:153], v[198:201], v[124:127]
	v_mfma_f32_16x16x32_bf16 v[48:51], v[158:161], v[198:201], v[48:51]
	v_mfma_f32_16x16x32_bf16 v[116:119], v[150:153], v[206:209], v[116:119]
	v_mfma_f32_16x16x32_bf16 v[40:43], v[158:161], v[206:209], v[40:43]
	v_mfma_f32_16x16x32_bf16 v[108:111], v[150:153], v[224:227], v[108:111]
	v_mfma_f32_16x16x32_bf16 v[32:35], v[158:161], v[224:227], v[32:35]
	v_mfma_f32_16x16x32_bf16 v[132:135], v[154:157], v[194:197], v[132:135]
	v_mfma_f32_16x16x32_bf16 v[56:59], v[162:165], v[194:197], v[56:59]
	v_mfma_f32_16x16x32_bf16 v[124:127], v[154:157], v[202:205], v[124:127]
	v_mfma_f32_16x16x32_bf16 v[48:51], v[162:165], v[202:205], v[48:51]
	v_mfma_f32_16x16x32_bf16 v[116:119], v[154:157], v[210:213], v[116:119]
	v_mfma_f32_16x16x32_bf16 v[40:43], v[162:165], v[210:213], v[40:43]
	v_mfma_f32_16x16x32_bf16 v[108:111], v[154:157], v[228:231], v[108:111]
	v_mfma_f32_16x16x32_bf16 v[32:35], v[162:165], v[228:231], v[32:35]
	s_barrier
	ds_read_b128 v[166:169], v192 offset:16384
	ds_read_b128 v[194:197], v192 offset:17408
	ds_read_b128 v[198:201], v192 offset:18432
	ds_read_b128 v[202:205], v192 offset:19456
	ds_read_b128 v[206:209], v192 offset:20480
	ds_read_b128 v[210:213], v192 offset:21504
	ds_read_b128 v[224:227], v192 offset:22528
	ds_read_b128 v[228:231], v192 offset:23552
	s_add_i32 s34, s34, s38
	s_mov_b32 m0, s34
	s_nop 0
	global_load_lds_dwordx4 v172, s[42:43]
	s_add_i32 m0, s34, 0x2000
	s_add_u32 s34, s42, 0xa0000
	s_addc_u32 s35, s43, 0
	s_add_i32 s36, s46, s38
	global_load_lds_dwordx4 v140, s[42:43]
	s_mov_b32 m0, s36
	s_nop 0
	global_load_lds_dwordx4 v172, s[34:35]
	s_add_i32 m0, s36, 0x2000
	s_nop 0
	global_load_lds_dwordx4 v140, s[34:35]
	s_mov_b32 m0, s74
	s_nop 0
	global_load_lds_dwordx4 v172, s[44:45]
	s_mov_b32 m0, s75
	s_nop 0
	global_load_lds_dwordx4 v140, s[44:45]
	s_waitcnt vmcnt(8) lgkmcnt(0)
	s_barrier
	v_mfma_f32_16x16x32_bf16 v[104:107], v[88:91], v[166:169], v[104:107]
	v_mfma_f32_16x16x32_bf16 v[28:31], v[96:99], v[166:169], v[28:31]
	v_mfma_f32_16x16x32_bf16 v[84:87], v[88:91], v[198:201], v[84:87]
	v_mfma_f32_16x16x32_bf16 v[20:23], v[96:99], v[198:201], v[20:23]
	v_mfma_f32_16x16x32_bf16 v[76:79], v[88:91], v[206:209], v[76:79]
	v_mfma_f32_16x16x32_bf16 v[12:15], v[96:99], v[206:209], v[12:15]
	v_mfma_f32_16x16x32_bf16 v[68:71], v[88:91], v[224:227], v[68:71]
	v_mfma_f32_16x16x32_bf16 v[4:7], v[96:99], v[224:227], v[4:7]
	v_mfma_f32_16x16x32_bf16 v[104:107], v[92:95], v[194:197], v[104:107]
	v_mfma_f32_16x16x32_bf16 v[28:31], v[146:149], v[194:197], v[28:31]
	v_mfma_f32_16x16x32_bf16 v[84:87], v[92:95], v[202:205], v[84:87]
	v_mfma_f32_16x16x32_bf16 v[20:23], v[146:149], v[202:205], v[20:23]
	v_mfma_f32_16x16x32_bf16 v[76:79], v[92:95], v[210:213], v[76:79]
	v_mfma_f32_16x16x32_bf16 v[12:15], v[146:149], v[210:213], v[12:15]
	v_mfma_f32_16x16x32_bf16 v[68:71], v[92:95], v[228:231], v[68:71]
	v_mfma_f32_16x16x32_bf16 v[4:7], v[146:149], v[228:231], v[4:7]
	v_mfma_f32_16x16x32_bf16 v[24:27], v[158:161], v[166:169], v[24:27]
	v_mfma_f32_16x16x32_bf16 v[80:83], v[150:153], v[198:201], v[80:83]
	v_mfma_f32_16x16x32_bf16 v[16:19], v[158:161], v[198:201], v[16:19]
	v_mfma_f32_16x16x32_bf16 v[72:75], v[150:153], v[206:209], v[72:75]
	v_mfma_f32_16x16x32_bf16 v[8:11], v[158:161], v[206:209], v[8:11]
	v_mfma_f32_16x16x32_bf16 v[64:67], v[150:153], v[224:227], v[64:67]
	v_mfma_f32_16x16x32_bf16 v[0:3], v[158:161], v[224:227], v[0:3]
	v_mfma_f32_16x16x32_bf16 v[88:91], v[150:153], v[166:169], v[100:103]
	v_mfma_f32_16x16x32_bf16 v[24:27], v[162:165], v[194:197], v[24:27]
	v_mfma_f32_16x16x32_bf16 v[80:83], v[154:157], v[202:205], v[80:83]
	v_mfma_f32_16x16x32_bf16 v[16:19], v[162:165], v[202:205], v[16:19]
	v_mfma_f32_16x16x32_bf16 v[72:75], v[154:157], v[210:213], v[72:75]
	v_mfma_f32_16x16x32_bf16 v[8:11], v[162:165], v[210:213], v[8:11]
	v_mfma_f32_16x16x32_bf16 v[64:67], v[154:157], v[228:231], v[64:67]
	v_mfma_f32_16x16x32_bf16 v[0:3], v[162:165], v[228:231], v[0:3]
	v_mfma_f32_16x16x32_bf16 v[88:91], v[154:157], v[194:197], v[88:91]
	s_barrier
; #define PG8_STAGE(bufoff, gbase, voff) do { _Pragma("unroll") for (int _i = 0; _i < 2; ++_i) \
;         __builtin_amdgcn_global_load_lds((const unsigned*)((const char*)(gbase) + (voff)[_i]), (PG8_LAS unsigned*)(lds + (bufoff) + ldsw + _i * 8192), 16, 0, 0); } while (0)
; #define PG8_LDA(dst, b, h) do { _Pragma("unroll") for (int m = 0; m < 4; ++m) _Pragma("unroll") for (int k = 0; k < 2; ++k) dst[m][k] = *(const PG8_LAS bf16x8*)(lds + PG8_SA(b, h) + aoff + m * 2048 + k * 1024); } while (0)
; #define PG8_LDB(dst, b, h) do { _Pragma("unroll") for (int n = 0; n < 2; ++n) _Pragma("unroll") for (int k = 0; k < 2; ++k) dst[n][k] = *(const PG8_LAS bf16x8*)(lds + PG8_SB(b, h) + boff + n * 2048 + k * 1024); } while (0)
; #define PG8_MMA(ai, bj, At, Bt) do { __builtin_amdgcn_s_setprio(1); _Pragma("unroll") for (int m = 0; m < 4; ++m) _Pragma("unroll") for (int n = 0; n < 2; ++n) _Pragma("unroll") for (int k = 0; k < 2; ++k) \
;         acc[ai][bj][m][n] = __builtin_amdgcn_mfma_f32_16x16x32_bf16(Bt[n][k], At[m][k], acc[ai][bj][m][n], 0, 0, 0); __builtin_amdgcn_s_setprio(0); } while (0)
; #define PG8_WAIT_V(n) asm volatile("s_waitcnt vmcnt(" #n ")" ::: "memory")
; #define PG8_WAIT_L(n) asm volatile("s_waitcnt lgkmcnt(" #n ")" ::: "memory")
; #define PG8_BAR __builtin_amdgcn_s_barrier()
; #define PG8_SCHED __builtin_amdgcn_sched_barrier(0)
; template <class Epi, class Sched, bool ALIGN_EPI = false, bool SP2 = false>
; __device__ __forceinline__ void gemm_phase(PG8_LAS unsigned char* lds, const Gemm g, const Sched& S, const Epi& E, const int tid_in) {
;     ...
;             PG8_LDB(B0, 1, 0); PG8_LDB(B1, 1, 1); PG8_SCHED; PG8_LDA(At, 1, 0); PG8_STAGE(PG8_SA(0, 1), a2 + hstepA, voffA);
;             PG8_WAIT_V(8); PG8_WAIT_L(0); PG8_BAR; PG8_MMA(0, 0, At, B0); PG8_MMA(0, 1, At, B1); PG8_BAR; PG8_SCHED;
;             PG8_LDA(At, 1, 1); PG8_STAGE(PG8_SB(1, 0), b3, voffB); PG8_STAGE(PG8_SB(1, 1), b3 + hstepB, voffB); PG8_STAGE(PG8_SA(1, 0), a3, voffA);
;             PG8_WAIT_V(8); PG8_WAIT_L(0); PG8_BAR; PG8_MMA(1, 0, At, B0); PG8_MMA(1, 1, At, B1); PG8_BAR; PG8_SCHED;
;     ...
;         if constexpr (ALIGN_EPI) { if (wr == 0) PG8_BAR; }
	ds_read_b128 v[92:95], v249 offset:32768
	ds_read_b128 v[96:99], v249 offset:33792
	ds_read_b128 v[100:103], v249 offset:34816
	ds_read_b128 v[146:149], v249 offset:35840
	ds_read_b128 v[150:153], v249 offset:49152
	ds_read_b128 v[154:157], v249 offset:50176
	ds_read_b128 v[158:161], v249 offset:51200
	ds_read_b128 v[162:165], v249 offset:52224
	ds_read_b128 v[166:169], v192 offset:32768
	ds_read_b128 v[194:197], v192 offset:33792
	ds_read_b128 v[198:201], v192 offset:34816
	ds_read_b128 v[202:205], v192 offset:35840
	ds_read_b128 v[206:209], v192 offset:36864
	ds_read_b128 v[210:213], v192 offset:37888
	ds_read_b128 v[224:227], v192 offset:38912
	ds_read_b128 v[228:231], v192 offset:39936
	s_add_i32 s36, 0, 0x18000
	s_add_i32 s37, 0, 0x1c000
	s_add_u32 s34, s44, 0xa0000
	s_addc_u32 s35, s45, 0
	s_mov_b32 m0, s60
	s_nop 0
	global_load_lds_dwordx4 v172, s[34:35]
	s_mov_b32 m0, s61
	s_nop 0
	global_load_lds_dwordx4 v140, s[34:35]
	s_waitcnt vmcnt(8) lgkmcnt(0)
	s_barrier
	v_mfma_f32_16x16x32_bf16 v[136:139], v[92:95], v[166:169], v[136:139]
	v_mfma_f32_16x16x32_bf16 v[60:63], v[100:103], v[166:169], v[60:63]
	v_mfma_f32_16x16x32_bf16 v[128:131], v[92:95], v[198:201], v[128:131]
	v_mfma_f32_16x16x32_bf16 v[52:55], v[100:103], v[198:201], v[52:55]
	v_mfma_f32_16x16x32_bf16 v[120:123], v[92:95], v[206:209], v[120:123]
	v_mfma_f32_16x16x32_bf16 v[44:47], v[100:103], v[206:209], v[44:47]
	v_mfma_f32_16x16x32_bf16 v[112:115], v[92:95], v[224:227], v[112:115]
	v_mfma_f32_16x16x32_bf16 v[36:39], v[100:103], v[224:227], v[36:39]
	v_mfma_f32_16x16x32_bf16 v[136:139], v[96:99], v[194:197], v[136:139]
	v_mfma_f32_16x16x32_bf16 v[60:63], v[146:149], v[194:197], v[60:63]
	v_mfma_f32_16x16x32_bf16 v[128:131], v[96:99], v[202:205], v[128:131]
	v_mfma_f32_16x16x32_bf16 v[52:55], v[146:149], v[202:205], v[52:55]
	v_mfma_f32_16x16x32_bf16 v[120:123], v[96:99], v[210:213], v[120:123]
	v_mfma_f32_16x16x32_bf16 v[44:47], v[146:149], v[210:213], v[44:47]
	v_mfma_f32_16x16x32_bf16 v[112:115], v[96:99], v[228:231], v[112:115]
	v_mfma_f32_16x16x32_bf16 v[36:39], v[146:149], v[228:231], v[36:39]
	v_mfma_f32_16x16x32_bf16 v[132:135], v[150:153], v[166:169], v[132:135]
	v_mfma_f32_16x16x32_bf16 v[56:59], v[158:161], v[166:169], v[56:59]
	v_mfma_f32_16x16x32_bf16 v[124:127], v[150:153], v[198:201], v[124:127]
	v_mfma_f32_16x16x32_bf16 v[48:51], v[158:161], v[198:201], v[48:51]
	v_mfma_f32_16x16x32_bf16 v[116:119], v[150:153], v[206:209], v[116:119]
	v_mfma_f32_16x16x32_bf16 v[40:43], v[158:161], v[206:209], v[40:43]
	v_mfma_f32_16x16x32_bf16 v[108:111], v[150:153], v[224:227], v[108:111]
	v_mfma_f32_16x16x32_bf16 v[32:35], v[158:161], v[224:227], v[32:35]
	v_mfma_f32_16x16x32_bf16 v[132:135], v[154:157], v[194:197], v[132:135]
	v_mfma_f32_16x16x32_bf16 v[56:59], v[162:165], v[194:197], v[56:59]
	v_mfma_f32_16x16x32_bf16 v[124:127], v[154:157], v[202:205], v[124:127]
	v_mfma_f32_16x16x32_bf16 v[48:51], v[162:165], v[202:205], v[48:51]
	v_mfma_f32_16x16x32_bf16 v[116:119], v[154:157], v[210:213], v[116:119]
	v_mfma_f32_16x16x32_bf16 v[40:43], v[162:165], v[210:213], v[40:43]
	v_mfma_f32_16x16x32_bf16 v[108:111], v[154:157], v[228:231], v[108:111]
	v_mfma_f32_16x16x32_bf16 v[32:35], v[162:165], v[228:231], v[32:35]
	s_barrier
	ds_read_b128 v[166:169], v192 offset:49152
	ds_read_b128 v[194:197], v192 offset:50176
	ds_read_b128 v[198:201], v192 offset:51200
	ds_read_b128 v[202:205], v192 offset:52224
	ds_read_b128 v[206:209], v192 offset:53248
	ds_read_b128 v[210:213], v192 offset:54272
	ds_read_b128 v[224:227], v192 offset:55296
	ds_read_b128 v[228:231], v192 offset:56320
	s_add_i32 s34, s36, s38
	s_mov_b32 m0, s34
	s_add_u32 s100, s42, 0x80
	s_addc_u32 s101, s43, 0
	global_load_lds_dwordx4 v172, s[100:101]
	s_add_i32 m0, s34, 0x2000
	s_add_u32 s34, s42, 0xa0080
	s_addc_u32 s35, s43, 0
	s_add_i32 s36, s37, s38
	global_load_lds_dwordx4 v140, s[100:101]
	s_mov_b32 m0, s36
	s_nop 0
	global_load_lds_dwordx4 v172, s[34:35]
	s_add_i32 m0, s36, 0x2000
	s_nop 0
	global_load_lds_dwordx4 v140, s[34:35]
	s_mov_b32 m0, s58
	s_nop 0
	s_add_u32 s100, s44, 0x80
	s_addc_u32 s101, s45, 0
	global_load_lds_dwordx4 v172, s[100:101]
	s_mov_b32 m0, s59
	s_nop 0
	global_load_lds_dwordx4 v140, s[100:101]
	s_waitcnt vmcnt(8) lgkmcnt(0)
	s_barrier
	v_mfma_f32_16x16x32_bf16 v[104:107], v[92:95], v[166:169], v[104:107]
	v_mfma_f32_16x16x32_bf16 v[28:31], v[100:103], v[166:169], v[28:31]
	v_mfma_f32_16x16x32_bf16 v[84:87], v[92:95], v[198:201], v[84:87]
	v_mfma_f32_16x16x32_bf16 v[20:23], v[100:103], v[198:201], v[20:23]
	v_mfma_f32_16x16x32_bf16 v[76:79], v[92:95], v[206:209], v[76:79]
	v_mfma_f32_16x16x32_bf16 v[12:15], v[100:103], v[206:209], v[12:15]
	v_mfma_f32_16x16x32_bf16 v[68:71], v[92:95], v[224:227], v[68:71]
	v_mfma_f32_16x16x32_bf16 v[4:7], v[100:103], v[224:227], v[4:7]
	v_mfma_f32_16x16x32_bf16 v[104:107], v[96:99], v[194:197], v[104:107]
	v_mfma_f32_16x16x32_bf16 v[28:31], v[146:149], v[194:197], v[28:31]
	v_mfma_f32_16x16x32_bf16 v[84:87], v[96:99], v[202:205], v[84:87]
	v_mfma_f32_16x16x32_bf16 v[20:23], v[146:149], v[202:205], v[20:23]
	v_mfma_f32_16x16x32_bf16 v[76:79], v[96:99], v[210:213], v[76:79]
	v_mfma_f32_16x16x32_bf16 v[12:15], v[146:149], v[210:213], v[12:15]
	v_mfma_f32_16x16x32_bf16 v[68:71], v[96:99], v[228:231], v[68:71]
	v_mfma_f32_16x16x32_bf16 v[4:7], v[146:149], v[228:231], v[4:7]
	v_mfma_f32_16x16x32_bf16 v[88:91], v[150:153], v[166:169], v[88:91]
	v_mfma_f32_16x16x32_bf16 v[24:27], v[158:161], v[166:169], v[24:27]
	v_mfma_f32_16x16x32_bf16 v[80:83], v[150:153], v[198:201], v[80:83]
	v_mfma_f32_16x16x32_bf16 v[16:19], v[158:161], v[198:201], v[16:19]
	v_mfma_f32_16x16x32_bf16 v[72:75], v[150:153], v[206:209], v[72:75]
	v_mfma_f32_16x16x32_bf16 v[8:11], v[158:161], v[206:209], v[8:11]
	v_mfma_f32_16x16x32_bf16 v[64:67], v[150:153], v[224:227], v[64:67]
	v_mfma_f32_16x16x32_bf16 v[0:3], v[158:161], v[224:227], v[0:3]
	v_mfma_f32_16x16x32_bf16 v[100:103], v[154:157], v[194:197], v[88:91]
	v_mfma_f32_16x16x32_bf16 v[24:27], v[162:165], v[194:197], v[24:27]
	v_mfma_f32_16x16x32_bf16 v[80:83], v[154:157], v[202:205], v[80:83]
	v_mfma_f32_16x16x32_bf16 v[16:19], v[162:165], v[202:205], v[16:19]
	v_mfma_f32_16x16x32_bf16 v[72:75], v[154:157], v[210:213], v[72:75]
	v_mfma_f32_16x16x32_bf16 v[8:11], v[162:165], v[210:213], v[8:11]
	v_mfma_f32_16x16x32_bf16 v[64:67], v[154:157], v[228:231], v[64:67]
	v_mfma_f32_16x16x32_bf16 v[0:3], v[162:165], v[228:231], v[0:3]
	s_barrier
	s_add_i32 s33, s33, 2
	s_add_u32 s12, s12, 0x100
	s_addc_u32 s21, s21, 0
	s_cmp_gt_u32 s33, 3
	s_mov_b64 s[36:37], s[22:23]
	s_cbranch_scc0 .LBB0_756
	s_and_b64 vcc, exec, s[70:71]
	s_cbranch_vccz .LBB0_759
	s_barrier

;     __device__ __forceinline__ void a_ready(const Unit& u) const { wait_panel(cnt, u.pm, need, tmo, wave); }
;     __device__ __forceinline__ void a_ready(const Unit& u) const { wait_panel(cnt, u.pm, need, tmo, wave); }
; #define PG8_STAGE(bufoff, gbase, voff) do { _Pragma("unroll") for (int _i = 0; _i < 2; ++_i) \
;         __builtin_amdgcn_global_load_lds((const unsigned*)((const char*)(gbase) + (voff)[_i]), (PG8_LAS unsigned*)(lds + (bufoff) + ldsw + _i * 8192), 16, 0, 0); } while (0)
; #define PG8_LDA(dst, b, h) do { _Pragma("unroll") for (int m = 0; m < 4; ++m) _Pragma("unroll") for (int k = 0; k < 2; ++k) dst[m][k] = *(const PG8_LAS bf16x8*)(lds + PG8_SA(b, h) + aoff + m * 2048 + k * 1024); } while (0)
; #define PG8_LDB(dst, b, h) do { _Pragma("unroll") for (int n = 0; n < 2; ++n) _Pragma("unroll") for (int k = 0; k < 2; ++k) dst[n][k] = *(const PG8_LAS bf16x8*)(lds + PG8_SB(b, h) + boff + n * 2048 + k * 1024); } while (0)
; #define PG8_WAIT_V(n) asm volatile("s_waitcnt vmcnt(" #n ")" ::: "memory")
; #define PG8_WAIT_L(n) asm volatile("s_waitcnt lgkmcnt(" #n ")" ::: "memory")
; #define PG8_BAR __builtin_amdgcn_s_barrier()
; #define PG8_SCHED __builtin_amdgcn_sched_barrier(0)
; template <class Epi, class Sched, bool ALIGN_EPI = false, bool SP2 = false>
; __device__ __forceinline__ void gemm_phase(PG8_LAS unsigned char* lds, const Gemm g, const Sched& S, const Epi& E, const int tid_in) {
;     ...
;             const bool last = (t == nt - 2);
;             const char* a1 = cA + (size_t)(t + 1) * kstep;
;             const char* a2 = last ? nA : cA + (size_t)(t + 2) * kstep; const char* b2 = last ? nB : cB + (size_t)(t + 2) * kstep;
;             const char* a3 = a2 + kstep; const char* b3 = b2 + kstep;
;             if (last && has_next) S.a_ready(nxt);
;             if constexpr (SP2) {
;             PG8_LDB(B0, 0, 0); PG8_LDB(B1, 0, 1); PG8_SCHED; PG8_LDA(At, 0, 0); PG8_STAGE(PG8_SA(1, 1), a1 + hstepA, voffA);
;             PG8_WAIT_V(8); PG8_WAIT_L(0); PG8_BAR; PG8_MMA(0, 0, At, B0); PG8_MMA(0, 1, At, B1); PG8_BAR; PG8_SCHED;
;             PG8_LDA(At, 0, 1); PG8_STAGE(PG8_SB(0, 0), b2, voffB); PG8_STAGE(PG8_SB(0, 1), b2 + hstepB, voffB); PG8_STAGE(PG8_SA(0, 0), a2, voffA);
;             PG8_WAIT_V(8); PG8_WAIT_L(0); PG8_BAR; PG8_MMA(1, 0, At, B0); PG8_MMA(1, 1, At, B1); PG8_BAR; PG8_SCHED;
.LBB0_1268:
	ds_read_b128 v[104:107], v249
	ds_read_b128 v[108:111], v249 offset:1024
	ds_read_b128 v[112:115], v249 offset:2048
	ds_read_b128 v[116:119], v249 offset:3072
	ds_read_b128 v[144:147], v249 offset:16384
	ds_read_b128 v[148:151], v249 offset:17408
	ds_read_b128 v[152:155], v249 offset:18432
	ds_read_b128 v[156:159], v249 offset:19456
	ds_read_b128 v[160:163], v204
	ds_read_b128 v[192:195], v204 offset:1024
	ds_read_b128 v[196:199], v204 offset:2048
	ds_read_b128 v[206:209], v204 offset:3072
	ds_read_b128 v[210:213], v204 offset:4096
	ds_read_b128 v[224:227], v204 offset:5120
	ds_read_b128 v[228:231], v204 offset:6144
	ds_read_b128 v[232:235], v204 offset:7168
	s_add_u32 s22, s50, 0x100
	s_addc_u32 s23, s51, 0
	s_add_i32 s63, 0, 0x10000
	s_cmp_eq_u32 s62, 36
	s_cselect_b32 s55, s43, s23
	s_cselect_b32 s54, s42, s22
	s_cselect_b32 s53, s49, s61
	s_cselect_b32 s52, s48, s60
	s_add_i32 s64, 0, 0x14000
	s_add_i32 m0, s30, 0xc000
	s_nop 0
	global_load_lds_dwordx4 v170, s[50:51]
	s_add_i32 m0, s30, 0xe000
	s_nop 0
	global_load_lds_dwordx4 v190, s[50:51]
	s_waitcnt vmcnt(8) lgkmcnt(0)
	s_barrier
	v_mfma_f32_16x16x32_bf16 v[140:143], v[104:107], v[160:163], v[140:143]
	v_mfma_f32_16x16x32_bf16 v[136:139], v[112:115], v[160:163], v[136:139]
	v_mfma_f32_16x16x32_bf16 v[124:127], v[104:107], v[196:199], v[124:127]
	v_mfma_f32_16x16x32_bf16 v[120:123], v[112:115], v[196:199], v[120:123]
	v_mfma_f32_16x16x32_bf16 v[92:95], v[104:107], v[210:213], v[92:95]
	v_mfma_f32_16x16x32_bf16 v[88:91], v[112:115], v[210:213], v[88:91]
	v_mfma_f32_16x16x32_bf16 v[76:79], v[104:107], v[228:231], v[76:79]
	v_mfma_f32_16x16x32_bf16 v[72:75], v[112:115], v[228:231], v[72:75]
	v_mfma_f32_16x16x32_bf16 v[140:143], v[108:111], v[192:195], v[140:143]
	v_mfma_f32_16x16x32_bf16 v[136:139], v[116:119], v[192:195], v[136:139]
	v_mfma_f32_16x16x32_bf16 v[124:127], v[108:111], v[206:209], v[124:127]
	v_mfma_f32_16x16x32_bf16 v[120:123], v[116:119], v[206:209], v[120:123]
	v_mfma_f32_16x16x32_bf16 v[92:95], v[108:111], v[224:227], v[92:95]
	v_mfma_f32_16x16x32_bf16 v[88:91], v[116:119], v[224:227], v[88:91]
	v_mfma_f32_16x16x32_bf16 v[76:79], v[108:111], v[232:235], v[76:79]
	v_mfma_f32_16x16x32_bf16 v[72:75], v[116:119], v[232:235], v[72:75]
	v_mfma_f32_16x16x32_bf16 v[132:135], v[144:147], v[160:163], v[132:135]
	v_mfma_f32_16x16x32_bf16 v[128:131], v[152:155], v[160:163], v[128:131]
	v_mfma_f32_16x16x32_bf16 v[100:103], v[144:147], v[196:199], v[100:103]
	v_mfma_f32_16x16x32_bf16 v[96:99], v[152:155], v[196:199], v[96:99]
	v_mfma_f32_16x16x32_bf16 v[84:87], v[144:147], v[210:213], v[84:87]
	v_mfma_f32_16x16x32_bf16 v[80:83], v[152:155], v[210:213], v[80:83]
	v_mfma_f32_16x16x32_bf16 v[68:71], v[144:147], v[228:231], v[68:71]
	v_mfma_f32_16x16x32_bf16 v[64:67], v[152:155], v[228:231], v[64:67]
	v_mfma_f32_16x16x32_bf16 v[132:135], v[148:151], v[192:195], v[132:135]
	v_mfma_f32_16x16x32_bf16 v[128:131], v[156:159], v[192:195], v[128:131]
	v_mfma_f32_16x16x32_bf16 v[100:103], v[148:151], v[206:209], v[100:103]
	v_mfma_f32_16x16x32_bf16 v[96:99], v[156:159], v[206:209], v[96:99]
	v_mfma_f32_16x16x32_bf16 v[84:87], v[148:151], v[224:227], v[84:87]
	v_mfma_f32_16x16x32_bf16 v[80:83], v[156:159], v[224:227], v[80:83]
	v_mfma_f32_16x16x32_bf16 v[68:71], v[148:151], v[232:235], v[68:71]
	v_mfma_f32_16x16x32_bf16 v[64:67], v[156:159], v[232:235], v[64:67]
	s_barrier
	ds_read_b128 v[160:163], v204 offset:16384
	ds_read_b128 v[192:195], v204 offset:17408
	ds_read_b128 v[196:199], v204 offset:18432
	ds_read_b128 v[206:209], v204 offset:19456
	ds_read_b128 v[210:213], v204 offset:20480
	ds_read_b128 v[224:227], v204 offset:21504
	ds_read_b128 v[228:231], v204 offset:22528
	ds_read_b128 v[232:235], v204 offset:23552
	s_add_i32 s50, s63, s21
	s_mov_b32 m0, s50
	s_nop 0
	global_load_lds_dwordx4 v172, s[52:53]
	s_add_i32 m0, s50, 0x2000
	s_add_u32 s50, s52, 0xa0000
	s_addc_u32 s51, s53, 0
	s_add_u32 vcc_lo, s52, 0x80
	s_addc_u32 vcc_hi, s53, 0
	s_add_i32 s63, s64, s21
	global_load_lds_dwordx4 v168, s[52:53]
	s_mov_b32 m0, s63
	s_nop 0
	global_load_lds_dwordx4 v172, s[50:51]
	s_add_i32 m0, s63, 0x2000
	s_nop 0
	global_load_lds_dwordx4 v168, s[50:51]
	s_mov_b32 m0, s30
	s_nop 0
	global_load_lds_dwordx4 v164, s[54:55]
	s_mov_b32 m0, s31
	s_nop 0
	global_load_lds_dwordx4 v166, s[54:55]
	s_waitcnt vmcnt(8) lgkmcnt(0)
	s_barrier
	v_mfma_f32_16x16x32_bf16 v[60:63], v[104:107], v[160:163], v[60:63]
	v_mfma_f32_16x16x32_bf16 v[56:59], v[112:115], v[160:163], v[56:59]
	v_mfma_f32_16x16x32_bf16 v[44:47], v[104:107], v[196:199], v[44:47]
	v_mfma_f32_16x16x32_bf16 v[40:43], v[112:115], v[196:199], v[40:43]
	v_mfma_f32_16x16x32_bf16 v[28:31], v[104:107], v[210:213], v[28:31]
	v_mfma_f32_16x16x32_bf16 v[24:27], v[112:115], v[210:213], v[24:27]
	v_mfma_f32_16x16x32_bf16 v[12:15], v[104:107], v[228:231], v[12:15]
	v_mfma_f32_16x16x32_bf16 v[8:11], v[112:115], v[228:231], v[8:11]
	v_mfma_f32_16x16x32_bf16 v[60:63], v[108:111], v[192:195], v[60:63]
	v_mfma_f32_16x16x32_bf16 v[56:59], v[116:119], v[192:195], v[56:59]
	v_mfma_f32_16x16x32_bf16 v[44:47], v[108:111], v[206:209], v[44:47]
	v_mfma_f32_16x16x32_bf16 v[40:43], v[116:119], v[206:209], v[40:43]
	v_mfma_f32_16x16x32_bf16 v[28:31], v[108:111], v[224:227], v[28:31]
	v_mfma_f32_16x16x32_bf16 v[24:27], v[116:119], v[224:227], v[24:27]
	v_mfma_f32_16x16x32_bf16 v[12:15], v[108:111], v[232:235], v[12:15]
	v_mfma_f32_16x16x32_bf16 v[8:11], v[116:119], v[232:235], v[8:11]
	v_mfma_f32_16x16x32_bf16 v[52:55], v[144:147], v[160:163], v[52:55]
	v_mfma_f32_16x16x32_bf16 v[48:51], v[152:155], v[160:163], v[48:51]
	v_mfma_f32_16x16x32_bf16 v[36:39], v[144:147], v[196:199], v[36:39]
	v_mfma_f32_16x16x32_bf16 v[32:35], v[152:155], v[196:199], v[32:35]
	v_mfma_f32_16x16x32_bf16 v[20:23], v[144:147], v[210:213], v[20:23]
	v_mfma_f32_16x16x32_bf16 v[16:19], v[152:155], v[210:213], v[16:19]
	v_mfma_f32_16x16x32_bf16 v[4:7], v[144:147], v[228:231], v[4:7]
	v_mfma_f32_16x16x32_bf16 v[0:3], v[152:155], v[228:231], v[0:3]
	v_mfma_f32_16x16x32_bf16 v[52:55], v[148:151], v[192:195], v[52:55]
	v_mfma_f32_16x16x32_bf16 v[48:51], v[156:159], v[192:195], v[48:51]
	v_mfma_f32_16x16x32_bf16 v[36:39], v[148:151], v[206:209], v[36:39]
	v_mfma_f32_16x16x32_bf16 v[32:35], v[156:159], v[206:209], v[32:35]
	v_mfma_f32_16x16x32_bf16 v[20:23], v[148:151], v[224:227], v[20:23]
	v_mfma_f32_16x16x32_bf16 v[16:19], v[156:159], v[224:227], v[16:19]
	v_mfma_f32_16x16x32_bf16 v[4:7], v[148:151], v[232:235], v[4:7]
	v_mfma_f32_16x16x32_bf16 v[0:3], v[156:159], v[232:235], v[0:3]
	s_barrier
; #define PG8_STAGE(bufoff, gbase, voff) do { _Pragma("unroll") for (int _i = 0; _i < 2; ++_i) \
;         __builtin_amdgcn_global_load_lds((const unsigned*)((const char*)(gbase) + (voff)[_i]), (PG8_LAS unsigned*)(lds + (bufoff) + ldsw + _i * 8192), 16, 0, 0); } while (0)
; #define PG8_LDA(dst, b, h) do { _Pragma("unroll") for (int m = 0; m < 4; ++m) _Pragma("unroll") for (int k = 0; k < 2; ++k) dst[m][k] = *(const PG8_LAS bf16x8*)(lds + PG8_SA(b, h) + aoff + m * 2048 + k * 1024); } while (0)
; #define PG8_LDB(dst, b, h) do { _Pragma("unroll") for (int n = 0; n < 2; ++n) _Pragma("unroll") for (int k = 0; k < 2; ++k) dst[n][k] = *(const PG8_LAS bf16x8*)(lds + PG8_SB(b, h) + boff + n * 2048 + k * 1024); } while (0)
; #define PG8_MMA(ai, bj, At, Bt) do { __builtin_amdgcn_s_setprio(1); _Pragma("unroll") for (int m = 0; m < 4; ++m) _Pragma("unroll") for (int n = 0; n < 2; ++n) _Pragma("unroll") for (int k = 0; k < 2; ++k) \
;         acc[ai][bj][m][n] = __builtin_amdgcn_mfma_f32_16x16x32_bf16(Bt[n][k], At[m][k], acc[ai][bj][m][n], 0, 0, 0); __builtin_amdgcn_s_setprio(0); } while (0)
; #define PG8_WAIT_V(n) asm volatile("s_waitcnt vmcnt(" #n ")" ::: "memory")
; #define PG8_WAIT_L(n) asm volatile("s_waitcnt lgkmcnt(" #n ")" ::: "memory")
; #define PG8_BAR __builtin_amdgcn_s_barrier()
; #define PG8_SCHED __builtin_amdgcn_sched_barrier(0)
; template <class Epi, class Sched, bool ALIGN_EPI = false, bool SP2 = false>
; __device__ __forceinline__ void gemm_phase(PG8_LAS unsigned char* lds, const Gemm g, const Sched& S, const Epi& E, const int tid_in) {
;     ...
;             PG8_LDB(B0, 1, 0); PG8_LDB(B1, 1, 1); PG8_SCHED; PG8_LDA(At, 1, 0); PG8_STAGE(PG8_SA(0, 1), a2 + hstepA, voffA);
;             PG8_WAIT_V(8); PG8_WAIT_L(0); PG8_BAR; PG8_MMA(0, 0, At, B0); PG8_MMA(0, 1, At, B1); PG8_BAR; PG8_SCHED;
;             PG8_LDA(At, 1, 1); PG8_STAGE(PG8_SB(1, 0), b3, voffB); PG8_STAGE(PG8_SB(1, 1), b3 + hstepB, voffB); PG8_STAGE(PG8_SA(1, 0), a3, voffA);
;             PG8_WAIT_V(8); PG8_WAIT_L(0); PG8_BAR; PG8_MMA(1, 0, At, B0); PG8_MMA(1, 1, At, B1); PG8_BAR; PG8_SCHED;
;     ...
;         if constexpr (ALIGN_EPI) { if (wr == 0) PG8_BAR; }
	ds_read_b128 v[104:107], v249 offset:32768
	ds_read_b128 v[108:111], v249 offset:33792
	ds_read_b128 v[112:115], v249 offset:34816
	ds_read_b128 v[116:119], v249 offset:35840
	ds_read_b128 v[144:147], v249 offset:49152
	ds_read_b128 v[148:151], v249 offset:50176
	ds_read_b128 v[152:155], v249 offset:51200
	ds_read_b128 v[156:159], v249 offset:52224
	ds_read_b128 v[160:163], v204 offset:32768
	ds_read_b128 v[192:195], v204 offset:33792
	ds_read_b128 v[196:199], v204 offset:34816
	ds_read_b128 v[206:209], v204 offset:35840
	ds_read_b128 v[210:213], v204 offset:36864
	ds_read_b128 v[224:227], v204 offset:37888
	ds_read_b128 v[228:231], v204 offset:38912
	ds_read_b128 v[232:235], v204 offset:39936
	s_add_i32 s63, 0, 0x18000
	s_add_i32 s64, 0, 0x1c000
	s_add_u32 s50, s54, 0xa0000
	s_addc_u32 s51, s55, 0
	s_mov_b32 m0, s6
	s_nop 0
	global_load_lds_dwordx4 v164, s[50:51]
	s_mov_b32 m0, s38
	s_nop 0
	global_load_lds_dwordx4 v166, s[50:51]
	s_waitcnt vmcnt(8) lgkmcnt(0)
	s_barrier
	v_mfma_f32_16x16x32_bf16 v[140:143], v[104:107], v[160:163], v[140:143]
	v_mfma_f32_16x16x32_bf16 v[136:139], v[112:115], v[160:163], v[136:139]
	v_mfma_f32_16x16x32_bf16 v[124:127], v[104:107], v[196:199], v[124:127]
	v_mfma_f32_16x16x32_bf16 v[120:123], v[112:115], v[196:199], v[120:123]
	v_mfma_f32_16x16x32_bf16 v[92:95], v[104:107], v[210:213], v[92:95]
	v_mfma_f32_16x16x32_bf16 v[88:91], v[112:115], v[210:213], v[88:91]
	v_mfma_f32_16x16x32_bf16 v[76:79], v[104:107], v[228:231], v[76:79]
	v_mfma_f32_16x16x32_bf16 v[72:75], v[112:115], v[228:231], v[72:75]
	v_mfma_f32_16x16x32_bf16 v[140:143], v[108:111], v[192:195], v[140:143]
	v_mfma_f32_16x16x32_bf16 v[136:139], v[116:119], v[192:195], v[136:139]
	v_mfma_f32_16x16x32_bf16 v[124:127], v[108:111], v[206:209], v[124:127]
	v_mfma_f32_16x16x32_bf16 v[120:123], v[116:119], v[206:209], v[120:123]
	v_mfma_f32_16x16x32_bf16 v[92:95], v[108:111], v[224:227], v[92:95]
	v_mfma_f32_16x16x32_bf16 v[88:91], v[116:119], v[224:227], v[88:91]
	v_mfma_f32_16x16x32_bf16 v[76:79], v[108:111], v[232:235], v[76:79]
	v_mfma_f32_16x16x32_bf16 v[72:75], v[116:119], v[232:235], v[72:75]
	v_mfma_f32_16x16x32_bf16 v[132:135], v[144:147], v[160:163], v[132:135]
	v_mfma_f32_16x16x32_bf16 v[128:131], v[152:155], v[160:163], v[128:131]
	v_mfma_f32_16x16x32_bf16 v[100:103], v[144:147], v[196:199], v[100:103]
	v_mfma_f32_16x16x32_bf16 v[96:99], v[152:155], v[196:199], v[96:99]
	v_mfma_f32_16x16x32_bf16 v[84:87], v[144:147], v[210:213], v[84:87]
	v_mfma_f32_16x16x32_bf16 v[80:83], v[152:155], v[210:213], v[80:83]
	v_mfma_f32_16x16x32_bf16 v[68:71], v[144:147], v[228:231], v[68:71]
	v_mfma_f32_16x16x32_bf16 v[64:67], v[152:155], v[228:231], v[64:67]
	v_mfma_f32_16x16x32_bf16 v[132:135], v[148:151], v[192:195], v[132:135]
	v_mfma_f32_16x16x32_bf16 v[128:131], v[156:159], v[192:195], v[128:131]
	v_mfma_f32_16x16x32_bf16 v[100:103], v[148:151], v[206:209], v[100:103]
	v_mfma_f32_16x16x32_bf16 v[96:99], v[156:159], v[206:209], v[96:99]
	v_mfma_f32_16x16x32_bf16 v[84:87], v[148:151], v[224:227], v[84:87]
	v_mfma_f32_16x16x32_bf16 v[80:83], v[156:159], v[224:227], v[80:83]
	v_mfma_f32_16x16x32_bf16 v[68:71], v[148:151], v[232:235], v[68:71]
	v_mfma_f32_16x16x32_bf16 v[64:67], v[156:159], v[232:235], v[64:67]
	s_barrier
	ds_read_b128 v[160:163], v204 offset:49152
	ds_read_b128 v[192:195], v204 offset:50176
	ds_read_b128 v[196:199], v204 offset:51200
	ds_read_b128 v[206:209], v204 offset:52224
	ds_read_b128 v[210:213], v204 offset:53248
	ds_read_b128 v[224:227], v204 offset:54272
	ds_read_b128 v[228:231], v204 offset:55296
	ds_read_b128 v[232:235], v204 offset:56320
	s_add_i32 s50, s63, s21
	s_mov_b32 m0, s50
	s_add_u32 s100, s52, 0x80
	s_addc_u32 s101, s53, 0
	global_load_lds_dwordx4 v172, s[100:101]
	s_add_i32 m0, s50, 0x2000
	s_add_u32 s50, s52, 0xa0080
	s_addc_u32 s51, s53, 0
	s_add_i32 s52, s64, s21
	global_load_lds_dwordx4 v168, vcc
	s_mov_b32 m0, s52
	s_nop 0
	global_load_lds_dwordx4 v172, s[50:51]
	s_add_i32 m0, s52, 0x2000
	s_nop 0
	global_load_lds_dwordx4 v168, s[50:51]
	s_mov_b32 m0, s33
	s_nop 0
	s_add_u32 s100, s54, 0x80
	s_addc_u32 s101, s55, 0
	global_load_lds_dwordx4 v164, s[100:101]
	s_mov_b32 m0, s35
	s_nop 0
	global_load_lds_dwordx4 v166, s[100:101]
	s_waitcnt vmcnt(8) lgkmcnt(0)
	s_barrier
	v_mfma_f32_16x16x32_bf16 v[60:63], v[104:107], v[160:163], v[60:63]
	v_mfma_f32_16x16x32_bf16 v[56:59], v[112:115], v[160:163], v[56:59]
	v_mfma_f32_16x16x32_bf16 v[44:47], v[104:107], v[196:199], v[44:47]
	v_mfma_f32_16x16x32_bf16 v[40:43], v[112:115], v[196:199], v[40:43]
	v_mfma_f32_16x16x32_bf16 v[28:31], v[104:107], v[210:213], v[28:31]
	v_mfma_f32_16x16x32_bf16 v[24:27], v[112:115], v[210:213], v[24:27]
	v_mfma_f32_16x16x32_bf16 v[12:15], v[104:107], v[228:231], v[12:15]
	v_mfma_f32_16x16x32_bf16 v[8:11], v[112:115], v[228:231], v[8:11]
	v_mfma_f32_16x16x32_bf16 v[60:63], v[108:111], v[192:195], v[60:63]
	v_mfma_f32_16x16x32_bf16 v[56:59], v[116:119], v[192:195], v[56:59]
	v_mfma_f32_16x16x32_bf16 v[44:47], v[108:111], v[206:209], v[44:47]
	v_mfma_f32_16x16x32_bf16 v[40:43], v[116:119], v[206:209], v[40:43]
	v_mfma_f32_16x16x32_bf16 v[28:31], v[108:111], v[224:227], v[28:31]
	v_mfma_f32_16x16x32_bf16 v[24:27], v[116:119], v[224:227], v[24:27]
	v_mfma_f32_16x16x32_bf16 v[12:15], v[108:111], v[232:235], v[12:15]
	v_mfma_f32_16x16x32_bf16 v[8:11], v[116:119], v[232:235], v[8:11]
	v_mfma_f32_16x16x32_bf16 v[52:55], v[144:147], v[160:163], v[52:55]
	v_mfma_f32_16x16x32_bf16 v[48:51], v[152:155], v[160:163], v[48:51]
	v_mfma_f32_16x16x32_bf16 v[36:39], v[144:147], v[196:199], v[36:39]
	v_mfma_f32_16x16x32_bf16 v[32:35], v[152:155], v[196:199], v[32:35]
	v_mfma_f32_16x16x32_bf16 v[20:23], v[144:147], v[210:213], v[20:23]
	v_mfma_f32_16x16x32_bf16 v[16:19], v[152:155], v[210:213], v[16:19]
	v_mfma_f32_16x16x32_bf16 v[4:7], v[144:147], v[228:231], v[4:7]
	v_mfma_f32_16x16x32_bf16 v[0:3], v[152:155], v[228:231], v[0:3]
	v_mfma_f32_16x16x32_bf16 v[52:55], v[148:151], v[192:195], v[52:55]
	v_mfma_f32_16x16x32_bf16 v[48:51], v[156:159], v[192:195], v[48:51]
	v_mfma_f32_16x16x32_bf16 v[36:39], v[148:151], v[206:209], v[36:39]
	v_mfma_f32_16x16x32_bf16 v[32:35], v[156:159], v[206:209], v[32:35]
	v_mfma_f32_16x16x32_bf16 v[20:23], v[148:151], v[224:227], v[20:23]
	v_mfma_f32_16x16x32_bf16 v[16:19], v[156:159], v[224:227], v[16:19]
	v_mfma_f32_16x16x32_bf16 v[4:7], v[148:151], v[232:235], v[4:7]
	v_mfma_f32_16x16x32_bf16 v[0:3], v[156:159], v[232:235], v[0:3]
	s_barrier
	s_add_i32 s62, s62, 2
	s_add_u32 s60, s60, 0x100
	s_addc_u32 s61, s61, 0
	s_cmp_gt_u32 s62, 37
	s_mov_b64 s[50:51], s[22:23]
	s_cbranch_scc0 .LBB0_1268
	s_and_b64 vcc, exec, s[46:47]
	s_cbranch_vccz .LBB0_1271
	s_barrier

;     __device__ __forceinline__ void a_ready(const Unit& u) const { wait_panel(cnt, u.pm, need, tmo, wave); }
;     __device__ __forceinline__ void a_ready(const Unit& u) const { wait_panel(cnt, u.pm, need, tmo, wave); }
; #define PG8_STAGE(bufoff, gbase, voff) do { _Pragma("unroll") for (int _i = 0; _i < 2; ++_i) \
;         __builtin_amdgcn_global_load_lds((const unsigned*)((const char*)(gbase) + (voff)[_i]), (PG8_LAS unsigned*)(lds + (bufoff) + ldsw + _i * 8192), 16, 0, 0); } while (0)
; #define PG8_LDA(dst, b, h) do { _Pragma("unroll") for (int m = 0; m < 4; ++m) _Pragma("unroll") for (int k = 0; k < 2; ++k) dst[m][k] = *(const PG8_LAS bf16x8*)(lds + PG8_SA(b, h) + aoff + m * 2048 + k * 1024); } while (0)
; #define PG8_LDB(dst, b, h) do { _Pragma("unroll") for (int n = 0; n < 2; ++n) _Pragma("unroll") for (int k = 0; k < 2; ++k) dst[n][k] = *(const PG8_LAS bf16x8*)(lds + PG8_SB(b, h) + boff + n * 2048 + k * 1024); } while (0)
; #define PG8_WAIT_V(n) asm volatile("s_waitcnt vmcnt(" #n ")" ::: "memory")
; #define PG8_WAIT_L(n) asm volatile("s_waitcnt lgkmcnt(" #n ")" ::: "memory")
; #define PG8_BAR __builtin_amdgcn_s_barrier()
; #define PG8_SCHED __builtin_amdgcn_sched_barrier(0)
; template <class Epi, class Sched, bool ALIGN_EPI = false, bool SP2 = false>
; __device__ __forceinline__ void gemm_phase(PG8_LAS unsigned char* lds, const Gemm g, const Sched& S, const Epi& E, const int tid_in) {
;     ...
;             const bool last = (t == nt - 2);
;             const char* a1 = cA + (size_t)(t + 1) * kstep;
;             const char* a2 = last ? nA : cA + (size_t)(t + 2) * kstep; const char* b2 = last ? nB : cB + (size_t)(t + 2) * kstep;
;             const char* a3 = a2 + kstep; const char* b3 = b2 + kstep;
;             if (last && has_next) S.a_ready(nxt);
;             if constexpr (SP2) {
;             PG8_LDB(B0, 0, 0); PG8_LDB(B1, 0, 1); PG8_SCHED; PG8_LDA(At, 0, 0); PG8_STAGE(PG8_SA(1, 1), a1 + hstepA, voffA);
;             PG8_WAIT_V(8); PG8_WAIT_L(0); PG8_BAR; PG8_MMA(0, 0, At, B0); PG8_MMA(0, 1, At, B1); PG8_BAR; PG8_SCHED;
;             PG8_LDA(At, 0, 1); PG8_STAGE(PG8_SB(0, 0), b2, voffB); PG8_STAGE(PG8_SB(0, 1), b2 + hstepB, voffB); PG8_STAGE(PG8_SA(0, 0), a2, voffA);
;             PG8_WAIT_V(8); PG8_WAIT_L(0); PG8_BAR; PG8_MMA(1, 0, At, B0); PG8_MMA(1, 1, At, B1); PG8_BAR; PG8_SCHED;
.LBB0_1286:
	ds_read_b128 v[64:67], v249
	ds_read_b128 v[68:71], v249 offset:1024
	ds_read_b128 v[72:75], v249 offset:2048
	ds_read_b128 v[76:79], v249 offset:3072
	ds_read_b128 v[80:83], v249 offset:16384
	ds_read_b128 v[84:87], v249 offset:17408
	ds_read_b128 v[88:91], v249 offset:18432
	ds_read_b128 v[92:95], v249 offset:19456
	ds_read_b128 v[96:99], v154
	ds_read_b128 v[100:103], v154 offset:1024
	ds_read_b128 v[104:107], v154 offset:2048
	ds_read_b128 v[108:111], v154 offset:3072
	ds_read_b128 v[112:115], v154 offset:4096
	ds_read_b128 v[116:119], v154 offset:5120
	ds_read_b128 v[120:123], v154 offset:6144
	ds_read_b128 v[124:127], v154 offset:7168
	s_add_u32 s22, s62, 0x100
	s_addc_u32 s23, s63, 0
	s_add_i32 s68, 0, 0x10000
	s_cmp_eq_u32 s61, 4
	s_cselect_b32 s67, s57, s23
	s_cselect_b32 s66, s56, s22
	s_cselect_b32 s65, s55, s60
	s_cselect_b32 s64, s54, s59
	s_add_i32 s69, 0, 0x14000
	s_add_i32 m0, s12, 0xc000
	s_nop 0
	global_load_lds_dwordx4 v148, s[62:63]
	s_add_i32 m0, s12, 0xe000
	s_nop 0
	global_load_lds_dwordx4 v146, s[62:63]
	s_waitcnt vmcnt(8) lgkmcnt(0)
	s_barrier
	v_mfma_f32_16x16x32_bf16 v[60:63], v[64:67], v[96:99], v[60:63]
	v_mfma_f32_16x16x32_bf16 v[56:59], v[72:75], v[96:99], v[56:59]
	v_mfma_f32_16x16x32_bf16 v[48:51], v[64:67], v[104:107], v[48:51]
	v_mfma_f32_16x16x32_bf16 v[40:43], v[72:75], v[104:107], v[40:43]
	v_mfma_f32_16x16x32_bf16 v[32:35], v[64:67], v[112:115], v[32:35]
	v_mfma_f32_16x16x32_bf16 v[24:27], v[72:75], v[112:115], v[24:27]
	v_mfma_f32_16x16x32_bf16 v[16:19], v[64:67], v[120:123], v[16:19]
	v_mfma_f32_16x16x32_bf16 v[8:11], v[72:75], v[120:123], v[8:11]
	v_mfma_f32_16x16x32_bf16 v[60:63], v[68:71], v[100:103], v[60:63]
	v_mfma_f32_16x16x32_bf16 v[56:59], v[76:79], v[100:103], v[56:59]
	v_mfma_f32_16x16x32_bf16 v[48:51], v[68:71], v[108:111], v[48:51]
	v_mfma_f32_16x16x32_bf16 v[40:43], v[76:79], v[108:111], v[40:43]
	v_mfma_f32_16x16x32_bf16 v[32:35], v[68:71], v[116:119], v[32:35]
	v_mfma_f32_16x16x32_bf16 v[24:27], v[76:79], v[116:119], v[24:27]
	v_mfma_f32_16x16x32_bf16 v[16:19], v[68:71], v[124:127], v[16:19]
	v_mfma_f32_16x16x32_bf16 v[8:11], v[76:79], v[124:127], v[8:11]
	v_mfma_f32_16x16x32_bf16 v[52:55], v[80:83], v[96:99], v[52:55]
	v_mfma_f32_16x16x32_bf16 v[44:47], v[88:91], v[96:99], v[44:47]
	v_mfma_f32_16x16x32_bf16 v[36:39], v[80:83], v[104:107], v[36:39]
	v_mfma_f32_16x16x32_bf16 v[28:31], v[88:91], v[104:107], v[28:31]
	v_mfma_f32_16x16x32_bf16 v[20:23], v[80:83], v[112:115], v[20:23]
	v_mfma_f32_16x16x32_bf16 v[12:15], v[88:91], v[112:115], v[12:15]
	v_mfma_f32_16x16x32_bf16 v[4:7], v[80:83], v[120:123], v[4:7]
	v_mfma_f32_16x16x32_bf16 v[0:3], v[88:91], v[120:123], v[0:3]
	v_mfma_f32_16x16x32_bf16 v[52:55], v[84:87], v[100:103], v[52:55]
	v_mfma_f32_16x16x32_bf16 v[44:47], v[92:95], v[100:103], v[44:47]
	v_mfma_f32_16x16x32_bf16 v[36:39], v[84:87], v[108:111], v[36:39]
	v_mfma_f32_16x16x32_bf16 v[28:31], v[92:95], v[108:111], v[28:31]
	v_mfma_f32_16x16x32_bf16 v[20:23], v[84:87], v[116:119], v[20:23]
	v_mfma_f32_16x16x32_bf16 v[12:15], v[92:95], v[116:119], v[12:15]
	v_mfma_f32_16x16x32_bf16 v[4:7], v[84:87], v[124:127], v[4:7]
	v_mfma_f32_16x16x32_bf16 v[0:3], v[92:95], v[124:127], v[0:3]
	s_barrier
	s_add_i32 s62, s68, s6
	s_mov_b32 m0, s62
	s_add_u32 vcc_lo, s64, 0x80
	s_addc_u32 vcc_hi, s65, 0
	global_load_lds_dwordx4 v172, s[64:65]
	s_add_i32 m0, s62, 0x2000
	s_add_u32 s62, s64, 0xa0000
	s_addc_u32 s63, s65, 0
	s_add_i32 s68, s69, s6
	global_load_lds_dwordx4 v128, s[64:65]
	s_mov_b32 m0, s68
	s_nop 0
	global_load_lds_dwordx4 v172, s[62:63]
	s_add_i32 m0, s68, 0x2000
	s_nop 0
	global_load_lds_dwordx4 v128, s[62:63]
	s_mov_b32 m0, s12
	s_nop 0
	global_load_lds_dwordx4 v172, s[66:67]
	s_mov_b32 m0, s20
	s_nop 0
	global_load_lds_dwordx4 v128, s[66:67]
	s_waitcnt vmcnt(8) lgkmcnt(0)
	s_barrier
	s_barrier
; #define PG8_STAGE(bufoff, gbase, voff) do { _Pragma("unroll") for (int _i = 0; _i < 2; ++_i) \
;         __builtin_amdgcn_global_load_lds((const unsigned*)((const char*)(gbase) + (voff)[_i]), (PG8_LAS unsigned*)(lds + (bufoff) + ldsw + _i * 8192), 16, 0, 0); } while (0)
; #define PG8_LDA(dst, b, h) do { _Pragma("unroll") for (int m = 0; m < 4; ++m) _Pragma("unroll") for (int k = 0; k < 2; ++k) dst[m][k] = *(const PG8_LAS bf16x8*)(lds + PG8_SA(b, h) + aoff + m * 2048 + k * 1024); } while (0)
; #define PG8_LDB(dst, b, h) do { _Pragma("unroll") for (int n = 0; n < 2; ++n) _Pragma("unroll") for (int k = 0; k < 2; ++k) dst[n][k] = *(const PG8_LAS bf16x8*)(lds + PG8_SB(b, h) + boff + n * 2048 + k * 1024); } while (0)
; #define PG8_MMA(ai, bj, At, Bt) do { __builtin_amdgcn_s_setprio(1); _Pragma("unroll") for (int m = 0; m < 4; ++m) _Pragma("unroll") for (int n = 0; n < 2; ++n) _Pragma("unroll") for (int k = 0; k < 2; ++k) \
;         acc[ai][bj][m][n] = __builtin_amdgcn_mfma_f32_16x16x32_bf16(Bt[n][k], At[m][k], acc[ai][bj][m][n], 0, 0, 0); __builtin_amdgcn_s_setprio(0); } while (0)
; #define PG8_WAIT_V(n) asm volatile("s_waitcnt vmcnt(" #n ")" ::: "memory")
; #define PG8_WAIT_L(n) asm volatile("s_waitcnt lgkmcnt(" #n ")" ::: "memory")
; #define PG8_BAR __builtin_amdgcn_s_barrier()
; #define PG8_SCHED __builtin_amdgcn_sched_barrier(0)
; template <class Epi, class Sched, bool ALIGN_EPI = false, bool SP2 = false>
; __device__ __forceinline__ void gemm_phase(PG8_LAS unsigned char* lds, const Gemm g, const Sched& S, const Epi& E, const int tid_in) {
;     ...
;             PG8_LDB(B0, 1, 0); PG8_LDB(B1, 1, 1); PG8_SCHED; PG8_LDA(At, 1, 0); PG8_STAGE(PG8_SA(0, 1), a2 + hstepA, voffA);
;             PG8_WAIT_V(8); PG8_WAIT_L(0); PG8_BAR; PG8_MMA(0, 0, At, B0); PG8_MMA(0, 1, At, B1); PG8_BAR; PG8_SCHED;
;             PG8_LDA(At, 1, 1); PG8_STAGE(PG8_SB(1, 0), b3, voffB); PG8_STAGE(PG8_SB(1, 1), b3 + hstepB, voffB); PG8_STAGE(PG8_SA(1, 0), a3, voffA);
;             PG8_WAIT_V(8); PG8_WAIT_L(0); PG8_BAR; PG8_MMA(1, 0, At, B0); PG8_MMA(1, 1, At, B1); PG8_BAR; PG8_SCHED;
;     ...
;         if constexpr (ALIGN_EPI) { if (wr == 0) PG8_BAR; }
	ds_read_b128 v[64:67], v249 offset:32768
	ds_read_b128 v[68:71], v249 offset:33792
	ds_read_b128 v[72:75], v249 offset:34816
	ds_read_b128 v[76:79], v249 offset:35840
	ds_read_b128 v[80:83], v249 offset:49152
	ds_read_b128 v[84:87], v249 offset:50176
	ds_read_b128 v[88:91], v249 offset:51200
	ds_read_b128 v[92:95], v249 offset:52224
	ds_read_b128 v[96:99], v154 offset:32768
	ds_read_b128 v[100:103], v154 offset:33792
	ds_read_b128 v[104:107], v154 offset:34816
	ds_read_b128 v[108:111], v154 offset:35840
	ds_read_b128 v[112:115], v154 offset:36864
	ds_read_b128 v[116:119], v154 offset:37888
	ds_read_b128 v[120:123], v154 offset:38912
	ds_read_b128 v[124:127], v154 offset:39936
	s_add_i32 s68, 0, 0x18000
	s_add_i32 s69, 0, 0x1c000
	s_add_u32 s62, s66, 0xa0000
	s_addc_u32 s63, s67, 0
	s_mov_b32 m0, s21
	s_nop 0
	global_load_lds_dwordx4 v172, s[62:63]
	s_mov_b32 m0, s30
	s_nop 0
	global_load_lds_dwordx4 v128, s[62:63]
	s_waitcnt vmcnt(8) lgkmcnt(0)
	s_barrier
	v_mfma_f32_16x16x32_bf16 v[60:63], v[64:67], v[96:99], v[60:63]
	v_mfma_f32_16x16x32_bf16 v[56:59], v[72:75], v[96:99], v[56:59]
	v_mfma_f32_16x16x32_bf16 v[48:51], v[64:67], v[104:107], v[48:51]
	v_mfma_f32_16x16x32_bf16 v[40:43], v[72:75], v[104:107], v[40:43]
	v_mfma_f32_16x16x32_bf16 v[32:35], v[64:67], v[112:115], v[32:35]
	v_mfma_f32_16x16x32_bf16 v[24:27], v[72:75], v[112:115], v[24:27]
	v_mfma_f32_16x16x32_bf16 v[16:19], v[64:67], v[120:123], v[16:19]
	v_mfma_f32_16x16x32_bf16 v[8:11], v[72:75], v[120:123], v[8:11]
	v_mfma_f32_16x16x32_bf16 v[60:63], v[68:71], v[100:103], v[60:63]
	v_mfma_f32_16x16x32_bf16 v[56:59], v[76:79], v[100:103], v[56:59]
	v_mfma_f32_16x16x32_bf16 v[48:51], v[68:71], v[108:111], v[48:51]
	v_mfma_f32_16x16x32_bf16 v[40:43], v[76:79], v[108:111], v[40:43]
	v_mfma_f32_16x16x32_bf16 v[32:35], v[68:71], v[116:119], v[32:35]
	v_mfma_f32_16x16x32_bf16 v[24:27], v[76:79], v[116:119], v[24:27]
	v_mfma_f32_16x16x32_bf16 v[16:19], v[68:71], v[124:127], v[16:19]
	v_mfma_f32_16x16x32_bf16 v[8:11], v[76:79], v[124:127], v[8:11]
	v_mfma_f32_16x16x32_bf16 v[52:55], v[80:83], v[96:99], v[52:55]
	v_mfma_f32_16x16x32_bf16 v[44:47], v[88:91], v[96:99], v[44:47]
	v_mfma_f32_16x16x32_bf16 v[36:39], v[80:83], v[104:107], v[36:39]
	v_mfma_f32_16x16x32_bf16 v[28:31], v[88:91], v[104:107], v[28:31]
	v_mfma_f32_16x16x32_bf16 v[20:23], v[80:83], v[112:115], v[20:23]
	v_mfma_f32_16x16x32_bf16 v[12:15], v[88:91], v[112:115], v[12:15]
	v_mfma_f32_16x16x32_bf16 v[4:7], v[80:83], v[120:123], v[4:7]
	v_mfma_f32_16x16x32_bf16 v[0:3], v[88:91], v[120:123], v[0:3]
	v_mfma_f32_16x16x32_bf16 v[52:55], v[84:87], v[100:103], v[52:55]
	v_mfma_f32_16x16x32_bf16 v[44:47], v[92:95], v[100:103], v[44:47]
	v_mfma_f32_16x16x32_bf16 v[36:39], v[84:87], v[108:111], v[36:39]
	v_mfma_f32_16x16x32_bf16 v[28:31], v[92:95], v[108:111], v[28:31]
	v_mfma_f32_16x16x32_bf16 v[20:23], v[84:87], v[116:119], v[20:23]
	v_mfma_f32_16x16x32_bf16 v[12:15], v[92:95], v[116:119], v[12:15]
	v_mfma_f32_16x16x32_bf16 v[4:7], v[84:87], v[124:127], v[4:7]
	v_mfma_f32_16x16x32_bf16 v[0:3], v[92:95], v[124:127], v[0:3]
	s_barrier
	s_add_i32 s62, s68, s6
	s_mov_b32 m0, s62
	s_nop 0
	s_add_u32 s100, s64, 0x80
	s_addc_u32 s101, s65, 0
	global_load_lds_dwordx4 v172, s[100:101]
	s_add_i32 m0, s62, 0x2000
	s_add_u32 s62, s64, 0xa0080
	s_addc_u32 s63, s65, 0
	s_add_i32 s64, s69, s6
	global_load_lds_dwordx4 v128, vcc
	s_mov_b32 m0, s64
	s_nop 0
	global_load_lds_dwordx4 v172, s[62:63]
	s_add_i32 m0, s64, 0x2000
	s_nop 0
	global_load_lds_dwordx4 v128, s[62:63]
	s_mov_b32 m0, s31
	s_nop 0
	s_add_u32 s100, s66, 0x80
	s_addc_u32 s101, s67, 0
	global_load_lds_dwordx4 v172, s[100:101]
	s_mov_b32 m0, s33
	s_nop 0
	global_load_lds_dwordx4 v128, s[100:101]
	s_waitcnt vmcnt(8) lgkmcnt(0)
	s_barrier
	s_barrier
	s_add_i32 s61, s61, 2
	s_add_u32 s59, s59, 0x100
	s_addc_u32 s60, s60, 0
	s_cmp_gt_u32 s61, 5
	s_mov_b64 s[62:63], s[22:23]
	s_cbranch_scc0 .LBB0_1286
	s_and_b64 vcc, exec, s[28:29]
	s_cbranch_vccz .LBB0_1289
	s_barrier

;     __device__ __forceinline__ void a_ready(const Unit& u) const { wait_panel(cnt, u.pm, need, tmo, wave); }
;     __device__ __forceinline__ void a_ready(const Unit& u) const { wait_panel(cnt, u.pm, need, tmo, wave); }
; #define PG8_STAGE(bufoff, gbase, voff) do { _Pragma("unroll") for (int _i = 0; _i < 2; ++_i) \
;         __builtin_amdgcn_global_load_lds((const unsigned*)((const char*)(gbase) + (voff)[_i]), (PG8_LAS unsigned*)(lds + (bufoff) + ldsw + _i * 8192), 16, 0, 0); } while (0)
; #define PG8_LDA(dst, b, h) do { _Pragma("unroll") for (int m = 0; m < 4; ++m) _Pragma("unroll") for (int k = 0; k < 2; ++k) dst[m][k] = *(const PG8_LAS bf16x8*)(lds + PG8_SA(b, h) + aoff + m * 2048 + k * 1024); } while (0)
; #define PG8_LDB(dst, b, h) do { _Pragma("unroll") for (int n = 0; n < 2; ++n) _Pragma("unroll") for (int k = 0; k < 2; ++k) dst[n][k] = *(const PG8_LAS bf16x8*)(lds + PG8_SB(b, h) + boff + n * 2048 + k * 1024); } while (0)
; #define PG8_WAIT_V(n) asm volatile("s_waitcnt vmcnt(" #n ")" ::: "memory")
; #define PG8_WAIT_L(n) asm volatile("s_waitcnt lgkmcnt(" #n ")" ::: "memory")
; #define PG8_BAR __builtin_amdgcn_s_barrier()
; #define PG8_SCHED __builtin_amdgcn_sched_barrier(0)
; template <class Epi, class Sched, bool ALIGN_EPI = false, bool SP2 = false>
; __device__ __forceinline__ void gemm_phase(PG8_LAS unsigned char* lds, const Gemm g, const Sched& S, const Epi& E, const int tid_in) {
;     ...
;             const bool last = (t == nt - 2);
;             const char* a1 = cA + (size_t)(t + 1) * kstep;
;             const char* a2 = last ? nA : cA + (size_t)(t + 2) * kstep; const char* b2 = last ? nB : cB + (size_t)(t + 2) * kstep;
;             const char* a3 = a2 + kstep; const char* b3 = b2 + kstep;
;             if (last && has_next) S.a_ready(nxt);
;             if constexpr (SP2) {
;             PG8_LDB(B0, 0, 0); PG8_LDB(B1, 0, 1); PG8_SCHED; PG8_LDA(At, 0, 0); PG8_STAGE(PG8_SA(1, 1), a1 + hstepA, voffA);
;             PG8_WAIT_V(8); PG8_WAIT_L(0); PG8_BAR; PG8_MMA(0, 0, At, B0); PG8_MMA(0, 1, At, B1); PG8_BAR; PG8_SCHED;
;             PG8_LDA(At, 0, 1); PG8_STAGE(PG8_SB(0, 0), b2, voffB); PG8_STAGE(PG8_SB(0, 1), b2 + hstepB, voffB); PG8_STAGE(PG8_SA(0, 0), a2, voffA);
;             PG8_WAIT_V(8); PG8_WAIT_L(0); PG8_BAR; PG8_MMA(1, 0, At, B0); PG8_MMA(1, 1, At, B1); PG8_BAR; PG8_SCHED;
.LBB0_1444:
	ds_read_b128 v[140:143], v249
	ds_read_b128 v[148:151], v249 offset:1024
	ds_read_b128 v[152:155], v249 offset:2048
	ds_read_b128 v[156:159], v249 offset:3072
	ds_read_b128 v[160:163], v249 offset:16384
	ds_read_b128 v[164:167], v249 offset:17408
	ds_read_b128 v[168:171], v249 offset:18432
	ds_read_b128 v[190:193], v249 offset:19456
	ds_read_b128 v[194:197], v147
	ds_read_b128 v[198:201], v147 offset:1024
	ds_read_b128 v[202:205], v147 offset:2048
	ds_read_b128 v[206:209], v147 offset:3072
	ds_read_b128 v[210:213], v147 offset:4096
	ds_read_b128 v[224:227], v147 offset:5120
	ds_read_b128 v[228:231], v147 offset:6144
	ds_read_b128 v[232:235], v147 offset:7168
	s_add_u32 s22, s52, 0xfff80080
	s_addc_u32 s23, s53, -1
	s_add_i32 s58, 0, 0x10000
	s_cmp_eq_u32 s57, 28
	s_cselect_b32 s55, s35, s23
	s_cselect_b32 s54, s38, s22
	s_cselect_b32 s23, s43, s56
	s_cselect_b32 s22, s45, s51
	s_add_i32 s60, 0, 0x14000
	s_add_i32 m0, s18, 0xc000
	s_nop 0
	global_load_lds_dwordx4 v134, s[52:53]
	s_add_i32 m0, s18, 0xe000
	s_nop 0
	global_load_lds_dwordx4 v136, s[52:53]
	s_waitcnt vmcnt(8) lgkmcnt(0)
	s_barrier
	v_mfma_f32_16x16x32_bf16 v[124:127], v[140:143], v[194:197], v[124:127]
	v_mfma_f32_16x16x32_bf16 v[120:123], v[152:155], v[194:197], v[120:123]
	v_mfma_f32_16x16x32_bf16 v[112:115], v[140:143], v[202:205], v[112:115]
	v_mfma_f32_16x16x32_bf16 v[104:107], v[152:155], v[202:205], v[104:107]
	v_mfma_f32_16x16x32_bf16 v[96:99], v[140:143], v[210:213], v[96:99]
	v_mfma_f32_16x16x32_bf16 v[88:91], v[152:155], v[210:213], v[88:91]
	v_mfma_f32_16x16x32_bf16 v[80:83], v[140:143], v[228:231], v[80:83]
	v_mfma_f32_16x16x32_bf16 v[72:75], v[152:155], v[228:231], v[72:75]
	v_mfma_f32_16x16x32_bf16 v[124:127], v[148:151], v[198:201], v[124:127]
	v_mfma_f32_16x16x32_bf16 v[120:123], v[156:159], v[198:201], v[120:123]
	v_mfma_f32_16x16x32_bf16 v[112:115], v[148:151], v[206:209], v[112:115]
	v_mfma_f32_16x16x32_bf16 v[104:107], v[156:159], v[206:209], v[104:107]
	v_mfma_f32_16x16x32_bf16 v[96:99], v[148:151], v[224:227], v[96:99]
	v_mfma_f32_16x16x32_bf16 v[88:91], v[156:159], v[224:227], v[88:91]
	v_mfma_f32_16x16x32_bf16 v[80:83], v[148:151], v[232:235], v[80:83]
	v_mfma_f32_16x16x32_bf16 v[72:75], v[156:159], v[232:235], v[72:75]
	v_mfma_f32_16x16x32_bf16 v[116:119], v[160:163], v[194:197], v[116:119]
	v_mfma_f32_16x16x32_bf16 v[108:111], v[168:171], v[194:197], v[108:111]
	v_mfma_f32_16x16x32_bf16 v[100:103], v[160:163], v[202:205], v[100:103]
	v_mfma_f32_16x16x32_bf16 v[92:95], v[168:171], v[202:205], v[92:95]
	v_mfma_f32_16x16x32_bf16 v[84:87], v[160:163], v[210:213], v[84:87]
	v_mfma_f32_16x16x32_bf16 v[76:79], v[168:171], v[210:213], v[76:79]
	v_mfma_f32_16x16x32_bf16 v[68:71], v[160:163], v[228:231], v[68:71]
	v_mfma_f32_16x16x32_bf16 v[64:67], v[168:171], v[228:231], v[64:67]
	v_mfma_f32_16x16x32_bf16 v[116:119], v[164:167], v[198:201], v[116:119]
	v_mfma_f32_16x16x32_bf16 v[108:111], v[190:193], v[198:201], v[108:111]
	v_mfma_f32_16x16x32_bf16 v[100:103], v[164:167], v[206:209], v[100:103]
	v_mfma_f32_16x16x32_bf16 v[92:95], v[190:193], v[206:209], v[92:95]
	v_mfma_f32_16x16x32_bf16 v[84:87], v[164:167], v[224:227], v[84:87]
	v_mfma_f32_16x16x32_bf16 v[76:79], v[190:193], v[224:227], v[76:79]
	v_mfma_f32_16x16x32_bf16 v[68:71], v[164:167], v[232:235], v[68:71]
	v_mfma_f32_16x16x32_bf16 v[64:67], v[190:193], v[232:235], v[64:67]
	s_barrier
	ds_read_b128 v[194:197], v147 offset:16384
	ds_read_b128 v[198:201], v147 offset:17408
	ds_read_b128 v[202:205], v147 offset:18432
	ds_read_b128 v[206:209], v147 offset:19456
	ds_read_b128 v[210:213], v147 offset:20480
	ds_read_b128 v[224:227], v147 offset:21504
	ds_read_b128 v[228:231], v147 offset:22528
	ds_read_b128 v[232:235], v147 offset:23552
	s_add_i32 s58, s58, s17
	s_mov_b32 m0, s58
	s_nop 0
	global_load_lds_dwordx4 v172, s[22:23]
	s_add_i32 m0, s58, 0x2000
	s_add_u32 s58, s22, 0x80000
	s_addc_u32 s59, s23, 0
	s_add_i32 s60, s60, s17
	global_load_lds_dwordx4 v132, s[22:23]
	s_mov_b32 m0, s60
	s_nop 0
	global_load_lds_dwordx4 v172, s[58:59]
	s_add_i32 m0, s60, 0x2000
	s_nop 0
	global_load_lds_dwordx4 v132, s[58:59]
	s_add_u32 vcc_lo, s54, 0x80
	s_addc_u32 vcc_hi, s55, 0
	s_mov_b32 m0, s18
	s_nop 0
	global_load_lds_dwordx4 v128, s[54:55]
	s_mov_b32 m0, s19
	s_nop 0
	global_load_lds_dwordx4 v130, s[54:55]
	s_waitcnt vmcnt(8) lgkmcnt(0)
	s_barrier
	v_mfma_f32_16x16x32_bf16 v[60:63], v[140:143], v[194:197], v[60:63]
	v_mfma_f32_16x16x32_bf16 v[56:59], v[152:155], v[194:197], v[56:59]
	v_mfma_f32_16x16x32_bf16 v[48:51], v[140:143], v[202:205], v[48:51]
	v_mfma_f32_16x16x32_bf16 v[40:43], v[152:155], v[202:205], v[40:43]
	v_mfma_f32_16x16x32_bf16 v[32:35], v[140:143], v[210:213], v[32:35]
	v_mfma_f32_16x16x32_bf16 v[24:27], v[152:155], v[210:213], v[24:27]
	v_mfma_f32_16x16x32_bf16 v[16:19], v[140:143], v[228:231], v[16:19]
	v_mfma_f32_16x16x32_bf16 v[8:11], v[152:155], v[228:231], v[8:11]
	v_mfma_f32_16x16x32_bf16 v[60:63], v[148:151], v[198:201], v[60:63]
	v_mfma_f32_16x16x32_bf16 v[56:59], v[156:159], v[198:201], v[56:59]
	v_mfma_f32_16x16x32_bf16 v[48:51], v[148:151], v[206:209], v[48:51]
	v_mfma_f32_16x16x32_bf16 v[40:43], v[156:159], v[206:209], v[40:43]
	v_mfma_f32_16x16x32_bf16 v[32:35], v[148:151], v[224:227], v[32:35]
	v_mfma_f32_16x16x32_bf16 v[24:27], v[156:159], v[224:227], v[24:27]
	v_mfma_f32_16x16x32_bf16 v[16:19], v[148:151], v[232:235], v[16:19]
	v_mfma_f32_16x16x32_bf16 v[8:11], v[156:159], v[232:235], v[8:11]
	v_mfma_f32_16x16x32_bf16 v[52:55], v[160:163], v[194:197], v[52:55]
	v_mfma_f32_16x16x32_bf16 v[44:47], v[168:171], v[194:197], v[44:47]
	v_mfma_f32_16x16x32_bf16 v[36:39], v[160:163], v[202:205], v[36:39]
	v_mfma_f32_16x16x32_bf16 v[28:31], v[168:171], v[202:205], v[28:31]
	v_mfma_f32_16x16x32_bf16 v[20:23], v[160:163], v[210:213], v[20:23]
	v_mfma_f32_16x16x32_bf16 v[12:15], v[168:171], v[210:213], v[12:15]
	v_mfma_f32_16x16x32_bf16 v[4:7], v[160:163], v[228:231], v[4:7]
	v_mfma_f32_16x16x32_bf16 v[0:3], v[168:171], v[228:231], v[0:3]
	v_mfma_f32_16x16x32_bf16 v[52:55], v[164:167], v[198:201], v[52:55]
	v_mfma_f32_16x16x32_bf16 v[44:47], v[190:193], v[198:201], v[44:47]
	v_mfma_f32_16x16x32_bf16 v[36:39], v[164:167], v[206:209], v[36:39]
	v_mfma_f32_16x16x32_bf16 v[28:31], v[190:193], v[206:209], v[28:31]
	v_mfma_f32_16x16x32_bf16 v[20:23], v[164:167], v[224:227], v[20:23]
	v_mfma_f32_16x16x32_bf16 v[12:15], v[190:193], v[224:227], v[12:15]
	v_mfma_f32_16x16x32_bf16 v[4:7], v[164:167], v[232:235], v[4:7]
	v_mfma_f32_16x16x32_bf16 v[0:3], v[190:193], v[232:235], v[0:3]
	s_barrier
; #define PG8_STAGE(bufoff, gbase, voff) do { _Pragma("unroll") for (int _i = 0; _i < 2; ++_i) \
;         __builtin_amdgcn_global_load_lds((const unsigned*)((const char*)(gbase) + (voff)[_i]), (PG8_LAS unsigned*)(lds + (bufoff) + ldsw + _i * 8192), 16, 0, 0); } while (0)
; #define PG8_LDA(dst, b, h) do { _Pragma("unroll") for (int m = 0; m < 4; ++m) _Pragma("unroll") for (int k = 0; k < 2; ++k) dst[m][k] = *(const PG8_LAS bf16x8*)(lds + PG8_SA(b, h) + aoff + m * 2048 + k * 1024); } while (0)
; #define PG8_LDB(dst, b, h) do { _Pragma("unroll") for (int n = 0; n < 2; ++n) _Pragma("unroll") for (int k = 0; k < 2; ++k) dst[n][k] = *(const PG8_LAS bf16x8*)(lds + PG8_SB(b, h) + boff + n * 2048 + k * 1024); } while (0)
; #define PG8_MMA(ai, bj, At, Bt) do { __builtin_amdgcn_s_setprio(1); _Pragma("unroll") for (int m = 0; m < 4; ++m) _Pragma("unroll") for (int n = 0; n < 2; ++n) _Pragma("unroll") for (int k = 0; k < 2; ++k) \
;         acc[ai][bj][m][n] = __builtin_amdgcn_mfma_f32_16x16x32_bf16(Bt[n][k], At[m][k], acc[ai][bj][m][n], 0, 0, 0); __builtin_amdgcn_s_setprio(0); } while (0)
; #define PG8_WAIT_V(n) asm volatile("s_waitcnt vmcnt(" #n ")" ::: "memory")
; #define PG8_WAIT_L(n) asm volatile("s_waitcnt lgkmcnt(" #n ")" ::: "memory")
; #define PG8_BAR __builtin_amdgcn_s_barrier()
; #define PG8_SCHED __builtin_amdgcn_sched_barrier(0)
; template <class Epi, class Sched, bool ALIGN_EPI = false, bool SP2 = false>
; __device__ __forceinline__ void gemm_phase(PG8_LAS unsigned char* lds, const Gemm g, const Sched& S, const Epi& E, const int tid_in) {
;     ...
;             PG8_LDB(B0, 1, 0); PG8_LDB(B1, 1, 1); PG8_SCHED; PG8_LDA(At, 1, 0); PG8_STAGE(PG8_SA(0, 1), a2 + hstepA, voffA);
;             PG8_WAIT_V(8); PG8_WAIT_L(0); PG8_BAR; PG8_MMA(0, 0, At, B0); PG8_MMA(0, 1, At, B1); PG8_BAR; PG8_SCHED;
;             PG8_LDA(At, 1, 1); PG8_STAGE(PG8_SB(1, 0), b3, voffB); PG8_STAGE(PG8_SB(1, 1), b3 + hstepB, voffB); PG8_STAGE(PG8_SA(1, 0), a3, voffA);
;             PG8_WAIT_V(8); PG8_WAIT_L(0); PG8_BAR; PG8_MMA(1, 0, At, B0); PG8_MMA(1, 1, At, B1); PG8_BAR; PG8_SCHED;
;     ...
;         if constexpr (ALIGN_EPI) { if (wr == 0) PG8_BAR; }
	ds_read_b128 v[140:143], v249 offset:32768
	ds_read_b128 v[148:151], v249 offset:33792
	ds_read_b128 v[152:155], v249 offset:34816
	ds_read_b128 v[156:159], v249 offset:35840
	ds_read_b128 v[160:163], v249 offset:49152
	ds_read_b128 v[164:167], v249 offset:50176
	ds_read_b128 v[168:171], v249 offset:51200
	ds_read_b128 v[190:193], v249 offset:52224
	ds_read_b128 v[194:197], v147 offset:32768
	ds_read_b128 v[198:201], v147 offset:33792
	ds_read_b128 v[202:205], v147 offset:34816
	ds_read_b128 v[206:209], v147 offset:35840
	ds_read_b128 v[210:213], v147 offset:36864
	ds_read_b128 v[224:227], v147 offset:37888
	ds_read_b128 v[228:231], v147 offset:38912
	ds_read_b128 v[232:235], v147 offset:39936
	s_add_i32 s58, 0, 0x18000
	s_add_i32 s59, 0, 0x1c000
	s_add_u32 s54, s54, 0x80000
	s_addc_u32 s55, s55, 0
	s_mov_b32 m0, s20
	s_nop 0
	global_load_lds_dwordx4 v128, s[54:55]
	s_mov_b32 m0, s21
	s_nop 0
	global_load_lds_dwordx4 v130, s[54:55]
	s_waitcnt vmcnt(8) lgkmcnt(0)
	s_barrier
	v_mfma_f32_16x16x32_bf16 v[124:127], v[140:143], v[194:197], v[124:127]
	v_mfma_f32_16x16x32_bf16 v[120:123], v[152:155], v[194:197], v[120:123]
	v_mfma_f32_16x16x32_bf16 v[112:115], v[140:143], v[202:205], v[112:115]
	v_mfma_f32_16x16x32_bf16 v[104:107], v[152:155], v[202:205], v[104:107]
	v_mfma_f32_16x16x32_bf16 v[96:99], v[140:143], v[210:213], v[96:99]
	v_mfma_f32_16x16x32_bf16 v[88:91], v[152:155], v[210:213], v[88:91]
	v_mfma_f32_16x16x32_bf16 v[80:83], v[140:143], v[228:231], v[80:83]
	v_mfma_f32_16x16x32_bf16 v[72:75], v[152:155], v[228:231], v[72:75]
	v_mfma_f32_16x16x32_bf16 v[124:127], v[148:151], v[198:201], v[124:127]
	v_mfma_f32_16x16x32_bf16 v[120:123], v[156:159], v[198:201], v[120:123]
	v_mfma_f32_16x16x32_bf16 v[112:115], v[148:151], v[206:209], v[112:115]
	v_mfma_f32_16x16x32_bf16 v[104:107], v[156:159], v[206:209], v[104:107]
	v_mfma_f32_16x16x32_bf16 v[96:99], v[148:151], v[224:227], v[96:99]
	v_mfma_f32_16x16x32_bf16 v[88:91], v[156:159], v[224:227], v[88:91]
	v_mfma_f32_16x16x32_bf16 v[80:83], v[148:151], v[232:235], v[80:83]
	v_mfma_f32_16x16x32_bf16 v[72:75], v[156:159], v[232:235], v[72:75]
	v_mfma_f32_16x16x32_bf16 v[116:119], v[160:163], v[194:197], v[116:119]
	v_mfma_f32_16x16x32_bf16 v[108:111], v[168:171], v[194:197], v[108:111]
	v_mfma_f32_16x16x32_bf16 v[100:103], v[160:163], v[202:205], v[100:103]
	v_mfma_f32_16x16x32_bf16 v[92:95], v[168:171], v[202:205], v[92:95]
	v_mfma_f32_16x16x32_bf16 v[84:87], v[160:163], v[210:213], v[84:87]
	v_mfma_f32_16x16x32_bf16 v[76:79], v[168:171], v[210:213], v[76:79]
	v_mfma_f32_16x16x32_bf16 v[68:71], v[160:163], v[228:231], v[68:71]
	v_mfma_f32_16x16x32_bf16 v[64:67], v[168:171], v[228:231], v[64:67]
	v_mfma_f32_16x16x32_bf16 v[116:119], v[164:167], v[198:201], v[116:119]
	v_mfma_f32_16x16x32_bf16 v[108:111], v[190:193], v[198:201], v[108:111]
	v_mfma_f32_16x16x32_bf16 v[100:103], v[164:167], v[206:209], v[100:103]
	v_mfma_f32_16x16x32_bf16 v[92:95], v[190:193], v[206:209], v[92:95]
	v_mfma_f32_16x16x32_bf16 v[84:87], v[164:167], v[224:227], v[84:87]
	v_mfma_f32_16x16x32_bf16 v[76:79], v[190:193], v[224:227], v[76:79]
	v_mfma_f32_16x16x32_bf16 v[68:71], v[164:167], v[232:235], v[68:71]
	v_mfma_f32_16x16x32_bf16 v[64:67], v[190:193], v[232:235], v[64:67]
	s_barrier
	ds_read_b128 v[194:197], v147 offset:49152
	ds_read_b128 v[198:201], v147 offset:50176
	ds_read_b128 v[202:205], v147 offset:51200
	ds_read_b128 v[206:209], v147 offset:52224
	ds_read_b128 v[210:213], v147 offset:53248
	ds_read_b128 v[224:227], v147 offset:54272
	ds_read_b128 v[228:231], v147 offset:55296
	ds_read_b128 v[232:235], v147 offset:56320
	s_add_i32 s54, s58, s17
	s_mov_b32 m0, s54
	s_add_u32 s100, s22, 0x80
	s_addc_u32 s101, s23, 0
	global_load_lds_dwordx4 v172, s[100:101]
	s_add_i32 m0, s54, 0x2000
	s_add_u32 s22, s22, 0x80080
	s_addc_u32 s23, s23, 0
	s_add_i32 s54, s59, s17
	global_load_lds_dwordx4 v132, s[100:101]
	s_mov_b32 m0, s54
	s_nop 0
	global_load_lds_dwordx4 v172, s[22:23]
	s_add_i32 m0, s54, 0x2000
	s_nop 0
	global_load_lds_dwordx4 v132, s[22:23]
	s_mov_b32 m0, s29
	s_nop 0
	global_load_lds_dwordx4 v128, vcc
	s_mov_b32 m0, s30
	s_nop 0
	global_load_lds_dwordx4 v130, vcc
	s_waitcnt vmcnt(8) lgkmcnt(0)
	s_barrier
	v_mfma_f32_16x16x32_bf16 v[60:63], v[140:143], v[194:197], v[60:63]
	v_mfma_f32_16x16x32_bf16 v[56:59], v[152:155], v[194:197], v[56:59]
	v_mfma_f32_16x16x32_bf16 v[48:51], v[140:143], v[202:205], v[48:51]
	v_mfma_f32_16x16x32_bf16 v[40:43], v[152:155], v[202:205], v[40:43]
	v_mfma_f32_16x16x32_bf16 v[32:35], v[140:143], v[210:213], v[32:35]
	v_mfma_f32_16x16x32_bf16 v[24:27], v[152:155], v[210:213], v[24:27]
	v_mfma_f32_16x16x32_bf16 v[16:19], v[140:143], v[228:231], v[16:19]
	v_mfma_f32_16x16x32_bf16 v[8:11], v[152:155], v[228:231], v[8:11]
	v_mfma_f32_16x16x32_bf16 v[60:63], v[148:151], v[198:201], v[60:63]
	v_mfma_f32_16x16x32_bf16 v[56:59], v[156:159], v[198:201], v[56:59]
	v_mfma_f32_16x16x32_bf16 v[48:51], v[148:151], v[206:209], v[48:51]
	v_mfma_f32_16x16x32_bf16 v[40:43], v[156:159], v[206:209], v[40:43]
	v_mfma_f32_16x16x32_bf16 v[32:35], v[148:151], v[224:227], v[32:35]
	v_mfma_f32_16x16x32_bf16 v[24:27], v[156:159], v[224:227], v[24:27]
	v_mfma_f32_16x16x32_bf16 v[16:19], v[148:151], v[232:235], v[16:19]
	v_mfma_f32_16x16x32_bf16 v[8:11], v[156:159], v[232:235], v[8:11]
	v_mfma_f32_16x16x32_bf16 v[52:55], v[160:163], v[194:197], v[52:55]
	v_mfma_f32_16x16x32_bf16 v[44:47], v[168:171], v[194:197], v[44:47]
	v_mfma_f32_16x16x32_bf16 v[36:39], v[160:163], v[202:205], v[36:39]
	v_mfma_f32_16x16x32_bf16 v[28:31], v[168:171], v[202:205], v[28:31]
	v_mfma_f32_16x16x32_bf16 v[20:23], v[160:163], v[210:213], v[20:23]
	v_mfma_f32_16x16x32_bf16 v[12:15], v[168:171], v[210:213], v[12:15]
	v_mfma_f32_16x16x32_bf16 v[4:7], v[160:163], v[228:231], v[4:7]
	v_mfma_f32_16x16x32_bf16 v[0:3], v[168:171], v[228:231], v[0:3]
	v_mfma_f32_16x16x32_bf16 v[52:55], v[164:167], v[198:201], v[52:55]
	v_mfma_f32_16x16x32_bf16 v[44:47], v[190:193], v[198:201], v[44:47]
	v_mfma_f32_16x16x32_bf16 v[36:39], v[164:167], v[206:209], v[36:39]
	v_mfma_f32_16x16x32_bf16 v[28:31], v[190:193], v[206:209], v[28:31]
	v_mfma_f32_16x16x32_bf16 v[20:23], v[164:167], v[224:227], v[20:23]
	v_mfma_f32_16x16x32_bf16 v[12:15], v[190:193], v[224:227], v[12:15]
	v_mfma_f32_16x16x32_bf16 v[4:7], v[164:167], v[232:235], v[4:7]
	v_mfma_f32_16x16x32_bf16 v[0:3], v[190:193], v[232:235], v[0:3]
	s_barrier
	s_add_i32 s57, s57, 2
	s_add_u32 s52, s52, 0x100
	s_addc_u32 s53, s53, 0
	s_add_u32 s51, s51, 0x100
	s_addc_u32 s56, s56, 0
	s_cmp_gt_u32 s57, 29
	s_cbranch_scc0 .LBB0_1444
	s_and_b64 vcc, exec, s[36:37]
	s_cbranch_vccz .LBB0_1447
	s_barrier

;     __device__ __forceinline__ void a_ready(const Unit& u) const { wait_panel(cnt, u.pm, need, tmo, wave); }
;     __device__ __forceinline__ void a_ready(const Unit& u) const { wait_panel(cnt, u.pm, need, tmo, wave); }
; #define PG8_STAGE(bufoff, gbase, voff) do { _Pragma("unroll") for (int _i = 0; _i < 2; ++_i) \
;         __builtin_amdgcn_global_load_lds((const unsigned*)((const char*)(gbase) + (voff)[_i]), (PG8_LAS unsigned*)(lds + (bufoff) + ldsw + _i * 8192), 16, 0, 0); } while (0)
; #define PG8_LDA(dst, b, h) do { _Pragma("unroll") for (int m = 0; m < 4; ++m) _Pragma("unroll") for (int k = 0; k < 2; ++k) dst[m][k] = *(const PG8_LAS bf16x8*)(lds + PG8_SA(b, h) + aoff + m * 2048 + k * 1024); } while (0)
; #define PG8_LDB(dst, b, h) do { _Pragma("unroll") for (int n = 0; n < 2; ++n) _Pragma("unroll") for (int k = 0; k < 2; ++k) dst[n][k] = *(const PG8_LAS bf16x8*)(lds + PG8_SB(b, h) + boff + n * 2048 + k * 1024); } while (0)
; #define PG8_WAIT_V(n) asm volatile("s_waitcnt vmcnt(" #n ")" ::: "memory")
; #define PG8_WAIT_L(n) asm volatile("s_waitcnt lgkmcnt(" #n ")" ::: "memory")
; #define PG8_BAR __builtin_amdgcn_s_barrier()
; #define PG8_SCHED __builtin_amdgcn_sched_barrier(0)
; template <class Epi, class Sched, bool ALIGN_EPI = false, bool SP2 = false>
; __device__ __forceinline__ void gemm_phase(PG8_LAS unsigned char* lds, const Gemm g, const Sched& S, const Epi& E, const int tid_in) {
;     ...
;             const bool last = (t == nt - 2);
;             const char* a1 = cA + (size_t)(t + 1) * kstep;
;             const char* a2 = last ? nA : cA + (size_t)(t + 2) * kstep; const char* b2 = last ? nB : cB + (size_t)(t + 2) * kstep;
;             const char* a3 = a2 + kstep; const char* b3 = b2 + kstep;
;             if (last && has_next) S.a_ready(nxt);
;             if constexpr (SP2) {
;             PG8_LDB(B0, 0, 0); PG8_LDB(B1, 0, 1); PG8_SCHED; PG8_LDA(At, 0, 0); PG8_STAGE(PG8_SA(1, 1), a1 + hstepA, voffA);
;             PG8_WAIT_V(8); PG8_WAIT_L(0); PG8_BAR; PG8_MMA(0, 0, At, B0); PG8_MMA(0, 1, At, B1); PG8_BAR; PG8_SCHED;
;             PG8_LDA(At, 0, 1); PG8_STAGE(PG8_SB(0, 0), b2, voffB); PG8_STAGE(PG8_SB(0, 1), b2 + hstepB, voffB); PG8_STAGE(PG8_SA(0, 0), a2, voffA);
;             PG8_WAIT_V(8); PG8_WAIT_L(0); PG8_BAR; PG8_MMA(1, 0, At, B0); PG8_MMA(1, 1, At, B1); PG8_BAR; PG8_SCHED;
.LBB0_1960:
	ds_read_b128 v[32:35], v249
	ds_read_b128 v[36:39], v249 offset:1024
	ds_read_b128 v[48:51], v249 offset:2048
	ds_read_b128 v[52:55], v249 offset:3072
	ds_read_b128 v[104:107], v249 offset:16384
	ds_read_b128 v[116:119], v249 offset:17408
	ds_read_b128 v[128:131], v249 offset:18432
	ds_read_b128 v[140:143], v249 offset:19456
	ds_read_b128 v[144:147], v225
	ds_read_b128 v[156:159], v225 offset:1024
	ds_read_b128 v[160:163], v225 offset:2048
	ds_read_b128 v[200:203], v225 offset:3072
	ds_read_b128 v[204:207], v225 offset:4096
	ds_read_b128 v[208:211], v225 offset:5120
	ds_read_b128 v[226:229], v225 offset:6144
	ds_read_b128 v[230:233], v225 offset:7168
	s_add_u32 s22, s58, 0xfffc0080
	s_addc_u32 s23, s59, -1
	s_add_i32 s62, 0, 0x10000
	s_cmp_eq_u32 s53, 12
	s_cselect_b32 s61, s11, s23
	s_cselect_b32 s60, s12, s22
	s_cselect_b32 s23, s33, s51
	s_cselect_b32 s22, s34, s35
	s_add_i32 s64, 0, 0x14000
	s_add_i32 m0, s17, 0xc000
	s_nop 0
	global_load_lds_dwordx4 v196, s[58:59]
	s_add_i32 m0, s17, 0xe000
	s_nop 0
	global_load_lds_dwordx4 v198, s[58:59]
	s_waitcnt vmcnt(8) lgkmcnt(0)
	s_barrier
	v_mfma_f32_16x16x32_bf16 v[168:171], v[32:35], v[144:147], v[168:171]
	v_mfma_f32_16x16x32_bf16 v[164:167], v[48:51], v[144:147], v[164:167]
	v_mfma_f32_16x16x32_bf16 v[136:139], v[32:35], v[160:163], v[136:139]
	v_mfma_f32_16x16x32_bf16 v[132:135], v[48:51], v[160:163], v[132:135]
	v_mfma_f32_16x16x32_bf16 v[112:115], v[32:35], v[204:207], v[112:115]
	v_mfma_f32_16x16x32_bf16 v[108:111], v[48:51], v[204:207], v[108:111]
	v_mfma_f32_16x16x32_bf16 v[92:95], v[32:35], v[226:229], v[92:95]
	v_mfma_f32_16x16x32_bf16 v[88:91], v[48:51], v[226:229], v[88:91]
	v_mfma_f32_16x16x32_bf16 v[168:171], v[36:39], v[156:159], v[168:171]
	v_mfma_f32_16x16x32_bf16 v[164:167], v[52:55], v[156:159], v[164:167]
	v_mfma_f32_16x16x32_bf16 v[136:139], v[36:39], v[200:203], v[136:139]
	v_mfma_f32_16x16x32_bf16 v[132:135], v[52:55], v[200:203], v[132:135]
	v_mfma_f32_16x16x32_bf16 v[112:115], v[36:39], v[208:211], v[112:115]
	v_mfma_f32_16x16x32_bf16 v[108:111], v[52:55], v[208:211], v[108:111]
	v_mfma_f32_16x16x32_bf16 v[92:95], v[36:39], v[230:233], v[92:95]
	v_mfma_f32_16x16x32_bf16 v[88:91], v[52:55], v[230:233], v[88:91]
	v_mfma_f32_16x16x32_bf16 v[152:155], v[104:107], v[144:147], v[152:155]
	v_mfma_f32_16x16x32_bf16 v[124:127], v[104:107], v[160:163], v[124:127]
	v_mfma_f32_16x16x32_bf16 v[120:123], v[128:131], v[160:163], v[120:123]
	v_mfma_f32_16x16x32_bf16 v[100:103], v[104:107], v[204:207], v[100:103]
	v_mfma_f32_16x16x32_bf16 v[96:99], v[128:131], v[204:207], v[96:99]
	v_mfma_f32_16x16x32_bf16 v[84:87], v[104:107], v[226:229], v[84:87]
	v_mfma_f32_16x16x32_bf16 v[80:83], v[128:131], v[226:229], v[80:83]
	v_mfma_f32_16x16x32_bf16 v[152:155], v[116:119], v[156:159], v[152:155]
	v_mfma_f32_16x16x32_bf16 v[144:147], v[128:131], v[144:147], v[148:151]
	v_mfma_f32_16x16x32_bf16 v[124:127], v[116:119], v[200:203], v[124:127]
	v_mfma_f32_16x16x32_bf16 v[120:123], v[140:143], v[200:203], v[120:123]
	v_mfma_f32_16x16x32_bf16 v[100:103], v[116:119], v[208:211], v[100:103]
	v_mfma_f32_16x16x32_bf16 v[96:99], v[140:143], v[208:211], v[96:99]
	v_mfma_f32_16x16x32_bf16 v[84:87], v[116:119], v[230:233], v[84:87]
	v_mfma_f32_16x16x32_bf16 v[80:83], v[140:143], v[230:233], v[80:83]
	v_mfma_f32_16x16x32_bf16 v[144:147], v[140:143], v[156:159], v[144:147]
	s_barrier
	ds_read_b128 v[148:151], v225 offset:16384
	ds_read_b128 v[156:159], v225 offset:17408
	ds_read_b128 v[160:163], v225 offset:18432
	ds_read_b128 v[200:203], v225 offset:19456
	ds_read_b128 v[204:207], v225 offset:20480
	ds_read_b128 v[208:211], v225 offset:21504
	ds_read_b128 v[226:229], v225 offset:22528
	ds_read_b128 v[230:233], v225 offset:23552
	s_add_i32 s62, s62, s16
	s_mov_b32 m0, s62
	s_nop 0
	global_load_lds_dwordx4 v172, s[22:23]
	s_add_i32 m0, s62, 0x2000
	s_add_u32 s62, s22, 0x40000
	s_addc_u32 s63, s23, 0
	s_add_i32 s64, s64, s16
	global_load_lds_dwordx4 v194, s[22:23]
	s_mov_b32 m0, s64
	s_nop 0
	global_load_lds_dwordx4 v172, s[62:63]
	s_add_i32 m0, s64, 0x2000
	s_nop 0
	global_load_lds_dwordx4 v194, s[62:63]
	s_add_u32 vcc_lo, s60, 0x80
	s_addc_u32 vcc_hi, s61, 0
	s_mov_b32 m0, s17
	s_nop 0
	global_load_lds_dwordx4 v190, s[60:61]
	s_mov_b32 m0, s18
	s_nop 0
	global_load_lds_dwordx4 v192, s[60:61]
	s_waitcnt vmcnt(8) lgkmcnt(0)
	s_barrier
	v_mfma_f32_16x16x32_bf16 v[76:79], v[32:35], v[148:151], v[76:79]
	v_mfma_f32_16x16x32_bf16 v[72:75], v[48:51], v[148:151], v[72:75]
	v_mfma_f32_16x16x32_bf16 v[60:63], v[32:35], v[160:163], v[60:63]
	v_mfma_f32_16x16x32_bf16 v[56:59], v[48:51], v[160:163], v[56:59]
	v_mfma_f32_16x16x32_bf16 v[28:31], v[32:35], v[204:207], v[28:31]
	v_mfma_f32_16x16x32_bf16 v[24:27], v[48:51], v[204:207], v[24:27]
	v_mfma_f32_16x16x32_bf16 v[12:15], v[32:35], v[226:229], v[12:15]
	v_mfma_f32_16x16x32_bf16 v[8:11], v[48:51], v[226:229], v[8:11]
	v_mfma_f32_16x16x32_bf16 v[76:79], v[36:39], v[156:159], v[76:79]
	v_mfma_f32_16x16x32_bf16 v[72:75], v[52:55], v[156:159], v[72:75]
	v_mfma_f32_16x16x32_bf16 v[60:63], v[36:39], v[200:203], v[60:63]
	v_mfma_f32_16x16x32_bf16 v[56:59], v[52:55], v[200:203], v[56:59]
	v_mfma_f32_16x16x32_bf16 v[28:31], v[36:39], v[208:211], v[28:31]
	v_mfma_f32_16x16x32_bf16 v[24:27], v[52:55], v[208:211], v[24:27]
	v_mfma_f32_16x16x32_bf16 v[12:15], v[36:39], v[230:233], v[12:15]
	v_mfma_f32_16x16x32_bf16 v[8:11], v[52:55], v[230:233], v[8:11]
	v_mfma_f32_16x16x32_bf16 v[44:47], v[104:107], v[160:163], v[44:47]
	v_mfma_f32_16x16x32_bf16 v[40:43], v[128:131], v[160:163], v[40:43]
	v_mfma_f32_16x16x32_bf16 v[20:23], v[104:107], v[204:207], v[20:23]
	v_mfma_f32_16x16x32_bf16 v[16:19], v[128:131], v[204:207], v[16:19]
	v_mfma_f32_16x16x32_bf16 v[4:7], v[104:107], v[226:229], v[4:7]
	v_mfma_f32_16x16x32_bf16 v[0:3], v[128:131], v[226:229], v[0:3]
	v_mfma_f32_16x16x32_bf16 v[32:35], v[104:107], v[148:151], v[68:71]
	v_mfma_f32_16x16x32_bf16 v[36:39], v[128:131], v[148:151], v[64:67]
	v_mfma_f32_16x16x32_bf16 v[44:47], v[116:119], v[200:203], v[44:47]
	v_mfma_f32_16x16x32_bf16 v[40:43], v[140:143], v[200:203], v[40:43]
	v_mfma_f32_16x16x32_bf16 v[20:23], v[116:119], v[208:211], v[20:23]
	v_mfma_f32_16x16x32_bf16 v[16:19], v[140:143], v[208:211], v[16:19]
	v_mfma_f32_16x16x32_bf16 v[4:7], v[116:119], v[230:233], v[4:7]
	v_mfma_f32_16x16x32_bf16 v[0:3], v[140:143], v[230:233], v[0:3]
	v_mfma_f32_16x16x32_bf16 v[32:35], v[116:119], v[156:159], v[32:35]
	v_mfma_f32_16x16x32_bf16 v[36:39], v[140:143], v[156:159], v[36:39]
	s_barrier
; #define PG8_STAGE(bufoff, gbase, voff) do { _Pragma("unroll") for (int _i = 0; _i < 2; ++_i) \
;         __builtin_amdgcn_global_load_lds((const unsigned*)((const char*)(gbase) + (voff)[_i]), (PG8_LAS unsigned*)(lds + (bufoff) + ldsw + _i * 8192), 16, 0, 0); } while (0)
; #define PG8_LDA(dst, b, h) do { _Pragma("unroll") for (int m = 0; m < 4; ++m) _Pragma("unroll") for (int k = 0; k < 2; ++k) dst[m][k] = *(const PG8_LAS bf16x8*)(lds + PG8_SA(b, h) + aoff + m * 2048 + k * 1024); } while (0)
; #define PG8_LDB(dst, b, h) do { _Pragma("unroll") for (int n = 0; n < 2; ++n) _Pragma("unroll") for (int k = 0; k < 2; ++k) dst[n][k] = *(const PG8_LAS bf16x8*)(lds + PG8_SB(b, h) + boff + n * 2048 + k * 1024); } while (0)
; #define PG8_MMA(ai, bj, At, Bt) do { __builtin_amdgcn_s_setprio(1); _Pragma("unroll") for (int m = 0; m < 4; ++m) _Pragma("unroll") for (int n = 0; n < 2; ++n) _Pragma("unroll") for (int k = 0; k < 2; ++k) \
;         acc[ai][bj][m][n] = __builtin_amdgcn_mfma_f32_16x16x32_bf16(Bt[n][k], At[m][k], acc[ai][bj][m][n], 0, 0, 0); __builtin_amdgcn_s_setprio(0); } while (0)
; #define PG8_WAIT_V(n) asm volatile("s_waitcnt vmcnt(" #n ")" ::: "memory")
; #define PG8_WAIT_L(n) asm volatile("s_waitcnt lgkmcnt(" #n ")" ::: "memory")
; #define PG8_BAR __builtin_amdgcn_s_barrier()
; #define PG8_SCHED __builtin_amdgcn_sched_barrier(0)
; template <class Epi, class Sched, bool ALIGN_EPI = false, bool SP2 = false>
; __device__ __forceinline__ void gemm_phase(PG8_LAS unsigned char* lds, const Gemm g, const Sched& S, const Epi& E, const int tid_in) {
;     ...
;             PG8_LDB(B0, 1, 0); PG8_LDB(B1, 1, 1); PG8_SCHED; PG8_LDA(At, 1, 0); PG8_STAGE(PG8_SA(0, 1), a2 + hstepA, voffA);
;             PG8_WAIT_V(8); PG8_WAIT_L(0); PG8_BAR; PG8_MMA(0, 0, At, B0); PG8_MMA(0, 1, At, B1); PG8_BAR; PG8_SCHED;
;             PG8_LDA(At, 1, 1); PG8_STAGE(PG8_SB(1, 0), b3, voffB); PG8_STAGE(PG8_SB(1, 1), b3 + hstepB, voffB); PG8_STAGE(PG8_SA(1, 0), a3, voffA);
;             PG8_WAIT_V(8); PG8_WAIT_L(0); PG8_BAR; PG8_MMA(1, 0, At, B0); PG8_MMA(1, 1, At, B1); PG8_BAR; PG8_SCHED;
;     ...
;         if constexpr (ALIGN_EPI) { if (wr == 0) PG8_BAR; }
	ds_read_b128 v[48:51], v249 offset:32768
	ds_read_b128 v[52:55], v249 offset:33792
	ds_read_b128 v[64:67], v249 offset:34816
	ds_read_b128 v[68:71], v249 offset:35840
	ds_read_b128 v[104:107], v249 offset:49152
	ds_read_b128 v[116:119], v249 offset:50176
	ds_read_b128 v[128:131], v249 offset:51200
	ds_read_b128 v[140:143], v249 offset:52224
	ds_read_b128 v[148:151], v225 offset:32768
	ds_read_b128 v[156:159], v225 offset:33792
	ds_read_b128 v[160:163], v225 offset:34816
	ds_read_b128 v[200:203], v225 offset:35840
	ds_read_b128 v[204:207], v225 offset:36864
	ds_read_b128 v[208:211], v225 offset:37888
	ds_read_b128 v[226:229], v225 offset:38912
	ds_read_b128 v[230:233], v225 offset:39936
	s_add_i32 s62, 0, 0x18000
	s_add_i32 s63, 0, 0x1c000
	s_add_u32 s60, s60, 0x40000
	s_addc_u32 s61, s61, 0
	s_mov_b32 m0, s19
	s_nop 0
	global_load_lds_dwordx4 v190, s[60:61]
	s_mov_b32 m0, s20
	s_nop 0
	global_load_lds_dwordx4 v192, s[60:61]
	s_waitcnt vmcnt(8) lgkmcnt(0)
	s_barrier
	v_mfma_f32_16x16x32_bf16 v[168:171], v[48:51], v[148:151], v[168:171]
	v_mfma_f32_16x16x32_bf16 v[164:167], v[64:67], v[148:151], v[164:167]
	v_mfma_f32_16x16x32_bf16 v[136:139], v[48:51], v[160:163], v[136:139]
	v_mfma_f32_16x16x32_bf16 v[132:135], v[64:67], v[160:163], v[132:135]
	v_mfma_f32_16x16x32_bf16 v[112:115], v[48:51], v[204:207], v[112:115]
	v_mfma_f32_16x16x32_bf16 v[108:111], v[64:67], v[204:207], v[108:111]
	v_mfma_f32_16x16x32_bf16 v[92:95], v[48:51], v[226:229], v[92:95]
	v_mfma_f32_16x16x32_bf16 v[88:91], v[64:67], v[226:229], v[88:91]
	v_mfma_f32_16x16x32_bf16 v[168:171], v[52:55], v[156:159], v[168:171]
	v_mfma_f32_16x16x32_bf16 v[164:167], v[68:71], v[156:159], v[164:167]
	v_mfma_f32_16x16x32_bf16 v[136:139], v[52:55], v[200:203], v[136:139]
	v_mfma_f32_16x16x32_bf16 v[132:135], v[68:71], v[200:203], v[132:135]
	v_mfma_f32_16x16x32_bf16 v[112:115], v[52:55], v[208:211], v[112:115]
	v_mfma_f32_16x16x32_bf16 v[108:111], v[68:71], v[208:211], v[108:111]
	v_mfma_f32_16x16x32_bf16 v[92:95], v[52:55], v[230:233], v[92:95]
	v_mfma_f32_16x16x32_bf16 v[88:91], v[68:71], v[230:233], v[88:91]
	v_mfma_f32_16x16x32_bf16 v[152:155], v[104:107], v[148:151], v[152:155]
	v_mfma_f32_16x16x32_bf16 v[144:147], v[128:131], v[148:151], v[144:147]
	v_mfma_f32_16x16x32_bf16 v[124:127], v[104:107], v[160:163], v[124:127]
	v_mfma_f32_16x16x32_bf16 v[120:123], v[128:131], v[160:163], v[120:123]
	v_mfma_f32_16x16x32_bf16 v[100:103], v[104:107], v[204:207], v[100:103]
	v_mfma_f32_16x16x32_bf16 v[96:99], v[128:131], v[204:207], v[96:99]
	v_mfma_f32_16x16x32_bf16 v[84:87], v[104:107], v[226:229], v[84:87]
	v_mfma_f32_16x16x32_bf16 v[80:83], v[128:131], v[226:229], v[80:83]
	v_mfma_f32_16x16x32_bf16 v[152:155], v[116:119], v[156:159], v[152:155]
	v_mfma_f32_16x16x32_bf16 v[148:151], v[140:143], v[156:159], v[144:147]
	v_mfma_f32_16x16x32_bf16 v[124:127], v[116:119], v[200:203], v[124:127]
	v_mfma_f32_16x16x32_bf16 v[120:123], v[140:143], v[200:203], v[120:123]
	v_mfma_f32_16x16x32_bf16 v[100:103], v[116:119], v[208:211], v[100:103]
	v_mfma_f32_16x16x32_bf16 v[96:99], v[140:143], v[208:211], v[96:99]
	v_mfma_f32_16x16x32_bf16 v[84:87], v[116:119], v[230:233], v[84:87]
	v_mfma_f32_16x16x32_bf16 v[80:83], v[140:143], v[230:233], v[80:83]
	s_barrier
	ds_read_b128 v[144:147], v225 offset:49152
	ds_read_b128 v[156:159], v225 offset:50176
	ds_read_b128 v[160:163], v225 offset:51200
	ds_read_b128 v[200:203], v225 offset:52224
	ds_read_b128 v[204:207], v225 offset:53248
	ds_read_b128 v[208:211], v225 offset:54272
	ds_read_b128 v[226:229], v225 offset:55296
	ds_read_b128 v[230:233], v225 offset:56320
	s_add_i32 s60, s62, s16
	s_mov_b32 m0, s60
	s_add_u32 s100, s22, 0x80
	s_addc_u32 s101, s23, 0
	global_load_lds_dwordx4 v172, s[100:101]
	s_add_i32 m0, s60, 0x2000
	s_add_u32 s22, s22, 0x40080
	s_addc_u32 s23, s23, 0
	s_add_i32 s60, s63, s16
	global_load_lds_dwordx4 v194, s[100:101]
	s_mov_b32 m0, s60
	s_nop 0
	global_load_lds_dwordx4 v172, s[22:23]
	s_add_i32 m0, s60, 0x2000
	s_nop 0
	global_load_lds_dwordx4 v194, s[22:23]
	s_mov_b32 m0, s30
	s_nop 0
	global_load_lds_dwordx4 v190, vcc
	s_mov_b32 m0, s31
	s_nop 0
	global_load_lds_dwordx4 v192, vcc
	s_waitcnt vmcnt(8) lgkmcnt(0)
	s_barrier
	v_mfma_f32_16x16x32_bf16 v[76:79], v[48:51], v[144:147], v[76:79]
	v_mfma_f32_16x16x32_bf16 v[72:75], v[64:67], v[144:147], v[72:75]
	v_mfma_f32_16x16x32_bf16 v[60:63], v[48:51], v[160:163], v[60:63]
	v_mfma_f32_16x16x32_bf16 v[56:59], v[64:67], v[160:163], v[56:59]
	v_mfma_f32_16x16x32_bf16 v[28:31], v[48:51], v[204:207], v[28:31]
	v_mfma_f32_16x16x32_bf16 v[24:27], v[64:67], v[204:207], v[24:27]
	v_mfma_f32_16x16x32_bf16 v[12:15], v[48:51], v[226:229], v[12:15]
	v_mfma_f32_16x16x32_bf16 v[8:11], v[64:67], v[226:229], v[8:11]
	v_mfma_f32_16x16x32_bf16 v[76:79], v[52:55], v[156:159], v[76:79]
	v_mfma_f32_16x16x32_bf16 v[72:75], v[68:71], v[156:159], v[72:75]
	v_mfma_f32_16x16x32_bf16 v[60:63], v[52:55], v[200:203], v[60:63]
	v_mfma_f32_16x16x32_bf16 v[56:59], v[68:71], v[200:203], v[56:59]
	v_mfma_f32_16x16x32_bf16 v[28:31], v[52:55], v[208:211], v[28:31]
	v_mfma_f32_16x16x32_bf16 v[24:27], v[68:71], v[208:211], v[24:27]
	v_mfma_f32_16x16x32_bf16 v[12:15], v[52:55], v[230:233], v[12:15]
	v_mfma_f32_16x16x32_bf16 v[8:11], v[68:71], v[230:233], v[8:11]
	v_mfma_f32_16x16x32_bf16 v[32:35], v[104:107], v[144:147], v[32:35]
	v_mfma_f32_16x16x32_bf16 v[68:71], v[116:119], v[156:159], v[32:35]
	v_mfma_f32_16x16x32_bf16 v[32:35], v[128:131], v[144:147], v[36:39]
	v_mfma_f32_16x16x32_bf16 v[64:67], v[140:143], v[156:159], v[32:35]
	v_mfma_f32_16x16x32_bf16 v[32:35], v[104:107], v[160:163], v[44:47]
	v_mfma_f32_16x16x32_bf16 v[44:47], v[116:119], v[200:203], v[32:35]
	v_mfma_f32_16x16x32_bf16 v[32:35], v[128:131], v[160:163], v[40:43]
	v_mfma_f32_16x16x32_bf16 v[20:23], v[104:107], v[204:207], v[20:23]
	v_mfma_f32_16x16x32_bf16 v[16:19], v[128:131], v[204:207], v[16:19]
	v_mfma_f32_16x16x32_bf16 v[4:7], v[104:107], v[226:229], v[4:7]
	v_mfma_f32_16x16x32_bf16 v[0:3], v[128:131], v[226:229], v[0:3]
	v_mfma_f32_16x16x32_bf16 v[40:43], v[140:143], v[200:203], v[32:35]
	v_mfma_f32_16x16x32_bf16 v[20:23], v[116:119], v[208:211], v[20:23]
	v_mfma_f32_16x16x32_bf16 v[16:19], v[140:143], v[208:211], v[16:19]
	v_mfma_f32_16x16x32_bf16 v[4:7], v[116:119], v[230:233], v[4:7]
	v_mfma_f32_16x16x32_bf16 v[0:3], v[140:143], v[230:233], v[0:3]
	s_barrier
	s_add_i32 s53, s53, 2
	s_add_u32 s58, s58, 0x100
	s_addc_u32 s59, s59, 0
	s_add_u32 s35, s35, 0x100
	s_addc_u32 s51, s51, 0
	s_cmp_gt_u32 s53, 13
	s_cbranch_scc0 .LBB0_1960
	s_and_b64 vcc, exec, s[48:49]
	s_cbranch_vccz .LBB0_1963
	s_barrier

;     __device__ __forceinline__ void a_ready(const Unit& u) const { wait_panel(cnt, u.pm, need, tmo, wave); }
;     __device__ __forceinline__ void a_ready(const Unit& u) const { wait_panel(cnt, u.pm, need, tmo, wave); }
; #define PG8_STAGE(bufoff, gbase, voff) do { _Pragma("unroll") for (int _i = 0; _i < 2; ++_i) \
;         __builtin_amdgcn_global_load_lds((const unsigned*)((const char*)(gbase) + (voff)[_i]), (PG8_LAS unsigned*)(lds + (bufoff) + ldsw + _i * 8192), 16, 0, 0); } while (0)
; #define PG8_LDA(dst, b, h) do { _Pragma("unroll") for (int m = 0; m < 4; ++m) _Pragma("unroll") for (int k = 0; k < 2; ++k) dst[m][k] = *(const PG8_LAS bf16x8*)(lds + PG8_SA(b, h) + aoff + m * 2048 + k * 1024); } while (0)
; #define PG8_LDB(dst, b, h) do { _Pragma("unroll") for (int n = 0; n < 2; ++n) _Pragma("unroll") for (int k = 0; k < 2; ++k) dst[n][k] = *(const PG8_LAS bf16x8*)(lds + PG8_SB(b, h) + boff + n * 2048 + k * 1024); } while (0)
; #define PG8_WAIT_V(n) asm volatile("s_waitcnt vmcnt(" #n ")" ::: "memory")
; #define PG8_WAIT_L(n) asm volatile("s_waitcnt lgkmcnt(" #n ")" ::: "memory")
; #define PG8_BAR __builtin_amdgcn_s_barrier()
; #define PG8_SCHED __builtin_amdgcn_sched_barrier(0)
; template <class Epi, class Sched, bool ALIGN_EPI = false, bool SP2 = false>
; __device__ __forceinline__ void gemm_phase(PG8_LAS unsigned char* lds, const Gemm g, const Sched& S, const Epi& E, const int tid_in) {
;     ...
;             const bool last = (t == nt - 2);
;             const char* a1 = cA + (size_t)(t + 1) * kstep;
;             const char* a2 = last ? nA : cA + (size_t)(t + 2) * kstep; const char* b2 = last ? nB : cB + (size_t)(t + 2) * kstep;
;             const char* a3 = a2 + kstep; const char* b3 = b2 + kstep;
;             if (last && has_next) S.a_ready(nxt);
;             if constexpr (SP2) {
;             PG8_LDB(B0, 0, 0); PG8_LDB(B1, 0, 1); PG8_SCHED; PG8_LDA(At, 0, 0); PG8_STAGE(PG8_SA(1, 1), a1 + hstepA, voffA);
;             PG8_WAIT_V(8); PG8_WAIT_L(0); PG8_BAR; PG8_MMA(0, 0, At, B0); PG8_MMA(0, 1, At, B1); PG8_BAR; PG8_SCHED;
;             PG8_LDA(At, 0, 1); PG8_STAGE(PG8_SB(0, 0), b2, voffB); PG8_STAGE(PG8_SB(0, 1), b2 + hstepB, voffB); PG8_STAGE(PG8_SA(0, 0), a2, voffA);
;             PG8_WAIT_V(8); PG8_WAIT_L(0); PG8_BAR; PG8_MMA(1, 0, At, B0); PG8_MMA(1, 1, At, B1); PG8_BAR; PG8_SCHED;
.LBB0_2041:
	ds_read_b128 v[104:107], v249
	ds_read_b128 v[108:111], v249 offset:1024
	ds_read_b128 v[112:115], v249 offset:2048
	ds_read_b128 v[116:119], v249 offset:3072
	ds_read_b128 v[144:147], v249 offset:16384
	ds_read_b128 v[148:151], v249 offset:17408
	ds_read_b128 v[152:155], v249 offset:18432
	ds_read_b128 v[156:159], v249 offset:19456
	ds_read_b128 v[160:163], v204
	ds_read_b128 v[192:195], v204 offset:1024
	ds_read_b128 v[196:199], v204 offset:2048
	ds_read_b128 v[206:209], v204 offset:3072
	ds_read_b128 v[210:213], v204 offset:4096
	ds_read_b128 v[224:227], v204 offset:5120
	ds_read_b128 v[228:231], v204 offset:6144
	ds_read_b128 v[232:235], v204 offset:7168
	s_add_u32 s22, s58, 0xfff80080
	s_addc_u32 s23, s59, -1
	s_add_i32 s65, 0, 0x10000
	s_cmp_eq_u32 s64, 28
	s_cselect_b32 s61, s38, s23
	s_cselect_b32 s60, s51, s22
	s_cselect_b32 s23, s49, s63
	s_cselect_b32 s22, s57, s62
	s_add_i32 s68, 0, 0x14000
	s_add_i32 m0, s28, 0xc000
	s_nop 0
	global_load_lds_dwordx4 v170, s[58:59]
	s_add_i32 m0, s28, 0xe000
	s_nop 0
	global_load_lds_dwordx4 v190, s[58:59]
	s_waitcnt vmcnt(8) lgkmcnt(0)
	s_barrier
	v_mfma_f32_16x16x32_bf16 v[140:143], v[104:107], v[160:163], v[140:143]
	v_mfma_f32_16x16x32_bf16 v[136:139], v[112:115], v[160:163], v[136:139]
	v_mfma_f32_16x16x32_bf16 v[124:127], v[104:107], v[196:199], v[124:127]
	v_mfma_f32_16x16x32_bf16 v[120:123], v[112:115], v[196:199], v[120:123]
	v_mfma_f32_16x16x32_bf16 v[92:95], v[104:107], v[210:213], v[92:95]
	v_mfma_f32_16x16x32_bf16 v[88:91], v[112:115], v[210:213], v[88:91]
	v_mfma_f32_16x16x32_bf16 v[76:79], v[104:107], v[228:231], v[76:79]
	v_mfma_f32_16x16x32_bf16 v[72:75], v[112:115], v[228:231], v[72:75]
	v_mfma_f32_16x16x32_bf16 v[140:143], v[108:111], v[192:195], v[140:143]
	v_mfma_f32_16x16x32_bf16 v[136:139], v[116:119], v[192:195], v[136:139]
	v_mfma_f32_16x16x32_bf16 v[124:127], v[108:111], v[206:209], v[124:127]
	v_mfma_f32_16x16x32_bf16 v[120:123], v[116:119], v[206:209], v[120:123]
	v_mfma_f32_16x16x32_bf16 v[92:95], v[108:111], v[224:227], v[92:95]
	v_mfma_f32_16x16x32_bf16 v[88:91], v[116:119], v[224:227], v[88:91]
	v_mfma_f32_16x16x32_bf16 v[76:79], v[108:111], v[232:235], v[76:79]
	v_mfma_f32_16x16x32_bf16 v[72:75], v[116:119], v[232:235], v[72:75]
	v_mfma_f32_16x16x32_bf16 v[132:135], v[144:147], v[160:163], v[132:135]
	v_mfma_f32_16x16x32_bf16 v[128:131], v[152:155], v[160:163], v[128:131]
	v_mfma_f32_16x16x32_bf16 v[100:103], v[144:147], v[196:199], v[100:103]
	v_mfma_f32_16x16x32_bf16 v[96:99], v[152:155], v[196:199], v[96:99]
	v_mfma_f32_16x16x32_bf16 v[84:87], v[144:147], v[210:213], v[84:87]
	v_mfma_f32_16x16x32_bf16 v[80:83], v[152:155], v[210:213], v[80:83]
	v_mfma_f32_16x16x32_bf16 v[68:71], v[144:147], v[228:231], v[68:71]
	v_mfma_f32_16x16x32_bf16 v[64:67], v[152:155], v[228:231], v[64:67]
	v_mfma_f32_16x16x32_bf16 v[132:135], v[148:151], v[192:195], v[132:135]
	v_mfma_f32_16x16x32_bf16 v[128:131], v[156:159], v[192:195], v[128:131]
	v_mfma_f32_16x16x32_bf16 v[100:103], v[148:151], v[206:209], v[100:103]
	v_mfma_f32_16x16x32_bf16 v[96:99], v[156:159], v[206:209], v[96:99]
	v_mfma_f32_16x16x32_bf16 v[84:87], v[148:151], v[224:227], v[84:87]
	v_mfma_f32_16x16x32_bf16 v[80:83], v[156:159], v[224:227], v[80:83]
	v_mfma_f32_16x16x32_bf16 v[68:71], v[148:151], v[232:235], v[68:71]
	v_mfma_f32_16x16x32_bf16 v[64:67], v[156:159], v[232:235], v[64:67]
	s_barrier
	ds_read_b128 v[160:163], v204 offset:16384
	ds_read_b128 v[192:195], v204 offset:17408
	ds_read_b128 v[196:199], v204 offset:18432
	ds_read_b128 v[206:209], v204 offset:19456
	ds_read_b128 v[210:213], v204 offset:20480
	ds_read_b128 v[224:227], v204 offset:21504
	ds_read_b128 v[228:231], v204 offset:22528
	ds_read_b128 v[232:235], v204 offset:23552
	s_add_i32 s65, s65, s21
	s_mov_b32 m0, s65
	s_nop 0
	global_load_lds_dwordx4 v172, s[22:23]
	s_add_i32 m0, s65, 0x2000
	s_add_u32 s66, s22, 0x80000
	s_addc_u32 s67, s23, 0
	s_add_i32 s65, s68, s21
	global_load_lds_dwordx4 v168, s[22:23]
	s_mov_b32 m0, s65
	s_nop 0
	global_load_lds_dwordx4 v172, s[66:67]
	s_add_i32 m0, s65, 0x2000
	s_nop 0
	global_load_lds_dwordx4 v168, s[66:67]
	s_add_u32 vcc_lo, s60, 0x80
	s_addc_u32 vcc_hi, s61, 0
	s_mov_b32 m0, s28
	s_nop 0
	global_load_lds_dwordx4 v164, s[60:61]
	s_mov_b32 m0, s29
	s_nop 0
	global_load_lds_dwordx4 v166, s[60:61]
	s_waitcnt vmcnt(8) lgkmcnt(0)
	s_barrier
	v_mfma_f32_16x16x32_bf16 v[60:63], v[104:107], v[160:163], v[60:63]
	v_mfma_f32_16x16x32_bf16 v[56:59], v[112:115], v[160:163], v[56:59]
	v_mfma_f32_16x16x32_bf16 v[44:47], v[104:107], v[196:199], v[44:47]
	v_mfma_f32_16x16x32_bf16 v[40:43], v[112:115], v[196:199], v[40:43]
	v_mfma_f32_16x16x32_bf16 v[28:31], v[104:107], v[210:213], v[28:31]
	v_mfma_f32_16x16x32_bf16 v[24:27], v[112:115], v[210:213], v[24:27]
	v_mfma_f32_16x16x32_bf16 v[12:15], v[104:107], v[228:231], v[12:15]
	v_mfma_f32_16x16x32_bf16 v[8:11], v[112:115], v[228:231], v[8:11]
	v_mfma_f32_16x16x32_bf16 v[60:63], v[108:111], v[192:195], v[60:63]
	v_mfma_f32_16x16x32_bf16 v[56:59], v[116:119], v[192:195], v[56:59]
	v_mfma_f32_16x16x32_bf16 v[44:47], v[108:111], v[206:209], v[44:47]
	v_mfma_f32_16x16x32_bf16 v[40:43], v[116:119], v[206:209], v[40:43]
	v_mfma_f32_16x16x32_bf16 v[28:31], v[108:111], v[224:227], v[28:31]
	v_mfma_f32_16x16x32_bf16 v[24:27], v[116:119], v[224:227], v[24:27]
	v_mfma_f32_16x16x32_bf16 v[12:15], v[108:111], v[232:235], v[12:15]
	v_mfma_f32_16x16x32_bf16 v[8:11], v[116:119], v[232:235], v[8:11]
	v_mfma_f32_16x16x32_bf16 v[52:55], v[144:147], v[160:163], v[52:55]
	v_mfma_f32_16x16x32_bf16 v[48:51], v[152:155], v[160:163], v[48:51]
	v_mfma_f32_16x16x32_bf16 v[36:39], v[144:147], v[196:199], v[36:39]
	v_mfma_f32_16x16x32_bf16 v[32:35], v[152:155], v[196:199], v[32:35]
	v_mfma_f32_16x16x32_bf16 v[20:23], v[144:147], v[210:213], v[20:23]
	v_mfma_f32_16x16x32_bf16 v[16:19], v[152:155], v[210:213], v[16:19]
	v_mfma_f32_16x16x32_bf16 v[4:7], v[144:147], v[228:231], v[4:7]
	v_mfma_f32_16x16x32_bf16 v[0:3], v[152:155], v[228:231], v[0:3]
	v_mfma_f32_16x16x32_bf16 v[52:55], v[148:151], v[192:195], v[52:55]
	v_mfma_f32_16x16x32_bf16 v[48:51], v[156:159], v[192:195], v[48:51]
	v_mfma_f32_16x16x32_bf16 v[36:39], v[148:151], v[206:209], v[36:39]
	v_mfma_f32_16x16x32_bf16 v[32:35], v[156:159], v[206:209], v[32:35]
	v_mfma_f32_16x16x32_bf16 v[20:23], v[148:151], v[224:227], v[20:23]
	v_mfma_f32_16x16x32_bf16 v[16:19], v[156:159], v[224:227], v[16:19]
	v_mfma_f32_16x16x32_bf16 v[4:7], v[148:151], v[232:235], v[4:7]
	v_mfma_f32_16x16x32_bf16 v[0:3], v[156:159], v[232:235], v[0:3]
	s_barrier
; #define PG8_STAGE(bufoff, gbase, voff) do { _Pragma("unroll") for (int _i = 0; _i < 2; ++_i) \
;         __builtin_amdgcn_global_load_lds((const unsigned*)((const char*)(gbase) + (voff)[_i]), (PG8_LAS unsigned*)(lds + (bufoff) + ldsw + _i * 8192), 16, 0, 0); } while (0)
; #define PG8_LDA(dst, b, h) do { _Pragma("unroll") for (int m = 0; m < 4; ++m) _Pragma("unroll") for (int k = 0; k < 2; ++k) dst[m][k] = *(const PG8_LAS bf16x8*)(lds + PG8_SA(b, h) + aoff + m * 2048 + k * 1024); } while (0)
; #define PG8_LDB(dst, b, h) do { _Pragma("unroll") for (int n = 0; n < 2; ++n) _Pragma("unroll") for (int k = 0; k < 2; ++k) dst[n][k] = *(const PG8_LAS bf16x8*)(lds + PG8_SB(b, h) + boff + n * 2048 + k * 1024); } while (0)
; #define PG8_MMA(ai, bj, At, Bt) do { __builtin_amdgcn_s_setprio(1); _Pragma("unroll") for (int m = 0; m < 4; ++m) _Pragma("unroll") for (int n = 0; n < 2; ++n) _Pragma("unroll") for (int k = 0; k < 2; ++k) \
;         acc[ai][bj][m][n] = __builtin_amdgcn_mfma_f32_16x16x32_bf16(Bt[n][k], At[m][k], acc[ai][bj][m][n], 0, 0, 0); __builtin_amdgcn_s_setprio(0); } while (0)
; #define PG8_WAIT_V(n) asm volatile("s_waitcnt vmcnt(" #n ")" ::: "memory")
; #define PG8_WAIT_L(n) asm volatile("s_waitcnt lgkmcnt(" #n ")" ::: "memory")
; #define PG8_BAR __builtin_amdgcn_s_barrier()
; #define PG8_SCHED __builtin_amdgcn_sched_barrier(0)
; template <class Epi, class Sched, bool ALIGN_EPI = false, bool SP2 = false>
; __device__ __forceinline__ void gemm_phase(PG8_LAS unsigned char* lds, const Gemm g, const Sched& S, const Epi& E, const int tid_in) {
;     ...
;             PG8_LDB(B0, 1, 0); PG8_LDB(B1, 1, 1); PG8_SCHED; PG8_LDA(At, 1, 0); PG8_STAGE(PG8_SA(0, 1), a2 + hstepA, voffA);
;             PG8_WAIT_V(8); PG8_WAIT_L(0); PG8_BAR; PG8_MMA(0, 0, At, B0); PG8_MMA(0, 1, At, B1); PG8_BAR; PG8_SCHED;
;             PG8_LDA(At, 1, 1); PG8_STAGE(PG8_SB(1, 0), b3, voffB); PG8_STAGE(PG8_SB(1, 1), b3 + hstepB, voffB); PG8_STAGE(PG8_SA(1, 0), a3, voffA);
;             PG8_WAIT_V(8); PG8_WAIT_L(0); PG8_BAR; PG8_MMA(1, 0, At, B0); PG8_MMA(1, 1, At, B1); PG8_BAR; PG8_SCHED;
;     ...
;         if constexpr (ALIGN_EPI) { if (wr == 0) PG8_BAR; }
	ds_read_b128 v[104:107], v249 offset:32768
	ds_read_b128 v[108:111], v249 offset:33792
	ds_read_b128 v[112:115], v249 offset:34816
	ds_read_b128 v[116:119], v249 offset:35840
	ds_read_b128 v[144:147], v249 offset:49152
	ds_read_b128 v[148:151], v249 offset:50176
	ds_read_b128 v[152:155], v249 offset:51200
	ds_read_b128 v[156:159], v249 offset:52224
	ds_read_b128 v[160:163], v204 offset:32768
	ds_read_b128 v[192:195], v204 offset:33792
	ds_read_b128 v[196:199], v204 offset:34816
	ds_read_b128 v[206:209], v204 offset:35840
	ds_read_b128 v[210:213], v204 offset:36864
	ds_read_b128 v[224:227], v204 offset:37888
	ds_read_b128 v[228:231], v204 offset:38912
	ds_read_b128 v[232:235], v204 offset:39936
	s_add_i32 s65, 0, 0x18000
	s_add_i32 s66, 0, 0x1c000
	s_add_u32 s60, s60, 0x80000
	s_addc_u32 s61, s61, 0
	s_mov_b32 m0, s30
	s_nop 0
	global_load_lds_dwordx4 v164, s[60:61]
	s_mov_b32 m0, s6
	s_nop 0
	global_load_lds_dwordx4 v166, s[60:61]
	s_waitcnt vmcnt(8) lgkmcnt(0)
	s_barrier
	v_mfma_f32_16x16x32_bf16 v[140:143], v[104:107], v[160:163], v[140:143]
	v_mfma_f32_16x16x32_bf16 v[136:139], v[112:115], v[160:163], v[136:139]
	v_mfma_f32_16x16x32_bf16 v[124:127], v[104:107], v[196:199], v[124:127]
	v_mfma_f32_16x16x32_bf16 v[120:123], v[112:115], v[196:199], v[120:123]
	v_mfma_f32_16x16x32_bf16 v[92:95], v[104:107], v[210:213], v[92:95]
	v_mfma_f32_16x16x32_bf16 v[88:91], v[112:115], v[210:213], v[88:91]
	v_mfma_f32_16x16x32_bf16 v[76:79], v[104:107], v[228:231], v[76:79]
	v_mfma_f32_16x16x32_bf16 v[72:75], v[112:115], v[228:231], v[72:75]
	v_mfma_f32_16x16x32_bf16 v[140:143], v[108:111], v[192:195], v[140:143]
	v_mfma_f32_16x16x32_bf16 v[136:139], v[116:119], v[192:195], v[136:139]
	v_mfma_f32_16x16x32_bf16 v[124:127], v[108:111], v[206:209], v[124:127]
	v_mfma_f32_16x16x32_bf16 v[120:123], v[116:119], v[206:209], v[120:123]
	v_mfma_f32_16x16x32_bf16 v[92:95], v[108:111], v[224:227], v[92:95]
	v_mfma_f32_16x16x32_bf16 v[88:91], v[116:119], v[224:227], v[88:91]
	v_mfma_f32_16x16x32_bf16 v[76:79], v[108:111], v[232:235], v[76:79]
	v_mfma_f32_16x16x32_bf16 v[72:75], v[116:119], v[232:235], v[72:75]
	v_mfma_f32_16x16x32_bf16 v[132:135], v[144:147], v[160:163], v[132:135]
	v_mfma_f32_16x16x32_bf16 v[128:131], v[152:155], v[160:163], v[128:131]
	v_mfma_f32_16x16x32_bf16 v[100:103], v[144:147], v[196:199], v[100:103]
	v_mfma_f32_16x16x32_bf16 v[96:99], v[152:155], v[196:199], v[96:99]
	v_mfma_f32_16x16x32_bf16 v[84:87], v[144:147], v[210:213], v[84:87]
	v_mfma_f32_16x16x32_bf16 v[80:83], v[152:155], v[210:213], v[80:83]
	v_mfma_f32_16x16x32_bf16 v[68:71], v[144:147], v[228:231], v[68:71]
	v_mfma_f32_16x16x32_bf16 v[64:67], v[152:155], v[228:231], v[64:67]
	v_mfma_f32_16x16x32_bf16 v[132:135], v[148:151], v[192:195], v[132:135]
	v_mfma_f32_16x16x32_bf16 v[128:131], v[156:159], v[192:195], v[128:131]
	v_mfma_f32_16x16x32_bf16 v[100:103], v[148:151], v[206:209], v[100:103]
	v_mfma_f32_16x16x32_bf16 v[96:99], v[156:159], v[206:209], v[96:99]
	v_mfma_f32_16x16x32_bf16 v[84:87], v[148:151], v[224:227], v[84:87]
	v_mfma_f32_16x16x32_bf16 v[80:83], v[156:159], v[224:227], v[80:83]
	v_mfma_f32_16x16x32_bf16 v[68:71], v[148:151], v[232:235], v[68:71]
	v_mfma_f32_16x16x32_bf16 v[64:67], v[156:159], v[232:235], v[64:67]
	s_barrier
	ds_read_b128 v[160:163], v204 offset:49152
	ds_read_b128 v[192:195], v204 offset:50176
	ds_read_b128 v[196:199], v204 offset:51200
	ds_read_b128 v[206:209], v204 offset:52224
	ds_read_b128 v[210:213], v204 offset:53248
	ds_read_b128 v[224:227], v204 offset:54272
	ds_read_b128 v[228:231], v204 offset:55296
	ds_read_b128 v[232:235], v204 offset:56320
	s_add_i32 s60, s65, s21
	s_mov_b32 m0, s60
	s_add_u32 s100, s22, 0x80
	s_addc_u32 s101, s23, 0
	global_load_lds_dwordx4 v172, s[100:101]
	s_add_i32 m0, s60, 0x2000
	s_add_u32 s22, s22, 0x80080
	s_addc_u32 s23, s23, 0
	s_add_i32 s60, s66, s21
	global_load_lds_dwordx4 v168, s[100:101]
	s_mov_b32 m0, s60
	s_nop 0
	global_load_lds_dwordx4 v172, s[22:23]
	s_add_i32 m0, s60, 0x2000
	s_nop 0
	global_load_lds_dwordx4 v168, s[22:23]
	s_mov_b32 m0, s33
	s_nop 0
	global_load_lds_dwordx4 v164, vcc
	s_mov_b32 m0, s34
	s_nop 0
	global_load_lds_dwordx4 v166, vcc
	s_waitcnt vmcnt(8) lgkmcnt(0)
	s_barrier
	v_mfma_f32_16x16x32_bf16 v[60:63], v[104:107], v[160:163], v[60:63]
	v_mfma_f32_16x16x32_bf16 v[56:59], v[112:115], v[160:163], v[56:59]
	v_mfma_f32_16x16x32_bf16 v[44:47], v[104:107], v[196:199], v[44:47]
	v_mfma_f32_16x16x32_bf16 v[40:43], v[112:115], v[196:199], v[40:43]
	v_mfma_f32_16x16x32_bf16 v[28:31], v[104:107], v[210:213], v[28:31]
	v_mfma_f32_16x16x32_bf16 v[24:27], v[112:115], v[210:213], v[24:27]
	v_mfma_f32_16x16x32_bf16 v[12:15], v[104:107], v[228:231], v[12:15]
	v_mfma_f32_16x16x32_bf16 v[8:11], v[112:115], v[228:231], v[8:11]
	v_mfma_f32_16x16x32_bf16 v[60:63], v[108:111], v[192:195], v[60:63]
	v_mfma_f32_16x16x32_bf16 v[56:59], v[116:119], v[192:195], v[56:59]
	v_mfma_f32_16x16x32_bf16 v[44:47], v[108:111], v[206:209], v[44:47]
	v_mfma_f32_16x16x32_bf16 v[40:43], v[116:119], v[206:209], v[40:43]
	v_mfma_f32_16x16x32_bf16 v[28:31], v[108:111], v[224:227], v[28:31]
	v_mfma_f32_16x16x32_bf16 v[24:27], v[116:119], v[224:227], v[24:27]
	v_mfma_f32_16x16x32_bf16 v[12:15], v[108:111], v[232:235], v[12:15]
	v_mfma_f32_16x16x32_bf16 v[8:11], v[116:119], v[232:235], v[8:11]
	v_mfma_f32_16x16x32_bf16 v[52:55], v[144:147], v[160:163], v[52:55]
	v_mfma_f32_16x16x32_bf16 v[48:51], v[152:155], v[160:163], v[48:51]
	v_mfma_f32_16x16x32_bf16 v[36:39], v[144:147], v[196:199], v[36:39]
	v_mfma_f32_16x16x32_bf16 v[32:35], v[152:155], v[196:199], v[32:35]
	v_mfma_f32_16x16x32_bf16 v[20:23], v[144:147], v[210:213], v[20:23]
	v_mfma_f32_16x16x32_bf16 v[16:19], v[152:155], v[210:213], v[16:19]
	v_mfma_f32_16x16x32_bf16 v[4:7], v[144:147], v[228:231], v[4:7]
	v_mfma_f32_16x16x32_bf16 v[0:3], v[152:155], v[228:231], v[0:3]
	v_mfma_f32_16x16x32_bf16 v[52:55], v[148:151], v[192:195], v[52:55]
	v_mfma_f32_16x16x32_bf16 v[48:51], v[156:159], v[192:195], v[48:51]
	v_mfma_f32_16x16x32_bf16 v[36:39], v[148:151], v[206:209], v[36:39]
	v_mfma_f32_16x16x32_bf16 v[32:35], v[156:159], v[206:209], v[32:35]
	v_mfma_f32_16x16x32_bf16 v[20:23], v[148:151], v[224:227], v[20:23]
	v_mfma_f32_16x16x32_bf16 v[16:19], v[156:159], v[224:227], v[16:19]
	v_mfma_f32_16x16x32_bf16 v[4:7], v[148:151], v[232:235], v[4:7]
	v_mfma_f32_16x16x32_bf16 v[0:3], v[156:159], v[232:235], v[0:3]
	s_barrier
	s_add_i32 s64, s64, 2
	s_add_u32 s58, s58, 0x100
	s_addc_u32 s59, s59, 0
	s_add_u32 s62, s62, 0x100
	s_addc_u32 s63, s63, 0
	s_cmp_gt_u32 s64, 29
	s_cbranch_scc0 .LBB0_2041
	s_and_b64 vcc, exec, s[46:47]
	s_cbranch_vccz .LBB0_2044
	s_barrier

;     __device__ __forceinline__ void a_ready(const Unit& u) const { wait_panel(cnt, u.pm, need, tmo, wave); }
;     __device__ __forceinline__ void a_ready(const Unit& u) const { wait_panel(cnt, u.pm, need, tmo, wave); }
; #define PG8_STAGE(bufoff, gbase, voff) do { _Pragma("unroll") for (int _i = 0; _i < 2; ++_i) \
;         __builtin_amdgcn_global_load_lds((const unsigned*)((const char*)(gbase) + (voff)[_i]), (PG8_LAS unsigned*)(lds + (bufoff) + ldsw + _i * 8192), 16, 0, 0); } while (0)
; #define PG8_LDA(dst, b, h) do { _Pragma("unroll") for (int m = 0; m < 4; ++m) _Pragma("unroll") for (int k = 0; k < 2; ++k) dst[m][k] = *(const PG8_LAS bf16x8*)(lds + PG8_SA(b, h) + aoff + m * 2048 + k * 1024); } while (0)
; #define PG8_LDB(dst, b, h) do { _Pragma("unroll") for (int n = 0; n < 2; ++n) _Pragma("unroll") for (int k = 0; k < 2; ++k) dst[n][k] = *(const PG8_LAS bf16x8*)(lds + PG8_SB(b, h) + boff + n * 2048 + k * 1024); } while (0)
; #define PG8_WAIT_V(n) asm volatile("s_waitcnt vmcnt(" #n ")" ::: "memory")
; #define PG8_WAIT_L(n) asm volatile("s_waitcnt lgkmcnt(" #n ")" ::: "memory")
; #define PG8_BAR __builtin_amdgcn_s_barrier()
; #define PG8_SCHED __builtin_amdgcn_sched_barrier(0)
; template <class Epi, class Sched, bool ALIGN_EPI = false, bool SP2 = false>
; __device__ __forceinline__ void gemm_phase(PG8_LAS unsigned char* lds, const Gemm g, const Sched& S, const Epi& E, const int tid_in) {
;     ...
;             const bool last = (t == nt - 2);
;             const char* a1 = cA + (size_t)(t + 1) * kstep;
;             const char* a2 = last ? nA : cA + (size_t)(t + 2) * kstep; const char* b2 = last ? nB : cB + (size_t)(t + 2) * kstep;
;             const char* a3 = a2 + kstep; const char* b3 = b2 + kstep;
;             if (last && has_next) S.a_ready(nxt);
;             if constexpr (SP2) {
;             PG8_LDB(B0, 0, 0); PG8_LDB(B1, 0, 1); PG8_SCHED; PG8_LDA(At, 0, 0); PG8_STAGE(PG8_SA(1, 1), a1 + hstepA, voffA);
;             PG8_WAIT_V(8); PG8_WAIT_L(0); PG8_BAR; PG8_MMA(0, 0, At, B0); PG8_MMA(0, 1, At, B1); PG8_BAR; PG8_SCHED;
;             PG8_LDA(At, 0, 1); PG8_STAGE(PG8_SB(0, 0), b2, voffB); PG8_STAGE(PG8_SB(0, 1), b2 + hstepB, voffB); PG8_STAGE(PG8_SA(0, 0), a2, voffA);
;             PG8_WAIT_V(8); PG8_WAIT_L(0); PG8_BAR; PG8_MMA(1, 0, At, B0); PG8_MMA(1, 1, At, B1); PG8_BAR; PG8_SCHED;
.LBB0_2059:
	ds_read_b128 v[64:67], v249
	ds_read_b128 v[68:71], v249 offset:1024
	ds_read_b128 v[72:75], v249 offset:2048
	ds_read_b128 v[76:79], v249 offset:3072
	ds_read_b128 v[80:83], v249 offset:16384
	ds_read_b128 v[84:87], v249 offset:17408
	ds_read_b128 v[88:91], v249 offset:18432
	ds_read_b128 v[92:95], v249 offset:19456
	ds_read_b128 v[96:99], v154
	ds_read_b128 v[100:103], v154 offset:1024
	ds_read_b128 v[104:107], v154 offset:2048
	ds_read_b128 v[108:111], v154 offset:3072
	ds_read_b128 v[112:115], v154 offset:4096
	ds_read_b128 v[116:119], v154 offset:5120
	ds_read_b128 v[120:123], v154 offset:6144
	ds_read_b128 v[124:127], v154 offset:7168
	s_add_u32 s22, s62, 0xfff80080
	s_addc_u32 s23, s63, -1
	s_add_i32 s55, 0, 0x10000
	s_cmp_eq_u32 s53, 4
	s_cselect_b32 s65, s61, s23
	s_cselect_b32 s64, s60, s22
	s_cselect_b32 s23, s59, s38
	s_cselect_b32 s22, s58, s35
	s_add_i32 s57, 0, 0x14000
	s_add_i32 m0, s12, 0xc000
	s_nop 0
	global_load_lds_dwordx4 v148, s[62:63]
	s_add_i32 m0, s12, 0xe000
	s_nop 0
	global_load_lds_dwordx4 v146, s[62:63]
	s_waitcnt vmcnt(8) lgkmcnt(0)
	s_barrier
	v_mfma_f32_16x16x32_bf16 v[60:63], v[64:67], v[96:99], v[60:63]
	v_mfma_f32_16x16x32_bf16 v[56:59], v[72:75], v[96:99], v[56:59]
	v_mfma_f32_16x16x32_bf16 v[48:51], v[64:67], v[104:107], v[48:51]
	v_mfma_f32_16x16x32_bf16 v[40:43], v[72:75], v[104:107], v[40:43]
	v_mfma_f32_16x16x32_bf16 v[32:35], v[64:67], v[112:115], v[32:35]
	v_mfma_f32_16x16x32_bf16 v[24:27], v[72:75], v[112:115], v[24:27]
	v_mfma_f32_16x16x32_bf16 v[16:19], v[64:67], v[120:123], v[16:19]
	v_mfma_f32_16x16x32_bf16 v[8:11], v[72:75], v[120:123], v[8:11]
	v_mfma_f32_16x16x32_bf16 v[60:63], v[68:71], v[100:103], v[60:63]
	v_mfma_f32_16x16x32_bf16 v[56:59], v[76:79], v[100:103], v[56:59]
	v_mfma_f32_16x16x32_bf16 v[48:51], v[68:71], v[108:111], v[48:51]
	v_mfma_f32_16x16x32_bf16 v[40:43], v[76:79], v[108:111], v[40:43]
	v_mfma_f32_16x16x32_bf16 v[32:35], v[68:71], v[116:119], v[32:35]
	v_mfma_f32_16x16x32_bf16 v[24:27], v[76:79], v[116:119], v[24:27]
	v_mfma_f32_16x16x32_bf16 v[16:19], v[68:71], v[124:127], v[16:19]
	v_mfma_f32_16x16x32_bf16 v[8:11], v[76:79], v[124:127], v[8:11]
	v_mfma_f32_16x16x32_bf16 v[52:55], v[80:83], v[96:99], v[52:55]
	v_mfma_f32_16x16x32_bf16 v[44:47], v[88:91], v[96:99], v[44:47]
	v_mfma_f32_16x16x32_bf16 v[36:39], v[80:83], v[104:107], v[36:39]
	v_mfma_f32_16x16x32_bf16 v[28:31], v[88:91], v[104:107], v[28:31]
	v_mfma_f32_16x16x32_bf16 v[20:23], v[80:83], v[112:115], v[20:23]
	v_mfma_f32_16x16x32_bf16 v[12:15], v[88:91], v[112:115], v[12:15]
	v_mfma_f32_16x16x32_bf16 v[4:7], v[80:83], v[120:123], v[4:7]
	v_mfma_f32_16x16x32_bf16 v[0:3], v[88:91], v[120:123], v[0:3]
	v_mfma_f32_16x16x32_bf16 v[52:55], v[84:87], v[100:103], v[52:55]
	v_mfma_f32_16x16x32_bf16 v[44:47], v[92:95], v[100:103], v[44:47]
	v_mfma_f32_16x16x32_bf16 v[36:39], v[84:87], v[108:111], v[36:39]
	v_mfma_f32_16x16x32_bf16 v[28:31], v[92:95], v[108:111], v[28:31]
	v_mfma_f32_16x16x32_bf16 v[20:23], v[84:87], v[116:119], v[20:23]
	v_mfma_f32_16x16x32_bf16 v[12:15], v[92:95], v[116:119], v[12:15]
	v_mfma_f32_16x16x32_bf16 v[4:7], v[84:87], v[124:127], v[4:7]
	v_mfma_f32_16x16x32_bf16 v[0:3], v[92:95], v[124:127], v[0:3]
	s_barrier
	s_add_i32 s55, s55, s6
	s_mov_b32 m0, s55
	s_nop 0
	global_load_lds_dwordx4 v172, s[22:23]
	s_add_i32 m0, s55, 0x2000
	s_add_u32 s66, s22, 0x80000
	s_addc_u32 s67, s23, 0
	s_add_i32 s55, s57, s6
	global_load_lds_dwordx4 v128, s[22:23]
	s_mov_b32 m0, s55
	s_nop 0
	global_load_lds_dwordx4 v172, s[66:67]
	s_add_i32 m0, s55, 0x2000
	s_nop 0
	global_load_lds_dwordx4 v128, s[66:67]
	s_mov_b32 m0, s12
	s_nop 0
	global_load_lds_dwordx4 v172, s[64:65]
	s_mov_b32 m0, s20
	s_nop 0
	global_load_lds_dwordx4 v128, s[64:65]
	s_waitcnt vmcnt(8) lgkmcnt(0)
	s_barrier
	s_barrier
; #define PG8_STAGE(bufoff, gbase, voff) do { _Pragma("unroll") for (int _i = 0; _i < 2; ++_i) \
;         __builtin_amdgcn_global_load_lds((const unsigned*)((const char*)(gbase) + (voff)[_i]), (PG8_LAS unsigned*)(lds + (bufoff) + ldsw + _i * 8192), 16, 0, 0); } while (0)
; #define PG8_LDA(dst, b, h) do { _Pragma("unroll") for (int m = 0; m < 4; ++m) _Pragma("unroll") for (int k = 0; k < 2; ++k) dst[m][k] = *(const PG8_LAS bf16x8*)(lds + PG8_SA(b, h) + aoff + m * 2048 + k * 1024); } while (0)
; #define PG8_LDB(dst, b, h) do { _Pragma("unroll") for (int n = 0; n < 2; ++n) _Pragma("unroll") for (int k = 0; k < 2; ++k) dst[n][k] = *(const PG8_LAS bf16x8*)(lds + PG8_SB(b, h) + boff + n * 2048 + k * 1024); } while (0)
; #define PG8_MMA(ai, bj, At, Bt) do { __builtin_amdgcn_s_setprio(1); _Pragma("unroll") for (int m = 0; m < 4; ++m) _Pragma("unroll") for (int n = 0; n < 2; ++n) _Pragma("unroll") for (int k = 0; k < 2; ++k) \
;         acc[ai][bj][m][n] = __builtin_amdgcn_mfma_f32_16x16x32_bf16(Bt[n][k], At[m][k], acc[ai][bj][m][n], 0, 0, 0); __builtin_amdgcn_s_setprio(0); } while (0)
; #define PG8_WAIT_V(n) asm volatile("s_waitcnt vmcnt(" #n ")" ::: "memory")
; #define PG8_WAIT_L(n) asm volatile("s_waitcnt lgkmcnt(" #n ")" ::: "memory")
; #define PG8_BAR __builtin_amdgcn_s_barrier()
; #define PG8_SCHED __builtin_amdgcn_sched_barrier(0)
; template <class Epi, class Sched, bool ALIGN_EPI = false, bool SP2 = false>
; __device__ __forceinline__ void gemm_phase(PG8_LAS unsigned char* lds, const Gemm g, const Sched& S, const Epi& E, const int tid_in) {
;     ...
;             PG8_LDB(B0, 1, 0); PG8_LDB(B1, 1, 1); PG8_SCHED; PG8_LDA(At, 1, 0); PG8_STAGE(PG8_SA(0, 1), a2 + hstepA, voffA);
;             PG8_WAIT_V(8); PG8_WAIT_L(0); PG8_BAR; PG8_MMA(0, 0, At, B0); PG8_MMA(0, 1, At, B1); PG8_BAR; PG8_SCHED;
;             PG8_LDA(At, 1, 1); PG8_STAGE(PG8_SB(1, 0), b3, voffB); PG8_STAGE(PG8_SB(1, 1), b3 + hstepB, voffB); PG8_STAGE(PG8_SA(1, 0), a3, voffA);
;             PG8_WAIT_V(8); PG8_WAIT_L(0); PG8_BAR; PG8_MMA(1, 0, At, B0); PG8_MMA(1, 1, At, B1); PG8_BAR; PG8_SCHED;
;     ...
;         if constexpr (ALIGN_EPI) { if (wr == 0) PG8_BAR; }
	ds_read_b128 v[64:67], v249 offset:32768
	ds_read_b128 v[68:71], v249 offset:33792
	ds_read_b128 v[72:75], v249 offset:34816
	ds_read_b128 v[76:79], v249 offset:35840
	ds_read_b128 v[80:83], v249 offset:49152
	ds_read_b128 v[84:87], v249 offset:50176
	ds_read_b128 v[88:91], v249 offset:51200
	ds_read_b128 v[92:95], v249 offset:52224
	ds_read_b128 v[96:99], v154 offset:32768
	ds_read_b128 v[100:103], v154 offset:33792
	ds_read_b128 v[104:107], v154 offset:34816
	ds_read_b128 v[108:111], v154 offset:35840
	ds_read_b128 v[112:115], v154 offset:36864
	ds_read_b128 v[116:119], v154 offset:37888
	ds_read_b128 v[120:123], v154 offset:38912
	ds_read_b128 v[124:127], v154 offset:39936
	s_add_i32 s55, 0, 0x18000
	s_add_i32 s57, 0, 0x1c000
	s_add_u32 s64, s64, 0x80000
	s_addc_u32 s65, s65, 0
	s_mov_b32 m0, s21
	s_nop 0
	global_load_lds_dwordx4 v172, s[64:65]
	s_mov_b32 m0, s28
	s_nop 0
	global_load_lds_dwordx4 v128, s[64:65]
	s_waitcnt vmcnt(8) lgkmcnt(0)
	s_barrier
	v_mfma_f32_16x16x32_bf16 v[60:63], v[64:67], v[96:99], v[60:63]
	v_mfma_f32_16x16x32_bf16 v[56:59], v[72:75], v[96:99], v[56:59]
	v_mfma_f32_16x16x32_bf16 v[48:51], v[64:67], v[104:107], v[48:51]
	v_mfma_f32_16x16x32_bf16 v[40:43], v[72:75], v[104:107], v[40:43]
	v_mfma_f32_16x16x32_bf16 v[32:35], v[64:67], v[112:115], v[32:35]
	v_mfma_f32_16x16x32_bf16 v[24:27], v[72:75], v[112:115], v[24:27]
	v_mfma_f32_16x16x32_bf16 v[16:19], v[64:67], v[120:123], v[16:19]
	v_mfma_f32_16x16x32_bf16 v[8:11], v[72:75], v[120:123], v[8:11]
	v_mfma_f32_16x16x32_bf16 v[60:63], v[68:71], v[100:103], v[60:63]
	v_mfma_f32_16x16x32_bf16 v[56:59], v[76:79], v[100:103], v[56:59]
	v_mfma_f32_16x16x32_bf16 v[48:51], v[68:71], v[108:111], v[48:51]
	v_mfma_f32_16x16x32_bf16 v[40:43], v[76:79], v[108:111], v[40:43]
	v_mfma_f32_16x16x32_bf16 v[32:35], v[68:71], v[116:119], v[32:35]
	v_mfma_f32_16x16x32_bf16 v[24:27], v[76:79], v[116:119], v[24:27]
	v_mfma_f32_16x16x32_bf16 v[16:19], v[68:71], v[124:127], v[16:19]
	v_mfma_f32_16x16x32_bf16 v[8:11], v[76:79], v[124:127], v[8:11]
	v_mfma_f32_16x16x32_bf16 v[52:55], v[80:83], v[96:99], v[52:55]
	v_mfma_f32_16x16x32_bf16 v[44:47], v[88:91], v[96:99], v[44:47]
	v_mfma_f32_16x16x32_bf16 v[36:39], v[80:83], v[104:107], v[36:39]
	v_mfma_f32_16x16x32_bf16 v[28:31], v[88:91], v[104:107], v[28:31]
	v_mfma_f32_16x16x32_bf16 v[20:23], v[80:83], v[112:115], v[20:23]
	v_mfma_f32_16x16x32_bf16 v[12:15], v[88:91], v[112:115], v[12:15]
	v_mfma_f32_16x16x32_bf16 v[4:7], v[80:83], v[120:123], v[4:7]
	v_mfma_f32_16x16x32_bf16 v[0:3], v[88:91], v[120:123], v[0:3]
	v_mfma_f32_16x16x32_bf16 v[52:55], v[84:87], v[100:103], v[52:55]
	v_mfma_f32_16x16x32_bf16 v[44:47], v[92:95], v[100:103], v[44:47]
	v_mfma_f32_16x16x32_bf16 v[36:39], v[84:87], v[108:111], v[36:39]
	v_mfma_f32_16x16x32_bf16 v[28:31], v[92:95], v[108:111], v[28:31]
	v_mfma_f32_16x16x32_bf16 v[20:23], v[84:87], v[116:119], v[20:23]
	v_mfma_f32_16x16x32_bf16 v[12:15], v[92:95], v[116:119], v[12:15]
	v_mfma_f32_16x16x32_bf16 v[4:7], v[84:87], v[124:127], v[4:7]
	v_mfma_f32_16x16x32_bf16 v[0:3], v[92:95], v[124:127], v[0:3]
	s_barrier
	s_add_i32 s55, s55, s6
	s_mov_b32 m0, s55
	s_nop 0
	s_add_u32 s100, s22, 0x80
	s_addc_u32 s101, s23, 0
	global_load_lds_dwordx4 v172, s[100:101]
	s_add_i32 m0, s55, 0x2000
	s_add_u32 s22, s22, 0x80080
	s_addc_u32 s23, s23, 0
	s_add_i32 s55, s57, s6
	global_load_lds_dwordx4 v128, s[100:101]
	s_mov_b32 m0, s55
	s_nop 0
	global_load_lds_dwordx4 v172, s[22:23]
	s_add_i32 m0, s55, 0x2000
	s_nop 0
	global_load_lds_dwordx4 v128, s[22:23]
	s_mov_b32 m0, s29
	s_nop 0
	s_add_u32 s100, s64, 0xfff80080
	s_addc_u32 s101, s65, -1
	global_load_lds_dwordx4 v172, s[100:101]
	s_mov_b32 m0, s30
	s_nop 0
	global_load_lds_dwordx4 v128, s[100:101]
	s_waitcnt vmcnt(8) lgkmcnt(0)
	s_barrier
	s_barrier
	s_add_i32 s53, s53, 2
	s_add_u32 s62, s62, 0x100
	s_addc_u32 s63, s63, 0
	s_add_u32 s35, s35, 0x100
	s_addc_u32 s38, s38, 0
	s_cmp_gt_u32 s53, 5
	s_cbranch_scc0 .LBB0_2059
	s_and_b64 vcc, exec, s[36:37]
	s_cbranch_vccz .LBB0_2062
	s_barrier

;     __device__ __forceinline__ void a_ready(const Unit& u) const { wait_panel(cnt, u.pm, need, tmo, wave); }
;     __device__ __forceinline__ void a_ready(const Unit& u) const { wait_panel(cnt, u.pm, need, tmo, wave); }
; #define PG8_STAGE(bufoff, gbase, voff) do { _Pragma("unroll") for (int _i = 0; _i < 2; ++_i) \
;         __builtin_amdgcn_global_load_lds((const unsigned*)((const char*)(gbase) + (voff)[_i]), (PG8_LAS unsigned*)(lds + (bufoff) + ldsw + _i * 8192), 16, 0, 0); } while (0)
; #define PG8_LDA(dst, b, h) do { _Pragma("unroll") for (int m = 0; m < 4; ++m) _Pragma("unroll") for (int k = 0; k < 2; ++k) dst[m][k] = *(const PG8_LAS bf16x8*)(lds + PG8_SA(b, h) + aoff + m * 2048 + k * 1024); } while (0)
; #define PG8_LDB(dst, b, h) do { _Pragma("unroll") for (int n = 0; n < 2; ++n) _Pragma("unroll") for (int k = 0; k < 2; ++k) dst[n][k] = *(const PG8_LAS bf16x8*)(lds + PG8_SB(b, h) + boff + n * 2048 + k * 1024); } while (0)
; #define PG8_WAIT_V(n) asm volatile("s_waitcnt vmcnt(" #n ")" ::: "memory")
; #define PG8_WAIT_L(n) asm volatile("s_waitcnt lgkmcnt(" #n ")" ::: "memory")
; #define PG8_BAR __builtin_amdgcn_s_barrier()
; #define PG8_SCHED __builtin_amdgcn_sched_barrier(0)
; template <class Epi, class Sched, bool ALIGN_EPI = false, bool SP2 = false>
; __device__ __forceinline__ void gemm_phase(PG8_LAS unsigned char* lds, const Gemm g, const Sched& S, const Epi& E, const int tid_in) {
;     ...
;             const bool last = (t == nt - 2);
;             const char* a1 = cA + (size_t)(t + 1) * kstep;
;             const char* a2 = last ? nA : cA + (size_t)(t + 2) * kstep; const char* b2 = last ? nB : cB + (size_t)(t + 2) * kstep;
;             const char* a3 = a2 + kstep; const char* b3 = b2 + kstep;
;             if (last && has_next) S.a_ready(nxt);
;             if constexpr (SP2) {
;             PG8_LDB(B0, 0, 0); PG8_LDB(B1, 0, 1); PG8_SCHED; PG8_LDA(At, 0, 0); PG8_STAGE(PG8_SA(1, 1), a1 + hstepA, voffA);
;             PG8_WAIT_V(8); PG8_WAIT_L(0); PG8_BAR; PG8_MMA(0, 0, At, B0); PG8_MMA(0, 1, At, B1); PG8_BAR; PG8_SCHED;
;             PG8_LDA(At, 0, 1); PG8_STAGE(PG8_SB(0, 0), b2, voffB); PG8_STAGE(PG8_SB(0, 1), b2 + hstepB, voffB); PG8_STAGE(PG8_SA(0, 0), a2, voffA);
;             PG8_WAIT_V(8); PG8_WAIT_L(0); PG8_BAR; PG8_MMA(1, 0, At, B0); PG8_MMA(1, 1, At, B1); PG8_BAR; PG8_SCHED;
.LBB0_2312:
	ds_read_b128 v[144:147], v249
	ds_read_b128 v[148:151], v249 offset:1024
	ds_read_b128 v[152:155], v249 offset:2048
	ds_read_b128 v[156:159], v249 offset:3072
	ds_read_b128 v[160:163], v249 offset:16384
	ds_read_b128 v[164:167], v249 offset:17408
	ds_read_b128 v[168:171], v249 offset:18432
	ds_read_b128 v[190:193], v249 offset:19456
	ds_read_b128 v[198:201], v143
	ds_read_b128 v[202:205], v143 offset:1024
	ds_read_b128 v[206:209], v143 offset:2048
	ds_read_b128 v[210:213], v143 offset:3072
	ds_read_b128 v[224:227], v143 offset:4096
	ds_read_b128 v[228:231], v143 offset:5120
	ds_read_b128 v[232:235], v143 offset:6144
	ds_read_b128 v[236:239], v143 offset:7168
	s_add_u32 s22, s64, 0xfff80080
	s_addc_u32 s23, s65, -1
	s_add_i32 s55, 0, 0x10000
	s_cmp_eq_u32 s51, 28
	s_cselect_b32 s67, s6, s23
	s_cselect_b32 s66, s16, s22
	s_cselect_b32 s23, s17, s35
	s_cselect_b32 s22, s33, s34
	s_add_i32 s63, 0, 0x14000
	s_add_i32 m0, s37, 0xc000
	s_nop 0
	global_load_lds_dwordx4 v134, s[64:65]
	s_add_i32 m0, s37, 0xe000
	s_nop 0
	global_load_lds_dwordx4 v136, s[64:65]
	s_waitcnt vmcnt(8) lgkmcnt(0)
	s_barrier
	v_mfma_f32_16x16x32_bf16 v[124:127], v[144:147], v[198:201], v[124:127]
	v_mfma_f32_16x16x32_bf16 v[116:119], v[152:155], v[198:201], v[116:119]
	v_mfma_f32_16x16x32_bf16 v[108:111], v[144:147], v[206:209], v[108:111]
	v_mfma_f32_16x16x32_bf16 v[100:103], v[152:155], v[206:209], v[100:103]
	v_mfma_f32_16x16x32_bf16 v[92:95], v[144:147], v[224:227], v[92:95]
	v_mfma_f32_16x16x32_bf16 v[84:87], v[152:155], v[224:227], v[84:87]
	v_mfma_f32_16x16x32_bf16 v[76:79], v[144:147], v[232:235], v[76:79]
	v_mfma_f32_16x16x32_bf16 v[68:71], v[152:155], v[232:235], v[68:71]
	v_mfma_f32_16x16x32_bf16 v[124:127], v[148:151], v[202:205], v[124:127]
	v_mfma_f32_16x16x32_bf16 v[116:119], v[156:159], v[202:205], v[116:119]
	v_mfma_f32_16x16x32_bf16 v[108:111], v[148:151], v[210:213], v[108:111]
	v_mfma_f32_16x16x32_bf16 v[100:103], v[156:159], v[210:213], v[100:103]
	v_mfma_f32_16x16x32_bf16 v[92:95], v[148:151], v[228:231], v[92:95]
	v_mfma_f32_16x16x32_bf16 v[84:87], v[156:159], v[228:231], v[84:87]
	v_mfma_f32_16x16x32_bf16 v[76:79], v[148:151], v[236:239], v[76:79]
	v_mfma_f32_16x16x32_bf16 v[68:71], v[156:159], v[236:239], v[68:71]
	v_mfma_f32_16x16x32_bf16 v[120:123], v[160:163], v[198:201], v[120:123]
	v_mfma_f32_16x16x32_bf16 v[112:115], v[168:171], v[198:201], v[112:115]
	v_mfma_f32_16x16x32_bf16 v[104:107], v[160:163], v[206:209], v[104:107]
	v_mfma_f32_16x16x32_bf16 v[96:99], v[168:171], v[206:209], v[96:99]
	v_mfma_f32_16x16x32_bf16 v[88:91], v[160:163], v[224:227], v[88:91]
	v_mfma_f32_16x16x32_bf16 v[80:83], v[168:171], v[224:227], v[80:83]
	v_mfma_f32_16x16x32_bf16 v[72:75], v[160:163], v[232:235], v[72:75]
	v_mfma_f32_16x16x32_bf16 v[64:67], v[168:171], v[232:235], v[64:67]
	v_mfma_f32_16x16x32_bf16 v[120:123], v[164:167], v[202:205], v[120:123]
	v_mfma_f32_16x16x32_bf16 v[112:115], v[190:193], v[202:205], v[112:115]
	v_mfma_f32_16x16x32_bf16 v[104:107], v[164:167], v[210:213], v[104:107]
	v_mfma_f32_16x16x32_bf16 v[96:99], v[190:193], v[210:213], v[96:99]
	v_mfma_f32_16x16x32_bf16 v[88:91], v[164:167], v[228:231], v[88:91]
	v_mfma_f32_16x16x32_bf16 v[80:83], v[190:193], v[228:231], v[80:83]
	v_mfma_f32_16x16x32_bf16 v[72:75], v[164:167], v[236:239], v[72:75]
	v_mfma_f32_16x16x32_bf16 v[64:67], v[190:193], v[236:239], v[64:67]
	s_barrier
	ds_read_b128 v[198:201], v143 offset:16384
	ds_read_b128 v[202:205], v143 offset:17408
	ds_read_b128 v[206:209], v143 offset:18432
	ds_read_b128 v[210:213], v143 offset:19456
	ds_read_b128 v[224:227], v143 offset:20480
	ds_read_b128 v[228:231], v143 offset:21504
	ds_read_b128 v[232:235], v143 offset:22528
	ds_read_b128 v[236:239], v143 offset:23552
	s_add_i32 s55, s55, s69
	s_mov_b32 m0, s55
	s_nop 0
	global_load_lds_dwordx4 v172, s[22:23]
	s_add_i32 m0, s55, 0x2000
	s_add_u32 vcc_lo, s22, 0x80000
	s_addc_u32 vcc_hi, s23, 0
	s_add_i32 s55, s63, s69
	global_load_lds_dwordx4 v132, s[22:23]
	s_mov_b32 m0, s55
	s_nop 0
	global_load_lds_dwordx4 v172, vcc
	s_add_i32 m0, s55, 0x2000
	s_nop 0
	global_load_lds_dwordx4 v132, vcc
	s_mov_b32 m0, s37
	s_nop 0
	global_load_lds_dwordx4 v128, s[66:67]
	s_mov_b32 m0, s70
	s_nop 0
	global_load_lds_dwordx4 v130, s[66:67]
	s_waitcnt vmcnt(8) lgkmcnt(0)
	s_barrier
	v_mfma_f32_16x16x32_bf16 v[60:63], v[144:147], v[198:201], v[60:63]
	v_mfma_f32_16x16x32_bf16 v[52:55], v[152:155], v[198:201], v[52:55]
	v_mfma_f32_16x16x32_bf16 v[44:47], v[144:147], v[206:209], v[44:47]
	v_mfma_f32_16x16x32_bf16 v[36:39], v[152:155], v[206:209], v[36:39]
	v_mfma_f32_16x16x32_bf16 v[28:31], v[144:147], v[224:227], v[28:31]
	v_mfma_f32_16x16x32_bf16 v[20:23], v[152:155], v[224:227], v[20:23]
	v_mfma_f32_16x16x32_bf16 v[12:15], v[144:147], v[232:235], v[12:15]
	v_mfma_f32_16x16x32_bf16 v[4:7], v[152:155], v[232:235], v[4:7]
	v_mfma_f32_16x16x32_bf16 v[60:63], v[148:151], v[202:205], v[60:63]
	v_mfma_f32_16x16x32_bf16 v[52:55], v[156:159], v[202:205], v[52:55]
	v_mfma_f32_16x16x32_bf16 v[44:47], v[148:151], v[210:213], v[44:47]
	v_mfma_f32_16x16x32_bf16 v[36:39], v[156:159], v[210:213], v[36:39]
	v_mfma_f32_16x16x32_bf16 v[28:31], v[148:151], v[228:231], v[28:31]
	v_mfma_f32_16x16x32_bf16 v[20:23], v[156:159], v[228:231], v[20:23]
	v_mfma_f32_16x16x32_bf16 v[12:15], v[148:151], v[236:239], v[12:15]
	v_mfma_f32_16x16x32_bf16 v[4:7], v[156:159], v[236:239], v[4:7]
	v_mfma_f32_16x16x32_bf16 v[56:59], v[160:163], v[198:201], v[56:59]
	v_mfma_f32_16x16x32_bf16 v[48:51], v[168:171], v[198:201], v[48:51]
	v_mfma_f32_16x16x32_bf16 v[40:43], v[160:163], v[206:209], v[40:43]
	v_mfma_f32_16x16x32_bf16 v[32:35], v[168:171], v[206:209], v[32:35]
	v_mfma_f32_16x16x32_bf16 v[24:27], v[160:163], v[224:227], v[24:27]
	v_mfma_f32_16x16x32_bf16 v[16:19], v[168:171], v[224:227], v[16:19]
	v_mfma_f32_16x16x32_bf16 v[8:11], v[160:163], v[232:235], v[8:11]
	v_mfma_f32_16x16x32_bf16 v[0:3], v[168:171], v[232:235], v[0:3]
	v_mfma_f32_16x16x32_bf16 v[56:59], v[164:167], v[202:205], v[56:59]
	v_mfma_f32_16x16x32_bf16 v[48:51], v[190:193], v[202:205], v[48:51]
	v_mfma_f32_16x16x32_bf16 v[40:43], v[164:167], v[210:213], v[40:43]
	v_mfma_f32_16x16x32_bf16 v[32:35], v[190:193], v[210:213], v[32:35]
	v_mfma_f32_16x16x32_bf16 v[24:27], v[164:167], v[228:231], v[24:27]
	v_mfma_f32_16x16x32_bf16 v[16:19], v[190:193], v[228:231], v[16:19]
	v_mfma_f32_16x16x32_bf16 v[8:11], v[164:167], v[236:239], v[8:11]
	v_mfma_f32_16x16x32_bf16 v[0:3], v[190:193], v[236:239], v[0:3]
	s_barrier
; #define PG8_STAGE(bufoff, gbase, voff) do { _Pragma("unroll") for (int _i = 0; _i < 2; ++_i) \
;         __builtin_amdgcn_global_load_lds((const unsigned*)((const char*)(gbase) + (voff)[_i]), (PG8_LAS unsigned*)(lds + (bufoff) + ldsw + _i * 8192), 16, 0, 0); } while (0)
; #define PG8_LDA(dst, b, h) do { _Pragma("unroll") for (int m = 0; m < 4; ++m) _Pragma("unroll") for (int k = 0; k < 2; ++k) dst[m][k] = *(const PG8_LAS bf16x8*)(lds + PG8_SA(b, h) + aoff + m * 2048 + k * 1024); } while (0)
; #define PG8_LDB(dst, b, h) do { _Pragma("unroll") for (int n = 0; n < 2; ++n) _Pragma("unroll") for (int k = 0; k < 2; ++k) dst[n][k] = *(const PG8_LAS bf16x8*)(lds + PG8_SB(b, h) + boff + n * 2048 + k * 1024); } while (0)
; #define PG8_MMA(ai, bj, At, Bt) do { __builtin_amdgcn_s_setprio(1); _Pragma("unroll") for (int m = 0; m < 4; ++m) _Pragma("unroll") for (int n = 0; n < 2; ++n) _Pragma("unroll") for (int k = 0; k < 2; ++k) \
;         acc[ai][bj][m][n] = __builtin_amdgcn_mfma_f32_16x16x32_bf16(Bt[n][k], At[m][k], acc[ai][bj][m][n], 0, 0, 0); __builtin_amdgcn_s_setprio(0); } while (0)
; #define PG8_WAIT_V(n) asm volatile("s_waitcnt vmcnt(" #n ")" ::: "memory")
; #define PG8_WAIT_L(n) asm volatile("s_waitcnt lgkmcnt(" #n ")" ::: "memory")
; #define PG8_BAR __builtin_amdgcn_s_barrier()
; #define PG8_SCHED __builtin_amdgcn_sched_barrier(0)
; template <class Epi, class Sched, bool ALIGN_EPI = false, bool SP2 = false>
; __device__ __forceinline__ void gemm_phase(PG8_LAS unsigned char* lds, const Gemm g, const Sched& S, const Epi& E, const int tid_in) {
;     ...
;             PG8_LDB(B0, 1, 0); PG8_LDB(B1, 1, 1); PG8_SCHED; PG8_LDA(At, 1, 0); PG8_STAGE(PG8_SA(0, 1), a2 + hstepA, voffA);
;             PG8_WAIT_V(8); PG8_WAIT_L(0); PG8_BAR; PG8_MMA(0, 0, At, B0); PG8_MMA(0, 1, At, B1); PG8_BAR; PG8_SCHED;
;             PG8_LDA(At, 1, 1); PG8_STAGE(PG8_SB(1, 0), b3, voffB); PG8_STAGE(PG8_SB(1, 1), b3 + hstepB, voffB); PG8_STAGE(PG8_SA(1, 0), a3, voffA);
;             PG8_WAIT_V(8); PG8_WAIT_L(0); PG8_BAR; PG8_MMA(1, 0, At, B0); PG8_MMA(1, 1, At, B1); PG8_BAR; PG8_SCHED;
;     ...
;         if constexpr (ALIGN_EPI) { if (wr == 0) PG8_BAR; }
	ds_read_b128 v[144:147], v249 offset:32768
	ds_read_b128 v[148:151], v249 offset:33792
	ds_read_b128 v[152:155], v249 offset:34816
	ds_read_b128 v[156:159], v249 offset:35840
	ds_read_b128 v[160:163], v249 offset:49152
	ds_read_b128 v[164:167], v249 offset:50176
	ds_read_b128 v[168:171], v249 offset:51200
	ds_read_b128 v[190:193], v249 offset:52224
	ds_read_b128 v[198:201], v143 offset:32768
	ds_read_b128 v[202:205], v143 offset:33792
	ds_read_b128 v[206:209], v143 offset:34816
	ds_read_b128 v[210:213], v143 offset:35840
	ds_read_b128 v[224:227], v143 offset:36864
	ds_read_b128 v[228:231], v143 offset:37888
	ds_read_b128 v[232:235], v143 offset:38912
	ds_read_b128 v[236:239], v143 offset:39936
	s_add_i32 s55, 0, 0x18000
	s_add_i32 s63, 0, 0x1c000
	s_add_u32 s66, s66, 0x80000
	s_addc_u32 s67, s67, 0
	s_mov_b32 m0, s71
	s_nop 0
	global_load_lds_dwordx4 v128, s[66:67]
	s_mov_b32 m0, s72
	s_nop 0
	global_load_lds_dwordx4 v130, s[66:67]
	s_waitcnt vmcnt(8) lgkmcnt(0)
	s_barrier
	v_mfma_f32_16x16x32_bf16 v[124:127], v[144:147], v[198:201], v[124:127]
	v_mfma_f32_16x16x32_bf16 v[116:119], v[152:155], v[198:201], v[116:119]
	v_mfma_f32_16x16x32_bf16 v[108:111], v[144:147], v[206:209], v[108:111]
	v_mfma_f32_16x16x32_bf16 v[100:103], v[152:155], v[206:209], v[100:103]
	v_mfma_f32_16x16x32_bf16 v[92:95], v[144:147], v[224:227], v[92:95]
	v_mfma_f32_16x16x32_bf16 v[84:87], v[152:155], v[224:227], v[84:87]
	v_mfma_f32_16x16x32_bf16 v[76:79], v[144:147], v[232:235], v[76:79]
	v_mfma_f32_16x16x32_bf16 v[68:71], v[152:155], v[232:235], v[68:71]
	v_mfma_f32_16x16x32_bf16 v[124:127], v[148:151], v[202:205], v[124:127]
	v_mfma_f32_16x16x32_bf16 v[116:119], v[156:159], v[202:205], v[116:119]
	v_mfma_f32_16x16x32_bf16 v[108:111], v[148:151], v[210:213], v[108:111]
	v_mfma_f32_16x16x32_bf16 v[100:103], v[156:159], v[210:213], v[100:103]
	v_mfma_f32_16x16x32_bf16 v[92:95], v[148:151], v[228:231], v[92:95]
	v_mfma_f32_16x16x32_bf16 v[84:87], v[156:159], v[228:231], v[84:87]
	v_mfma_f32_16x16x32_bf16 v[76:79], v[148:151], v[236:239], v[76:79]
	v_mfma_f32_16x16x32_bf16 v[68:71], v[156:159], v[236:239], v[68:71]
	v_mfma_f32_16x16x32_bf16 v[120:123], v[160:163], v[198:201], v[120:123]
	v_mfma_f32_16x16x32_bf16 v[112:115], v[168:171], v[198:201], v[112:115]
	v_mfma_f32_16x16x32_bf16 v[104:107], v[160:163], v[206:209], v[104:107]
	v_mfma_f32_16x16x32_bf16 v[96:99], v[168:171], v[206:209], v[96:99]
	v_mfma_f32_16x16x32_bf16 v[88:91], v[160:163], v[224:227], v[88:91]
	v_mfma_f32_16x16x32_bf16 v[80:83], v[168:171], v[224:227], v[80:83]
	v_mfma_f32_16x16x32_bf16 v[72:75], v[160:163], v[232:235], v[72:75]
	v_mfma_f32_16x16x32_bf16 v[64:67], v[168:171], v[232:235], v[64:67]
	v_mfma_f32_16x16x32_bf16 v[120:123], v[164:167], v[202:205], v[120:123]
	v_mfma_f32_16x16x32_bf16 v[112:115], v[190:193], v[202:205], v[112:115]
	v_mfma_f32_16x16x32_bf16 v[104:107], v[164:167], v[210:213], v[104:107]
	v_mfma_f32_16x16x32_bf16 v[96:99], v[190:193], v[210:213], v[96:99]
	v_mfma_f32_16x16x32_bf16 v[88:91], v[164:167], v[228:231], v[88:91]
	v_mfma_f32_16x16x32_bf16 v[80:83], v[190:193], v[228:231], v[80:83]
	v_mfma_f32_16x16x32_bf16 v[72:75], v[164:167], v[236:239], v[72:75]
	v_mfma_f32_16x16x32_bf16 v[64:67], v[190:193], v[236:239], v[64:67]
	s_barrier
	ds_read_b128 v[198:201], v143 offset:49152
	ds_read_b128 v[202:205], v143 offset:50176
	ds_read_b128 v[206:209], v143 offset:51200
	ds_read_b128 v[210:213], v143 offset:52224
	ds_read_b128 v[224:227], v143 offset:53248
	ds_read_b128 v[228:231], v143 offset:54272
	ds_read_b128 v[232:235], v143 offset:55296
	ds_read_b128 v[236:239], v143 offset:56320
	s_add_i32 s55, s55, s69
	s_mov_b32 m0, s55
	s_add_u32 s100, s22, 0x80
	s_addc_u32 s101, s23, 0
	global_load_lds_dwordx4 v172, s[100:101]
	s_add_i32 m0, s55, 0x2000
	s_add_u32 s22, s22, 0x80080
	s_addc_u32 s23, s23, 0
	s_add_i32 s55, s63, s69
	global_load_lds_dwordx4 v132, s[100:101]
	s_mov_b32 m0, s55
	s_nop 0
	global_load_lds_dwordx4 v172, s[22:23]
	s_add_i32 m0, s55, 0x2000
	s_nop 0
	global_load_lds_dwordx4 v132, s[22:23]
	s_mov_b32 m0, s73
	s_nop 0
	s_add_u32 s100, s66, 0xfff80080
	s_addc_u32 s101, s67, -1
	global_load_lds_dwordx4 v128, s[100:101]
	s_mov_b32 m0, s74
	s_nop 0
	global_load_lds_dwordx4 v130, s[100:101]
	s_waitcnt vmcnt(8) lgkmcnt(0)
	s_barrier
	v_mfma_f32_16x16x32_bf16 v[60:63], v[144:147], v[198:201], v[60:63]
	v_mfma_f32_16x16x32_bf16 v[52:55], v[152:155], v[198:201], v[52:55]
	v_mfma_f32_16x16x32_bf16 v[44:47], v[144:147], v[206:209], v[44:47]
	v_mfma_f32_16x16x32_bf16 v[36:39], v[152:155], v[206:209], v[36:39]
	v_mfma_f32_16x16x32_bf16 v[28:31], v[144:147], v[224:227], v[28:31]
	v_mfma_f32_16x16x32_bf16 v[20:23], v[152:155], v[224:227], v[20:23]
	v_mfma_f32_16x16x32_bf16 v[12:15], v[144:147], v[232:235], v[12:15]
	v_mfma_f32_16x16x32_bf16 v[4:7], v[152:155], v[232:235], v[4:7]
	v_mfma_f32_16x16x32_bf16 v[60:63], v[148:151], v[202:205], v[60:63]
	v_mfma_f32_16x16x32_bf16 v[52:55], v[156:159], v[202:205], v[52:55]
	v_mfma_f32_16x16x32_bf16 v[44:47], v[148:151], v[210:213], v[44:47]
	v_mfma_f32_16x16x32_bf16 v[36:39], v[156:159], v[210:213], v[36:39]
	v_mfma_f32_16x16x32_bf16 v[28:31], v[148:151], v[228:231], v[28:31]
	v_mfma_f32_16x16x32_bf16 v[20:23], v[156:159], v[228:231], v[20:23]
	v_mfma_f32_16x16x32_bf16 v[12:15], v[148:151], v[236:239], v[12:15]
	v_mfma_f32_16x16x32_bf16 v[4:7], v[156:159], v[236:239], v[4:7]
	v_mfma_f32_16x16x32_bf16 v[56:59], v[160:163], v[198:201], v[56:59]
	v_mfma_f32_16x16x32_bf16 v[48:51], v[168:171], v[198:201], v[48:51]
	v_mfma_f32_16x16x32_bf16 v[40:43], v[160:163], v[206:209], v[40:43]
	v_mfma_f32_16x16x32_bf16 v[32:35], v[168:171], v[206:209], v[32:35]
	v_mfma_f32_16x16x32_bf16 v[24:27], v[160:163], v[224:227], v[24:27]
	v_mfma_f32_16x16x32_bf16 v[16:19], v[168:171], v[224:227], v[16:19]
	v_mfma_f32_16x16x32_bf16 v[8:11], v[160:163], v[232:235], v[8:11]
	v_mfma_f32_16x16x32_bf16 v[0:3], v[168:171], v[232:235], v[0:3]
	v_mfma_f32_16x16x32_bf16 v[56:59], v[164:167], v[202:205], v[56:59]
	v_mfma_f32_16x16x32_bf16 v[48:51], v[190:193], v[202:205], v[48:51]
	v_mfma_f32_16x16x32_bf16 v[40:43], v[164:167], v[210:213], v[40:43]
	v_mfma_f32_16x16x32_bf16 v[32:35], v[190:193], v[210:213], v[32:35]
	v_mfma_f32_16x16x32_bf16 v[24:27], v[164:167], v[228:231], v[24:27]
	v_mfma_f32_16x16x32_bf16 v[16:19], v[190:193], v[228:231], v[16:19]
	v_mfma_f32_16x16x32_bf16 v[8:11], v[164:167], v[236:239], v[8:11]
	v_mfma_f32_16x16x32_bf16 v[0:3], v[190:193], v[236:239], v[0:3]
	s_barrier
	s_add_i32 s51, s51, 2
	s_add_u32 s64, s64, 0x100
	s_addc_u32 s65, s65, 0
	s_add_u32 s34, s34, 0x100
	s_addc_u32 s35, s35, 0
	s_cmp_gt_u32 s51, 29
	s_cbranch_scc0 .LBB0_2312
	s_and_b64 vcc, exec, s[48:49]
	s_cbranch_vccz .LBB0_2315
	s_barrier

;     __device__ __forceinline__ void a_ready(const Unit& u) const { wait_panel(cnt, u.pm, need, tmo, wave); }
;     __device__ __forceinline__ void a_ready(const Unit& u) const { wait_panel(cnt, u.pm, need, tmo, wave); }
; #define PG8_STAGE(bufoff, gbase, voff) do { _Pragma("unroll") for (int _i = 0; _i < 2; ++_i) \
;         __builtin_amdgcn_global_load_lds((const unsigned*)((const char*)(gbase) + (voff)[_i]), (PG8_LAS unsigned*)(lds + (bufoff) + ldsw + _i * 8192), 16, 0, 0); } while (0)
; #define PG8_LDA(dst, b, h) do { _Pragma("unroll") for (int m = 0; m < 4; ++m) _Pragma("unroll") for (int k = 0; k < 2; ++k) dst[m][k] = *(const PG8_LAS bf16x8*)(lds + PG8_SA(b, h) + aoff + m * 2048 + k * 1024); } while (0)
; #define PG8_LDB(dst, b, h) do { _Pragma("unroll") for (int n = 0; n < 2; ++n) _Pragma("unroll") for (int k = 0; k < 2; ++k) dst[n][k] = *(const PG8_LAS bf16x8*)(lds + PG8_SB(b, h) + boff + n * 2048 + k * 1024); } while (0)
; #define PG8_WAIT_V(n) asm volatile("s_waitcnt vmcnt(" #n ")" ::: "memory")
; #define PG8_WAIT_L(n) asm volatile("s_waitcnt lgkmcnt(" #n ")" ::: "memory")
; #define PG8_BAR __builtin_amdgcn_s_barrier()
; #define PG8_SCHED __builtin_amdgcn_sched_barrier(0)
; template <class Epi, class Sched, bool ALIGN_EPI = false, bool SP2 = false>
; __device__ __forceinline__ void gemm_phase(PG8_LAS unsigned char* lds, const Gemm g, const Sched& S, const Epi& E, const int tid_in) {
;     ...
;             const bool last = (t == nt - 2);
;             const char* a1 = cA + (size_t)(t + 1) * kstep;
;             const char* a2 = last ? nA : cA + (size_t)(t + 2) * kstep; const char* b2 = last ? nB : cB + (size_t)(t + 2) * kstep;
;             const char* a3 = a2 + kstep; const char* b3 = b2 + kstep;
;             if (last && has_next) S.a_ready(nxt);
;             if constexpr (SP2) {
;             PG8_LDB(B0, 0, 0); PG8_LDB(B1, 0, 1); PG8_SCHED; PG8_LDA(At, 0, 0); PG8_STAGE(PG8_SA(1, 1), a1 + hstepA, voffA);
;             PG8_WAIT_V(8); PG8_WAIT_L(0); PG8_BAR; PG8_MMA(0, 0, At, B0); PG8_MMA(0, 1, At, B1); PG8_BAR; PG8_SCHED;
;             PG8_LDA(At, 0, 1); PG8_STAGE(PG8_SB(0, 0), b2, voffB); PG8_STAGE(PG8_SB(0, 1), b2 + hstepB, voffB); PG8_STAGE(PG8_SA(0, 0), a2, voffA);
;             PG8_WAIT_V(8); PG8_WAIT_L(0); PG8_BAR; PG8_MMA(1, 0, At, B0); PG8_MMA(1, 1, At, B1); PG8_BAR; PG8_SCHED;
.LBB0_2372:
	ds_read_b128 v[128:131], v249
	ds_read_b128 v[132:135], v249 offset:1024
	ds_read_b128 v[136:139], v249 offset:2048
	ds_read_b128 v[140:143], v249 offset:3072
	ds_read_b128 v[144:147], v249 offset:16384
	ds_read_b128 v[154:157], v249 offset:17408
	ds_read_b128 v[158:161], v249 offset:18432
	ds_read_b128 v[162:165], v249 offset:19456
	ds_read_b128 v[166:169], v200
	ds_read_b128 v[190:193], v200 offset:1024
	ds_read_b128 v[202:205], v200 offset:2048
	ds_read_b128 v[206:209], v200 offset:3072
	ds_read_b128 v[210:213], v200 offset:4096
	ds_read_b128 v[224:227], v200 offset:5120
	ds_read_b128 v[228:231], v200 offset:6144
	ds_read_b128 v[232:235], v200 offset:7168
	s_lshl_b32 s72, s85, 7
	s_add_u32 s73, s62, s72
	s_addc_u32 s74, s63, 0
	s_add_u32 s75, s73, 0x100
	s_addc_u32 s76, s74, 0
	s_and_b64 s[70:71], s[22:23], exec
	s_cselect_b32 s71, s59, s76
	s_cselect_b32 s70, s58, s75
	s_add_u32 s72, s64, s72
	s_addc_u32 s75, s65, 0
	s_add_u32 s72, s72, 0x100
	s_addc_u32 s75, s75, 0
	s_and_b64 s[22:23], s[22:23], exec
	s_cselect_b32 s23, s61, s75
	s_cselect_b32 s22, s60, s72
	s_add_i32 s75, 0, 0x10000
	s_add_i32 s76, 0, 0x14000
	s_add_u32 s72, s73, 0x150080
	s_addc_u32 s73, s74, 0
	s_add_i32 m0, s21, 0xc000
	s_nop 0
	global_load_lds_dwordx4 v148, s[72:73]
	s_add_i32 m0, s21, 0xe000
	s_nop 0
	global_load_lds_dwordx4 v150, s[72:73]
	s_waitcnt vmcnt(8) lgkmcnt(0)
	s_barrier
	v_mfma_f32_16x16x32_bf16 v[124:127], v[128:131], v[166:169], v[124:127]
	v_mfma_f32_16x16x32_bf16 v[120:123], v[136:139], v[166:169], v[120:123]
	v_mfma_f32_16x16x32_bf16 v[108:111], v[128:131], v[202:205], v[108:111]
	v_mfma_f32_16x16x32_bf16 v[104:107], v[136:139], v[202:205], v[104:107]
	v_mfma_f32_16x16x32_bf16 v[92:95], v[128:131], v[210:213], v[92:95]
	v_mfma_f32_16x16x32_bf16 v[88:91], v[136:139], v[210:213], v[88:91]
	v_mfma_f32_16x16x32_bf16 v[76:79], v[128:131], v[228:231], v[76:79]
	v_mfma_f32_16x16x32_bf16 v[72:75], v[136:139], v[228:231], v[72:75]
	v_mfma_f32_16x16x32_bf16 v[124:127], v[132:135], v[190:193], v[124:127]
	v_mfma_f32_16x16x32_bf16 v[120:123], v[140:143], v[190:193], v[120:123]
	v_mfma_f32_16x16x32_bf16 v[108:111], v[132:135], v[206:209], v[108:111]
	v_mfma_f32_16x16x32_bf16 v[104:107], v[140:143], v[206:209], v[104:107]
	v_mfma_f32_16x16x32_bf16 v[92:95], v[132:135], v[224:227], v[92:95]
	v_mfma_f32_16x16x32_bf16 v[88:91], v[140:143], v[224:227], v[88:91]
	v_mfma_f32_16x16x32_bf16 v[76:79], v[132:135], v[232:235], v[76:79]
	v_mfma_f32_16x16x32_bf16 v[72:75], v[140:143], v[232:235], v[72:75]
	v_mfma_f32_16x16x32_bf16 v[116:119], v[144:147], v[166:169], v[116:119]
	v_mfma_f32_16x16x32_bf16 v[112:115], v[158:161], v[166:169], v[112:115]
	v_mfma_f32_16x16x32_bf16 v[100:103], v[144:147], v[202:205], v[100:103]
	v_mfma_f32_16x16x32_bf16 v[96:99], v[158:161], v[202:205], v[96:99]
	v_mfma_f32_16x16x32_bf16 v[84:87], v[144:147], v[210:213], v[84:87]
	v_mfma_f32_16x16x32_bf16 v[80:83], v[158:161], v[210:213], v[80:83]
	v_mfma_f32_16x16x32_bf16 v[68:71], v[144:147], v[228:231], v[68:71]
	v_mfma_f32_16x16x32_bf16 v[64:67], v[158:161], v[228:231], v[64:67]
	v_mfma_f32_16x16x32_bf16 v[116:119], v[154:157], v[190:193], v[116:119]
	v_mfma_f32_16x16x32_bf16 v[112:115], v[162:165], v[190:193], v[112:115]
	v_mfma_f32_16x16x32_bf16 v[100:103], v[154:157], v[206:209], v[100:103]
	v_mfma_f32_16x16x32_bf16 v[96:99], v[162:165], v[206:209], v[96:99]
	v_mfma_f32_16x16x32_bf16 v[84:87], v[154:157], v[224:227], v[84:87]
	v_mfma_f32_16x16x32_bf16 v[80:83], v[162:165], v[224:227], v[80:83]
	v_mfma_f32_16x16x32_bf16 v[68:71], v[154:157], v[232:235], v[68:71]
	v_mfma_f32_16x16x32_bf16 v[64:67], v[162:165], v[232:235], v[64:67]
	s_barrier
	ds_read_b128 v[166:169], v200 offset:16384
	ds_read_b128 v[190:193], v200 offset:17408
	ds_read_b128 v[202:205], v200 offset:18432
	ds_read_b128 v[206:209], v200 offset:19456
	ds_read_b128 v[210:213], v200 offset:20480
	ds_read_b128 v[224:227], v200 offset:21504
	ds_read_b128 v[228:231], v200 offset:22528
	ds_read_b128 v[232:235], v200 offset:23552
	s_add_i32 s72, s75, s20
	s_mov_b32 m0, s72
	s_nop 0
	global_load_lds_dwordx4 v172, s[22:23]
	s_add_i32 m0, s72, 0x2000
	s_add_u32 s72, s22, 0x150000
	s_addc_u32 s73, s23, 0
	s_add_i32 s74, s76, s20
	global_load_lds_dwordx4 v152, s[22:23]
	s_mov_b32 m0, s74
	s_nop 0
	global_load_lds_dwordx4 v172, s[72:73]
	s_add_i32 m0, s74, 0x2000
	s_nop 0
	global_load_lds_dwordx4 v152, s[72:73]
	s_add_u32 vcc_lo, s70, 0x80
	s_addc_u32 vcc_hi, s71, 0
	s_mov_b32 m0, s21
	s_nop 0
	global_load_lds_dwordx4 v148, s[70:71]
	s_mov_b32 m0, s6
	s_nop 0
	global_load_lds_dwordx4 v150, s[70:71]
	s_waitcnt vmcnt(8) lgkmcnt(0)
	s_barrier
; #define PG8_STAGE(bufoff, gbase, voff) do { _Pragma("unroll") for (int _i = 0; _i < 2; ++_i) \
;         __builtin_amdgcn_global_load_lds((const unsigned*)((const char*)(gbase) + (voff)[_i]), (PG8_LAS unsigned*)(lds + (bufoff) + ldsw + _i * 8192), 16, 0, 0); } while (0)
; #define PG8_LDA(dst, b, h) do { _Pragma("unroll") for (int m = 0; m < 4; ++m) _Pragma("unroll") for (int k = 0; k < 2; ++k) dst[m][k] = *(const PG8_LAS bf16x8*)(lds + PG8_SA(b, h) + aoff + m * 2048 + k * 1024); } while (0)
; #define PG8_LDB(dst, b, h) do { _Pragma("unroll") for (int n = 0; n < 2; ++n) _Pragma("unroll") for (int k = 0; k < 2; ++k) dst[n][k] = *(const PG8_LAS bf16x8*)(lds + PG8_SB(b, h) + boff + n * 2048 + k * 1024); } while (0)
; #define PG8_MMA(ai, bj, At, Bt) do { __builtin_amdgcn_s_setprio(1); _Pragma("unroll") for (int m = 0; m < 4; ++m) _Pragma("unroll") for (int n = 0; n < 2; ++n) _Pragma("unroll") for (int k = 0; k < 2; ++k) \
;         acc[ai][bj][m][n] = __builtin_amdgcn_mfma_f32_16x16x32_bf16(Bt[n][k], At[m][k], acc[ai][bj][m][n], 0, 0, 0); __builtin_amdgcn_s_setprio(0); } while (0)
; #define PG8_WAIT_V(n) asm volatile("s_waitcnt vmcnt(" #n ")" ::: "memory")
; #define PG8_WAIT_L(n) asm volatile("s_waitcnt lgkmcnt(" #n ")" ::: "memory")
; #define PG8_BAR __builtin_amdgcn_s_barrier()
; #define PG8_SCHED __builtin_amdgcn_sched_barrier(0)
; template <class Epi, class Sched, bool ALIGN_EPI = false, bool SP2 = false>
; __device__ __forceinline__ void gemm_phase(PG8_LAS unsigned char* lds, const Gemm g, const Sched& S, const Epi& E, const int tid_in) {
;     ...
;             PG8_WAIT_V(8); PG8_WAIT_L(0); PG8_BAR; PG8_MMA(1, 0, At, B0); PG8_MMA(1, 1, At, B1); PG8_BAR; PG8_SCHED;
;             PG8_LDB(B0, 1, 0); PG8_LDB(B1, 1, 1); PG8_SCHED; PG8_LDA(At, 1, 0); PG8_STAGE(PG8_SA(0, 1), a2 + hstepA, voffA);
;             PG8_WAIT_V(8); PG8_WAIT_L(0); PG8_BAR; PG8_MMA(0, 0, At, B0); PG8_MMA(0, 1, At, B1); PG8_BAR; PG8_SCHED;
	v_mfma_f32_16x16x32_bf16 v[60:63], v[128:131], v[166:169], v[60:63]
	v_mfma_f32_16x16x32_bf16 v[56:59], v[136:139], v[166:169], v[56:59]
	v_mfma_f32_16x16x32_bf16 v[44:47], v[128:131], v[202:205], v[44:47]
	v_mfma_f32_16x16x32_bf16 v[40:43], v[136:139], v[202:205], v[40:43]
	v_mfma_f32_16x16x32_bf16 v[28:31], v[128:131], v[210:213], v[28:31]
	v_mfma_f32_16x16x32_bf16 v[24:27], v[136:139], v[210:213], v[24:27]
	v_mfma_f32_16x16x32_bf16 v[12:15], v[128:131], v[228:231], v[12:15]
	v_mfma_f32_16x16x32_bf16 v[8:11], v[136:139], v[228:231], v[8:11]
	v_mfma_f32_16x16x32_bf16 v[60:63], v[132:135], v[190:193], v[60:63]
	v_mfma_f32_16x16x32_bf16 v[56:59], v[140:143], v[190:193], v[56:59]
	v_mfma_f32_16x16x32_bf16 v[44:47], v[132:135], v[206:209], v[44:47]
	v_mfma_f32_16x16x32_bf16 v[40:43], v[140:143], v[206:209], v[40:43]
	v_mfma_f32_16x16x32_bf16 v[28:31], v[132:135], v[224:227], v[28:31]
	v_mfma_f32_16x16x32_bf16 v[24:27], v[140:143], v[224:227], v[24:27]
	v_mfma_f32_16x16x32_bf16 v[12:15], v[132:135], v[232:235], v[12:15]
	v_mfma_f32_16x16x32_bf16 v[8:11], v[140:143], v[232:235], v[8:11]
	v_mfma_f32_16x16x32_bf16 v[52:55], v[144:147], v[166:169], v[52:55]
	v_mfma_f32_16x16x32_bf16 v[48:51], v[158:161], v[166:169], v[48:51]
	v_mfma_f32_16x16x32_bf16 v[36:39], v[144:147], v[202:205], v[36:39]
	v_mfma_f32_16x16x32_bf16 v[32:35], v[158:161], v[202:205], v[32:35]
	v_mfma_f32_16x16x32_bf16 v[20:23], v[144:147], v[210:213], v[20:23]
	v_mfma_f32_16x16x32_bf16 v[16:19], v[158:161], v[210:213], v[16:19]
	v_mfma_f32_16x16x32_bf16 v[4:7], v[144:147], v[228:231], v[4:7]
	v_mfma_f32_16x16x32_bf16 v[0:3], v[158:161], v[228:231], v[0:3]
	v_mfma_f32_16x16x32_bf16 v[52:55], v[154:157], v[190:193], v[52:55]
	v_mfma_f32_16x16x32_bf16 v[48:51], v[162:165], v[190:193], v[48:51]
	v_mfma_f32_16x16x32_bf16 v[36:39], v[154:157], v[206:209], v[36:39]
	v_mfma_f32_16x16x32_bf16 v[32:35], v[162:165], v[206:209], v[32:35]
	v_mfma_f32_16x16x32_bf16 v[20:23], v[154:157], v[224:227], v[20:23]
	v_mfma_f32_16x16x32_bf16 v[16:19], v[162:165], v[224:227], v[16:19]
	v_mfma_f32_16x16x32_bf16 v[4:7], v[154:157], v[232:235], v[4:7]
	v_mfma_f32_16x16x32_bf16 v[0:3], v[162:165], v[232:235], v[0:3]
	s_barrier
	ds_read_b128 v[128:131], v249 offset:32768
	ds_read_b128 v[132:135], v249 offset:33792
	ds_read_b128 v[136:139], v249 offset:34816
	ds_read_b128 v[140:143], v249 offset:35840
	ds_read_b128 v[144:147], v249 offset:49152
	ds_read_b128 v[154:157], v249 offset:50176
	ds_read_b128 v[158:161], v249 offset:51200
	ds_read_b128 v[162:165], v249 offset:52224
	ds_read_b128 v[166:169], v200 offset:32768
	ds_read_b128 v[190:193], v200 offset:33792
	ds_read_b128 v[202:205], v200 offset:34816
	ds_read_b128 v[206:209], v200 offset:35840
	ds_read_b128 v[210:213], v200 offset:36864
	ds_read_b128 v[224:227], v200 offset:37888
	ds_read_b128 v[228:231], v200 offset:38912
	ds_read_b128 v[232:235], v200 offset:39936
	s_add_i32 s72, 0, 0x18000
	s_add_i32 s73, 0, 0x1c000
	s_add_u32 s70, s70, 0x150000
	s_addc_u32 s71, s71, 0
	s_mov_b32 m0, s34
	s_nop 0
	global_load_lds_dwordx4 v148, s[70:71]
	s_mov_b32 m0, s35
	s_nop 0
	global_load_lds_dwordx4 v150, s[70:71]
	s_waitcnt vmcnt(8) lgkmcnt(0)
	s_barrier
	v_mfma_f32_16x16x32_bf16 v[124:127], v[128:131], v[166:169], v[124:127]
	v_mfma_f32_16x16x32_bf16 v[120:123], v[136:139], v[166:169], v[120:123]
	v_mfma_f32_16x16x32_bf16 v[108:111], v[128:131], v[202:205], v[108:111]
	v_mfma_f32_16x16x32_bf16 v[104:107], v[136:139], v[202:205], v[104:107]
	v_mfma_f32_16x16x32_bf16 v[92:95], v[128:131], v[210:213], v[92:95]
	v_mfma_f32_16x16x32_bf16 v[88:91], v[136:139], v[210:213], v[88:91]
	v_mfma_f32_16x16x32_bf16 v[76:79], v[128:131], v[228:231], v[76:79]
	v_mfma_f32_16x16x32_bf16 v[72:75], v[136:139], v[228:231], v[72:75]
	v_mfma_f32_16x16x32_bf16 v[124:127], v[132:135], v[190:193], v[124:127]
	v_mfma_f32_16x16x32_bf16 v[120:123], v[140:143], v[190:193], v[120:123]
	v_mfma_f32_16x16x32_bf16 v[108:111], v[132:135], v[206:209], v[108:111]
	v_mfma_f32_16x16x32_bf16 v[104:107], v[140:143], v[206:209], v[104:107]
	v_mfma_f32_16x16x32_bf16 v[92:95], v[132:135], v[224:227], v[92:95]
	v_mfma_f32_16x16x32_bf16 v[88:91], v[140:143], v[224:227], v[88:91]
	v_mfma_f32_16x16x32_bf16 v[76:79], v[132:135], v[232:235], v[76:79]
	v_mfma_f32_16x16x32_bf16 v[72:75], v[140:143], v[232:235], v[72:75]
	v_mfma_f32_16x16x32_bf16 v[116:119], v[144:147], v[166:169], v[116:119]
	v_mfma_f32_16x16x32_bf16 v[112:115], v[158:161], v[166:169], v[112:115]
	v_mfma_f32_16x16x32_bf16 v[100:103], v[144:147], v[202:205], v[100:103]
	v_mfma_f32_16x16x32_bf16 v[96:99], v[158:161], v[202:205], v[96:99]
	v_mfma_f32_16x16x32_bf16 v[84:87], v[144:147], v[210:213], v[84:87]
	v_mfma_f32_16x16x32_bf16 v[80:83], v[158:161], v[210:213], v[80:83]
	v_mfma_f32_16x16x32_bf16 v[68:71], v[144:147], v[228:231], v[68:71]
	v_mfma_f32_16x16x32_bf16 v[64:67], v[158:161], v[228:231], v[64:67]
	v_mfma_f32_16x16x32_bf16 v[116:119], v[154:157], v[190:193], v[116:119]
	v_mfma_f32_16x16x32_bf16 v[112:115], v[162:165], v[190:193], v[112:115]
	v_mfma_f32_16x16x32_bf16 v[100:103], v[154:157], v[206:209], v[100:103]
	v_mfma_f32_16x16x32_bf16 v[96:99], v[162:165], v[206:209], v[96:99]
	v_mfma_f32_16x16x32_bf16 v[84:87], v[154:157], v[224:227], v[84:87]
	v_mfma_f32_16x16x32_bf16 v[80:83], v[162:165], v[224:227], v[80:83]
	v_mfma_f32_16x16x32_bf16 v[68:71], v[154:157], v[232:235], v[68:71]
	v_mfma_f32_16x16x32_bf16 v[64:67], v[162:165], v[232:235], v[64:67]
	s_barrier
; #define PG8_STAGE(bufoff, gbase, voff) do { _Pragma("unroll") for (int _i = 0; _i < 2; ++_i) \
;         __builtin_amdgcn_global_load_lds((const unsigned*)((const char*)(gbase) + (voff)[_i]), (PG8_LAS unsigned*)(lds + (bufoff) + ldsw + _i * 8192), 16, 0, 0); } while (0)
; #define PG8_LDA(dst, b, h) do { _Pragma("unroll") for (int m = 0; m < 4; ++m) _Pragma("unroll") for (int k = 0; k < 2; ++k) dst[m][k] = *(const PG8_LAS bf16x8*)(lds + PG8_SA(b, h) + aoff + m * 2048 + k * 1024); } while (0)
; #define PG8_MMA(ai, bj, At, Bt) do { __builtin_amdgcn_s_setprio(1); _Pragma("unroll") for (int m = 0; m < 4; ++m) _Pragma("unroll") for (int n = 0; n < 2; ++n) _Pragma("unroll") for (int k = 0; k < 2; ++k) \
;         acc[ai][bj][m][n] = __builtin_amdgcn_mfma_f32_16x16x32_bf16(Bt[n][k], At[m][k], acc[ai][bj][m][n], 0, 0, 0); __builtin_amdgcn_s_setprio(0); } while (0)
; #define PG8_WAIT_V(n) asm volatile("s_waitcnt vmcnt(" #n ")" ::: "memory")
; #define PG8_WAIT_L(n) asm volatile("s_waitcnt lgkmcnt(" #n ")" ::: "memory")
; #define PG8_BAR __builtin_amdgcn_s_barrier()
; #define PG8_SCHED __builtin_amdgcn_sched_barrier(0)
; template <class Epi, class Sched, bool ALIGN_EPI = false, bool SP2 = false>
; __device__ __forceinline__ void gemm_phase(PG8_LAS unsigned char* lds, const Gemm g, const Sched& S, const Epi& E, const int tid_in) {
;     ...
;         for (int t = 0; t < nt; t += 2) {
;     ...
;             PG8_LDA(At, 1, 1); PG8_STAGE(PG8_SB(1, 0), b3, voffB); PG8_STAGE(PG8_SB(1, 1), b3 + hstepB, voffB); PG8_STAGE(PG8_SA(1, 0), a3, voffA);
;             PG8_WAIT_V(8); PG8_WAIT_L(0); PG8_BAR; PG8_MMA(1, 0, At, B0); PG8_MMA(1, 1, At, B1); PG8_BAR; PG8_SCHED;
	ds_read_b128 v[166:169], v200 offset:49152
	ds_read_b128 v[190:193], v200 offset:50176
	ds_read_b128 v[202:205], v200 offset:51200
	ds_read_b128 v[206:209], v200 offset:52224
	ds_read_b128 v[210:213], v200 offset:53248
	ds_read_b128 v[224:227], v200 offset:54272
	ds_read_b128 v[228:231], v200 offset:55296
	ds_read_b128 v[232:235], v200 offset:56320
	s_add_i32 s70, s72, s20
	s_mov_b32 m0, s70
	s_add_u32 s100, s22, 0x80
	s_addc_u32 s101, s23, 0
	global_load_lds_dwordx4 v172, s[100:101]
	s_add_i32 m0, s70, 0x2000
	s_add_u32 s22, s22, 0x150080
	s_addc_u32 s23, s23, 0
	s_add_i32 s70, s73, s20
	global_load_lds_dwordx4 v152, s[100:101]
	s_mov_b32 m0, s70
	s_nop 0
	global_load_lds_dwordx4 v172, s[22:23]
	s_add_i32 m0, s70, 0x2000
	s_nop 0
	global_load_lds_dwordx4 v152, s[22:23]
	s_mov_b32 m0, s93
	s_nop 0
	global_load_lds_dwordx4 v148, vcc
	s_mov_b32 m0, s94
	s_nop 0
	global_load_lds_dwordx4 v150, vcc
	s_waitcnt vmcnt(8) lgkmcnt(0)
	s_barrier
	v_mfma_f32_16x16x32_bf16 v[60:63], v[128:131], v[166:169], v[60:63]
	v_mfma_f32_16x16x32_bf16 v[56:59], v[136:139], v[166:169], v[56:59]
	v_mfma_f32_16x16x32_bf16 v[44:47], v[128:131], v[202:205], v[44:47]
	v_mfma_f32_16x16x32_bf16 v[40:43], v[136:139], v[202:205], v[40:43]
	v_mfma_f32_16x16x32_bf16 v[28:31], v[128:131], v[210:213], v[28:31]
	v_mfma_f32_16x16x32_bf16 v[24:27], v[136:139], v[210:213], v[24:27]
	v_mfma_f32_16x16x32_bf16 v[12:15], v[128:131], v[228:231], v[12:15]
	v_mfma_f32_16x16x32_bf16 v[8:11], v[136:139], v[228:231], v[8:11]
	v_mfma_f32_16x16x32_bf16 v[60:63], v[132:135], v[190:193], v[60:63]
	v_mfma_f32_16x16x32_bf16 v[56:59], v[140:143], v[190:193], v[56:59]
	v_mfma_f32_16x16x32_bf16 v[44:47], v[132:135], v[206:209], v[44:47]
	v_mfma_f32_16x16x32_bf16 v[40:43], v[140:143], v[206:209], v[40:43]
	v_mfma_f32_16x16x32_bf16 v[28:31], v[132:135], v[224:227], v[28:31]
	v_mfma_f32_16x16x32_bf16 v[24:27], v[140:143], v[224:227], v[24:27]
	v_mfma_f32_16x16x32_bf16 v[12:15], v[132:135], v[232:235], v[12:15]
	v_mfma_f32_16x16x32_bf16 v[8:11], v[140:143], v[232:235], v[8:11]
	v_mfma_f32_16x16x32_bf16 v[52:55], v[144:147], v[166:169], v[52:55]
	v_mfma_f32_16x16x32_bf16 v[48:51], v[158:161], v[166:169], v[48:51]
	v_mfma_f32_16x16x32_bf16 v[36:39], v[144:147], v[202:205], v[36:39]
	v_mfma_f32_16x16x32_bf16 v[32:35], v[158:161], v[202:205], v[32:35]
	v_mfma_f32_16x16x32_bf16 v[20:23], v[144:147], v[210:213], v[20:23]
	v_mfma_f32_16x16x32_bf16 v[16:19], v[158:161], v[210:213], v[16:19]
	v_mfma_f32_16x16x32_bf16 v[4:7], v[144:147], v[228:231], v[4:7]
	v_mfma_f32_16x16x32_bf16 v[0:3], v[158:161], v[228:231], v[0:3]
	v_mfma_f32_16x16x32_bf16 v[52:55], v[154:157], v[190:193], v[52:55]
	v_mfma_f32_16x16x32_bf16 v[48:51], v[162:165], v[190:193], v[48:51]
	v_mfma_f32_16x16x32_bf16 v[36:39], v[154:157], v[206:209], v[36:39]
	v_mfma_f32_16x16x32_bf16 v[32:35], v[162:165], v[206:209], v[32:35]
	v_mfma_f32_16x16x32_bf16 v[20:23], v[154:157], v[224:227], v[20:23]
	v_mfma_f32_16x16x32_bf16 v[16:19], v[162:165], v[224:227], v[16:19]
	v_mfma_f32_16x16x32_bf16 v[4:7], v[154:157], v[232:235], v[4:7]
	v_mfma_f32_16x16x32_bf16 v[0:3], v[162:165], v[232:235], v[0:3]
	s_barrier
	s_add_i32 s22, s85, 2
	s_cmpk_gt_u32 s85, 0x51
	s_mov_b32 s85, s22
	s_cbranch_scc1 .LBB0_2387

;     __device__ __forceinline__ void a_ready(const Unit& u) const { wait_panel(cnt, u.pm, need, tmo, wave); }
;     __device__ __forceinline__ void a_ready(const Unit& u) const { wait_panel(cnt, u.pm, need, tmo, wave); }
; #define PG8_STAGE(bufoff, gbase, voff) do { _Pragma("unroll") for (int _i = 0; _i < 2; ++_i) \
;         __builtin_amdgcn_global_load_lds((const unsigned*)((const char*)(gbase) + (voff)[_i]), (PG8_LAS unsigned*)(lds + (bufoff) + ldsw + _i * 8192), 16, 0, 0); } while (0)
; #define PG8_LDA(dst, b, h) do { _Pragma("unroll") for (int m = 0; m < 4; ++m) _Pragma("unroll") for (int k = 0; k < 2; ++k) dst[m][k] = *(const PG8_LAS bf16x8*)(lds + PG8_SA(b, h) + aoff + m * 2048 + k * 1024); } while (0)
; #define PG8_LDB(dst, b, h) do { _Pragma("unroll") for (int n = 0; n < 2; ++n) _Pragma("unroll") for (int k = 0; k < 2; ++k) dst[n][k] = *(const PG8_LAS bf16x8*)(lds + PG8_SB(b, h) + boff + n * 2048 + k * 1024); } while (0)
; #define PG8_WAIT_V(n) asm volatile("s_waitcnt vmcnt(" #n ")" ::: "memory")
; #define PG8_WAIT_L(n) asm volatile("s_waitcnt lgkmcnt(" #n ")" ::: "memory")
; #define PG8_BAR __builtin_amdgcn_s_barrier()
; #define PG8_SCHED __builtin_amdgcn_sched_barrier(0)
; template <class Epi, class Sched, bool ALIGN_EPI = false, bool SP2 = false>
; __device__ __forceinline__ void gemm_phase(PG8_LAS unsigned char* lds, const Gemm g, const Sched& S, const Epi& E, const int tid_in) {
;     ...
;             const bool last = (t == nt - 2);
;             const char* a1 = cA + (size_t)(t + 1) * kstep;
;             const char* a2 = last ? nA : cA + (size_t)(t + 2) * kstep; const char* b2 = last ? nB : cB + (size_t)(t + 2) * kstep;
;             const char* a3 = a2 + kstep; const char* b3 = b2 + kstep;
;             if (last && has_next) S.a_ready(nxt);
;             if constexpr (SP2) {
;             PG8_LDB(B0, 0, 0); PG8_LDB(B1, 0, 1); PG8_SCHED; PG8_LDA(At, 0, 0); PG8_STAGE(PG8_SA(1, 1), a1 + hstepA, voffA);
;             PG8_WAIT_V(8); PG8_WAIT_L(0); PG8_BAR; PG8_MMA(0, 0, At, B0); PG8_MMA(0, 1, At, B1); PG8_BAR; PG8_SCHED;
;             PG8_LDA(At, 0, 1); PG8_STAGE(PG8_SB(0, 0), b2, voffB); PG8_STAGE(PG8_SB(0, 1), b2 + hstepB, voffB); PG8_STAGE(PG8_SA(0, 0), a2, voffA);
;             PG8_WAIT_V(8); PG8_WAIT_L(0); PG8_BAR; PG8_MMA(1, 0, At, B0); PG8_MMA(1, 1, At, B1); PG8_BAR; PG8_SCHED;
.LBB0_2427:
	ds_read_b128 v[64:67], v249
	ds_read_b128 v[68:71], v249 offset:1024
	ds_read_b128 v[72:75], v249 offset:2048
	ds_read_b128 v[76:79], v249 offset:3072
	ds_read_b128 v[80:83], v249 offset:16384
	ds_read_b128 v[84:87], v249 offset:17408
	ds_read_b128 v[88:91], v249 offset:18432
	ds_read_b128 v[92:95], v249 offset:19456
	ds_read_b128 v[96:99], v150
	ds_read_b128 v[100:103], v150 offset:1024
	ds_read_b128 v[104:107], v150 offset:2048
	ds_read_b128 v[108:111], v150 offset:3072
	ds_read_b128 v[112:115], v150 offset:4096
	ds_read_b128 v[116:119], v150 offset:5120
	ds_read_b128 v[120:123], v150 offset:6144
	ds_read_b128 v[124:127], v150 offset:7168
	s_lshl_b32 s74, s37, 7
	s_add_u32 s75, s62, s74
	s_addc_u32 s76, s63, 0
	s_add_u32 s77, s75, 0x100
	s_addc_u32 s85, s76, 0
	s_and_b64 s[72:73], s[22:23], exec
	s_cselect_b32 s73, s65, s85
	s_cselect_b32 s72, s64, s77
	s_add_u32 s74, s66, s74
	s_addc_u32 s77, s67, 0
	s_add_u32 s74, s74, 0x100
	s_addc_u32 s77, s77, 0
	s_and_b64 s[22:23], s[22:23], exec
	s_cselect_b32 s23, s69, s77
	s_cselect_b32 s22, s68, s74
	s_add_i32 s77, 0, 0x10000
	s_add_i32 s85, 0, 0x14000
	s_add_u32 s74, s75, 0x150080
	s_addc_u32 s75, s76, 0
	s_add_i32 m0, s17, 0xc000
	s_nop 0
	global_load_lds_dwordx4 v172, s[74:75]
	s_add_i32 m0, s17, 0xe000
	s_nop 0
	global_load_lds_dwordx4 v128, s[74:75]
	s_waitcnt vmcnt(8) lgkmcnt(0)
	s_barrier
	v_mfma_f32_16x16x32_bf16 v[60:63], v[64:67], v[96:99], v[60:63]
	v_mfma_f32_16x16x32_bf16 v[56:59], v[72:75], v[96:99], v[56:59]
	v_mfma_f32_16x16x32_bf16 v[44:47], v[64:67], v[104:107], v[44:47]
	v_mfma_f32_16x16x32_bf16 v[40:43], v[72:75], v[104:107], v[40:43]
	v_mfma_f32_16x16x32_bf16 v[32:35], v[64:67], v[112:115], v[32:35]
	v_mfma_f32_16x16x32_bf16 v[24:27], v[72:75], v[112:115], v[24:27]
	v_mfma_f32_16x16x32_bf16 v[16:19], v[64:67], v[120:123], v[16:19]
	v_mfma_f32_16x16x32_bf16 v[8:11], v[72:75], v[120:123], v[8:11]
	v_mfma_f32_16x16x32_bf16 v[60:63], v[68:71], v[100:103], v[60:63]
	v_mfma_f32_16x16x32_bf16 v[56:59], v[76:79], v[100:103], v[56:59]
	v_mfma_f32_16x16x32_bf16 v[44:47], v[68:71], v[108:111], v[44:47]
	v_mfma_f32_16x16x32_bf16 v[40:43], v[76:79], v[108:111], v[40:43]
	v_mfma_f32_16x16x32_bf16 v[32:35], v[68:71], v[116:119], v[32:35]
	v_mfma_f32_16x16x32_bf16 v[24:27], v[76:79], v[116:119], v[24:27]
	v_mfma_f32_16x16x32_bf16 v[16:19], v[68:71], v[124:127], v[16:19]
	v_mfma_f32_16x16x32_bf16 v[8:11], v[76:79], v[124:127], v[8:11]
	v_mfma_f32_16x16x32_bf16 v[52:55], v[80:83], v[96:99], v[52:55]
	v_mfma_f32_16x16x32_bf16 v[48:51], v[88:91], v[96:99], v[48:51]
	v_mfma_f32_16x16x32_bf16 v[36:39], v[80:83], v[104:107], v[36:39]
	v_mfma_f32_16x16x32_bf16 v[28:31], v[88:91], v[104:107], v[28:31]
	v_mfma_f32_16x16x32_bf16 v[20:23], v[80:83], v[112:115], v[20:23]
	v_mfma_f32_16x16x32_bf16 v[12:15], v[88:91], v[112:115], v[12:15]
	v_mfma_f32_16x16x32_bf16 v[4:7], v[80:83], v[120:123], v[4:7]
	v_mfma_f32_16x16x32_bf16 v[0:3], v[88:91], v[120:123], v[0:3]
	v_mfma_f32_16x16x32_bf16 v[52:55], v[84:87], v[100:103], v[52:55]
	v_mfma_f32_16x16x32_bf16 v[48:51], v[92:95], v[100:103], v[48:51]
	v_mfma_f32_16x16x32_bf16 v[36:39], v[84:87], v[108:111], v[36:39]
	v_mfma_f32_16x16x32_bf16 v[28:31], v[92:95], v[108:111], v[28:31]
	v_mfma_f32_16x16x32_bf16 v[20:23], v[84:87], v[116:119], v[20:23]
	v_mfma_f32_16x16x32_bf16 v[12:15], v[92:95], v[116:119], v[12:15]
	v_mfma_f32_16x16x32_bf16 v[4:7], v[84:87], v[124:127], v[4:7]
	v_mfma_f32_16x16x32_bf16 v[0:3], v[92:95], v[124:127], v[0:3]
	s_barrier
	s_add_i32 s74, s77, s16
	s_mov_b32 m0, s74
	s_nop 0
	global_load_lds_dwordx4 v172, s[22:23]
	s_add_i32 m0, s74, 0x2000
	s_add_u32 s74, s22, 0x150000
	s_addc_u32 s75, s23, 0
	s_add_i32 s76, s85, s16
	global_load_lds_dwordx4 v128, s[22:23]
	s_mov_b32 m0, s76
	s_add_u32 vcc_lo, s72, 0x80
	s_addc_u32 vcc_hi, s73, 0
	global_load_lds_dwordx4 v172, s[74:75]
	s_add_i32 m0, s76, 0x2000
	s_nop 0
	global_load_lds_dwordx4 v128, s[74:75]
	s_mov_b32 m0, s17
	s_nop 0
	global_load_lds_dwordx4 v172, s[72:73]
	s_mov_b32 m0, s20
	s_nop 0
	global_load_lds_dwordx4 v128, s[72:73]
	s_waitcnt vmcnt(8) lgkmcnt(0)
	s_barrier
; #define PG8_STAGE(bufoff, gbase, voff) do { _Pragma("unroll") for (int _i = 0; _i < 2; ++_i) \
;         __builtin_amdgcn_global_load_lds((const unsigned*)((const char*)(gbase) + (voff)[_i]), (PG8_LAS unsigned*)(lds + (bufoff) + ldsw + _i * 8192), 16, 0, 0); } while (0)
; #define PG8_LDA(dst, b, h) do { _Pragma("unroll") for (int m = 0; m < 4; ++m) _Pragma("unroll") for (int k = 0; k < 2; ++k) dst[m][k] = *(const PG8_LAS bf16x8*)(lds + PG8_SA(b, h) + aoff + m * 2048 + k * 1024); } while (0)
; #define PG8_LDB(dst, b, h) do { _Pragma("unroll") for (int n = 0; n < 2; ++n) _Pragma("unroll") for (int k = 0; k < 2; ++k) dst[n][k] = *(const PG8_LAS bf16x8*)(lds + PG8_SB(b, h) + boff + n * 2048 + k * 1024); } while (0)
; #define PG8_MMA(ai, bj, At, Bt) do { __builtin_amdgcn_s_setprio(1); _Pragma("unroll") for (int m = 0; m < 4; ++m) _Pragma("unroll") for (int n = 0; n < 2; ++n) _Pragma("unroll") for (int k = 0; k < 2; ++k) \
;         acc[ai][bj][m][n] = __builtin_amdgcn_mfma_f32_16x16x32_bf16(Bt[n][k], At[m][k], acc[ai][bj][m][n], 0, 0, 0); __builtin_amdgcn_s_setprio(0); } while (0)
; #define PG8_WAIT_V(n) asm volatile("s_waitcnt vmcnt(" #n ")" ::: "memory")
; #define PG8_WAIT_L(n) asm volatile("s_waitcnt lgkmcnt(" #n ")" ::: "memory")
; #define PG8_BAR __builtin_amdgcn_s_barrier()
; #define PG8_SCHED __builtin_amdgcn_sched_barrier(0)
; template <class Epi, class Sched, bool ALIGN_EPI = false, bool SP2 = false>
; __device__ __forceinline__ void gemm_phase(PG8_LAS unsigned char* lds, const Gemm g, const Sched& S, const Epi& E, const int tid_in) {
;     ...
;         for (int t = 0; t < nt; t += 2) {
;     ...
;             PG8_LDB(B0, 1, 0); PG8_LDB(B1, 1, 1); PG8_SCHED; PG8_LDA(At, 1, 0); PG8_STAGE(PG8_SA(0, 1), a2 + hstepA, voffA);
;             PG8_WAIT_V(8); PG8_WAIT_L(0); PG8_BAR; PG8_MMA(0, 0, At, B0); PG8_MMA(0, 1, At, B1); PG8_BAR; PG8_SCHED;
;             PG8_LDA(At, 1, 1); PG8_STAGE(PG8_SB(1, 0), b3, voffB); PG8_STAGE(PG8_SB(1, 1), b3 + hstepB, voffB); PG8_STAGE(PG8_SA(1, 0), a3, voffA);
;             PG8_WAIT_V(8); PG8_WAIT_L(0); PG8_BAR; PG8_MMA(1, 0, At, B0); PG8_MMA(1, 1, At, B1); PG8_BAR; PG8_SCHED;
	s_barrier
	ds_read_b128 v[64:67], v249 offset:32768
	ds_read_b128 v[68:71], v249 offset:33792
	ds_read_b128 v[72:75], v249 offset:34816
	ds_read_b128 v[76:79], v249 offset:35840
	ds_read_b128 v[80:83], v249 offset:49152
	ds_read_b128 v[84:87], v249 offset:50176
	ds_read_b128 v[88:91], v249 offset:51200
	ds_read_b128 v[92:95], v249 offset:52224
	ds_read_b128 v[96:99], v150 offset:32768
	ds_read_b128 v[100:103], v150 offset:33792
	ds_read_b128 v[104:107], v150 offset:34816
	ds_read_b128 v[108:111], v150 offset:35840
	ds_read_b128 v[112:115], v150 offset:36864
	ds_read_b128 v[116:119], v150 offset:37888
	ds_read_b128 v[120:123], v150 offset:38912
	ds_read_b128 v[124:127], v150 offset:39936
	s_add_i32 s74, 0, 0x18000
	s_add_i32 s75, 0, 0x1c000
	s_add_u32 s72, s72, 0x150000
	s_addc_u32 s73, s73, 0
	s_mov_b32 m0, s21
	s_nop 0
	global_load_lds_dwordx4 v172, s[72:73]
	s_mov_b32 m0, s31
	s_nop 0
	global_load_lds_dwordx4 v128, s[72:73]
	s_waitcnt vmcnt(8) lgkmcnt(0)
	s_barrier
	v_mfma_f32_16x16x32_bf16 v[60:63], v[64:67], v[96:99], v[60:63]
	v_mfma_f32_16x16x32_bf16 v[56:59], v[72:75], v[96:99], v[56:59]
	v_mfma_f32_16x16x32_bf16 v[44:47], v[64:67], v[104:107], v[44:47]
	v_mfma_f32_16x16x32_bf16 v[40:43], v[72:75], v[104:107], v[40:43]
	v_mfma_f32_16x16x32_bf16 v[32:35], v[64:67], v[112:115], v[32:35]
	v_mfma_f32_16x16x32_bf16 v[24:27], v[72:75], v[112:115], v[24:27]
	v_mfma_f32_16x16x32_bf16 v[16:19], v[64:67], v[120:123], v[16:19]
	v_mfma_f32_16x16x32_bf16 v[8:11], v[72:75], v[120:123], v[8:11]
	v_mfma_f32_16x16x32_bf16 v[60:63], v[68:71], v[100:103], v[60:63]
	v_mfma_f32_16x16x32_bf16 v[56:59], v[76:79], v[100:103], v[56:59]
	v_mfma_f32_16x16x32_bf16 v[44:47], v[68:71], v[108:111], v[44:47]
	v_mfma_f32_16x16x32_bf16 v[40:43], v[76:79], v[108:111], v[40:43]
	v_mfma_f32_16x16x32_bf16 v[32:35], v[68:71], v[116:119], v[32:35]
	v_mfma_f32_16x16x32_bf16 v[24:27], v[76:79], v[116:119], v[24:27]
	v_mfma_f32_16x16x32_bf16 v[16:19], v[68:71], v[124:127], v[16:19]
	v_mfma_f32_16x16x32_bf16 v[8:11], v[76:79], v[124:127], v[8:11]
	v_mfma_f32_16x16x32_bf16 v[52:55], v[80:83], v[96:99], v[52:55]
	v_mfma_f32_16x16x32_bf16 v[48:51], v[88:91], v[96:99], v[48:51]
	v_mfma_f32_16x16x32_bf16 v[36:39], v[80:83], v[104:107], v[36:39]
	v_mfma_f32_16x16x32_bf16 v[28:31], v[88:91], v[104:107], v[28:31]
	v_mfma_f32_16x16x32_bf16 v[20:23], v[80:83], v[112:115], v[20:23]
	v_mfma_f32_16x16x32_bf16 v[12:15], v[88:91], v[112:115], v[12:15]
	v_mfma_f32_16x16x32_bf16 v[4:7], v[80:83], v[120:123], v[4:7]
	v_mfma_f32_16x16x32_bf16 v[0:3], v[88:91], v[120:123], v[0:3]
	v_mfma_f32_16x16x32_bf16 v[52:55], v[84:87], v[100:103], v[52:55]
	v_mfma_f32_16x16x32_bf16 v[48:51], v[92:95], v[100:103], v[48:51]
	v_mfma_f32_16x16x32_bf16 v[36:39], v[84:87], v[108:111], v[36:39]
	v_mfma_f32_16x16x32_bf16 v[28:31], v[92:95], v[108:111], v[28:31]
	v_mfma_f32_16x16x32_bf16 v[20:23], v[84:87], v[116:119], v[20:23]
	v_mfma_f32_16x16x32_bf16 v[12:15], v[92:95], v[116:119], v[12:15]
	v_mfma_f32_16x16x32_bf16 v[4:7], v[84:87], v[124:127], v[4:7]
	v_mfma_f32_16x16x32_bf16 v[0:3], v[92:95], v[124:127], v[0:3]
	s_barrier
	s_add_i32 s72, s74, s16
	s_mov_b32 m0, s72
	s_nop 0
	s_add_u32 s100, s22, 0x80
	s_addc_u32 s101, s23, 0
	global_load_lds_dwordx4 v172, s[100:101]
	s_add_i32 m0, s72, 0x2000
	s_add_u32 s22, s22, 0x150080
	s_addc_u32 s23, s23, 0
	s_add_i32 s72, s75, s16
	global_load_lds_dwordx4 v128, s[100:101]
	s_mov_b32 m0, s72
	s_nop 0
	global_load_lds_dwordx4 v172, s[22:23]
	s_add_i32 m0, s72, 0x2000
	s_nop 0
	global_load_lds_dwordx4 v128, s[22:23]
	s_mov_b32 m0, s33
	s_nop 0
	global_load_lds_dwordx4 v172, vcc
	s_mov_b32 m0, s34
	s_nop 0
	global_load_lds_dwordx4 v128, vcc
	s_waitcnt vmcnt(8) lgkmcnt(0)
	s_barrier
	s_barrier
	s_add_i32 s22, s37, 2
	s_cmp_gt_u32 s37, 9
	s_mov_b32 s37, s22
	s_cbranch_scc1 .LBB0_2442
